# v22
# speedup vs baseline: 1.0322x; 1.0146x over previous
; #define LDA(dst, b, h)                                                                                               \
;   _Pragma("unroll") for (int m = 0; m < 4; ++m) _Pragma("unroll") for (int k = 0; k < 2; ++k) dst[m][k] =            \
;       *reinterpret_cast<const bf16x8*>(SA(b, h) + lds_byte(wr * 64 + m * 16 + fr, k * 32 + fq * 8))
; #define LDB(dst, b, h)                                                                                               \
;   _Pragma("unroll") for (int n = 0; n < 2; ++n) _Pragma("unroll") for (int k = 0; k < 2; ++k) dst[n][k] =            \
;       *reinterpret_cast<const bf16x8*>(SB(b, h) + lds_byte(wc * 32 + n * 16 + fr, k * 32 + fq * 8))
; #define WAIT_V(n) asm volatile("s_waitcnt vmcnt(" #n ")" ::: "memory")
; #define WAIT_L(n) asm volatile("s_waitcnt lgkmcnt(" #n ")" ::: "memory")
; #define BAR __builtin_amdgcn_s_barrier()
; #define SCHED __builtin_amdgcn_sched_barrier(0)
; template <int EPI>
; __device__ __forceinline__ void gemm_phase(const u16* __restrict__ A, const u16* __restrict__ Bt, const int K,
;                                            const int nN, char* shm, const EpiArgs& ea) {
;     ...
;     for (int t = 0; t < nt - 2; t += 2) {
;       LDB(B0, 0, 0); SCHED; LDA(At, 0, 0); STAGE(SA(1, 1), rA, brow + HALF, t + 1);
;       WAIT_V(10); WAIT_L(8); BAR; WAIT_L(0); MMA(0, 0, At, B0); BAR; SCHED;
;       LDB(B1, 0, 1); STAGE(SB(0, 0), rB, bcol, t + 2);
;       WAIT_V(10); BAR; WAIT_L(0); MMA(0, 1, At, B1); BAR;
;       LDA(At, 0, 1); STAGE(SA(0, 0), rA, brow, t + 2);
;       BAR; WAIT_L(0); MMA(1, 0, At, B0); BAR; SCHED;
;       STAGE(SB(0, 1), rB, bcol + HALF, t + 2);
;       WAIT_V(10); BAR; MMA(1, 1, At, B1); BAR;
.LBB0_172:
	ds_read_b128 v[142:145], v133
	ds_read_b128 v[146:149], v133 offset:1024
	ds_read_b128 v[150:153], v133 offset:2048
	ds_read_b128 v[154:157], v133 offset:3072
	s_add_i32 s73, s67, s72
	s_mov_b32 m0, s57
	s_add_i32 s6, s73, 0x4000
	ds_read_b128 v[162:165], v134
	ds_read_b128 v[166:169], v134 offset:1024
	ds_read_b128 v[170:173], v135
	ds_read_b128 v[176:179], v135 offset:1024
	ds_read_b128 v[180:183], v136
	ds_read_b128 v[184:187], v136 offset:1024
	ds_read_b128 v[188:191], v137
	ds_read_b128 v[192:195], v137 offset:1024
	buffer_load_dwordx4 v130, s[0:3], s6 offen lds
	s_add_i32 s6, s73, 0x6000
	s_mov_b32 m0, s58
	s_nop 0
	buffer_load_dwordx4 v130, s[0:3], s6 offen lds
	s_waitcnt vmcnt(10)
	s_waitcnt lgkmcnt(8)
	s_barrier
	s_waitcnt lgkmcnt(7)
	v_mfma_f32_16x16x32_bf16 v[124:127], v[142:145], v[162:165], v[124:127]
	v_mfma_f32_16x16x32_bf16 v[120:123], v[150:153], v[162:165], v[120:123]
	s_waitcnt lgkmcnt(5)
	v_mfma_f32_16x16x32_bf16 v[116:119], v[142:145], v[170:173], v[116:119]
	v_mfma_f32_16x16x32_bf16 v[112:115], v[150:153], v[170:173], v[112:115]
	s_waitcnt lgkmcnt(3)
	v_mfma_f32_16x16x32_bf16 v[108:111], v[142:145], v[180:183], v[108:111]
	v_mfma_f32_16x16x32_bf16 v[104:107], v[150:153], v[180:183], v[104:107]
	s_waitcnt lgkmcnt(1)
	v_mfma_f32_16x16x32_bf16 v[100:103], v[142:145], v[188:191], v[100:103]
	v_mfma_f32_16x16x32_bf16 v[96:99], v[150:153], v[188:191], v[96:99]
	v_mfma_f32_16x16x32_bf16 v[124:127], v[146:149], v[166:169], v[124:127]
	v_mfma_f32_16x16x32_bf16 v[120:123], v[154:157], v[166:169], v[120:123]
	v_mfma_f32_16x16x32_bf16 v[116:119], v[146:149], v[176:179], v[116:119]
	v_mfma_f32_16x16x32_bf16 v[112:115], v[154:157], v[176:179], v[112:115]
	v_mfma_f32_16x16x32_bf16 v[108:111], v[146:149], v[184:187], v[108:111]
	v_mfma_f32_16x16x32_bf16 v[104:107], v[154:157], v[184:187], v[104:107]
	s_waitcnt lgkmcnt(0)
	v_mfma_f32_16x16x32_bf16 v[100:103], v[146:149], v[192:195], v[100:103]
	v_mfma_f32_16x16x32_bf16 v[96:99], v[154:157], v[192:195], v[96:99]
	s_barrier
	s_add_i32 s74, s70, s72
	s_mov_b32 m0, s34
	s_add_i32 s75, s74, 0x8000
	s_mov_b32 s6, s2
	s_mov_b32 s7, s3
	ds_read_b128 v[196:199], v138
	ds_read_b128 v[200:203], v138 offset:1024
	ds_read_b128 v[204:207], v138 offset:2048
	ds_read_b128 v[208:211], v138 offset:3072
	buffer_load_dwordx4 v130, s[4:7], s75 offen lds
	s_add_i32 s75, s74, 0xa000
	s_mov_b32 m0, s35
	s_nop 0
	buffer_load_dwordx4 v130, s[4:7], s75 offen lds
	s_waitcnt vmcnt(10)
	s_barrier
	s_waitcnt lgkmcnt(3)
	v_mfma_f32_16x16x32_bf16 v[92:95], v[196:199], v[162:165], v[92:95]
	s_waitcnt lgkmcnt(1)
	v_mfma_f32_16x16x32_bf16 v[88:91], v[204:207], v[162:165], v[88:91]
	v_mfma_f32_16x16x32_bf16 v[84:87], v[196:199], v[170:173], v[84:87]
	v_mfma_f32_16x16x32_bf16 v[80:83], v[204:207], v[170:173], v[80:83]
	v_mfma_f32_16x16x32_bf16 v[76:79], v[196:199], v[180:183], v[76:79]
	v_mfma_f32_16x16x32_bf16 v[72:75], v[204:207], v[180:183], v[72:75]
	v_mfma_f32_16x16x32_bf16 v[68:71], v[196:199], v[188:191], v[68:71]
	v_mfma_f32_16x16x32_bf16 v[64:67], v[204:207], v[188:191], v[64:67]
	v_mfma_f32_16x16x32_bf16 v[92:95], v[200:203], v[166:169], v[92:95]
	s_waitcnt lgkmcnt(0)
	v_mfma_f32_16x16x32_bf16 v[88:91], v[208:211], v[166:169], v[88:91]
	v_mfma_f32_16x16x32_bf16 v[84:87], v[200:203], v[176:179], v[84:87]
	v_mfma_f32_16x16x32_bf16 v[80:83], v[208:211], v[176:179], v[80:83]
	v_mfma_f32_16x16x32_bf16 v[76:79], v[200:203], v[184:187], v[76:79]
	v_mfma_f32_16x16x32_bf16 v[72:75], v[208:211], v[184:187], v[72:75]
	v_mfma_f32_16x16x32_bf16 v[68:71], v[200:203], v[192:195], v[68:71]
	v_mfma_f32_16x16x32_bf16 v[64:67], v[208:211], v[192:195], v[64:67]
	s_add_i32 s75, s69, s72
	s_mov_b32 m0, s38
	s_add_i32 s78, s75, 0x8000
	s_barrier
	ds_read_b128 v[162:165], v134 offset:16384
	ds_read_b128 v[166:169], v134 offset:17408
	ds_read_b128 v[170:173], v135 offset:16384
	ds_read_b128 v[176:179], v135 offset:17408
	ds_read_b128 v[180:183], v136 offset:16384
	ds_read_b128 v[184:187], v136 offset:17408
	ds_read_b128 v[188:191], v137 offset:16384
	ds_read_b128 v[192:195], v137 offset:17408
	buffer_load_dwordx4 v130, s[0:3], s78 offen lds
	s_add_i32 s78, s75, 0xa000
	s_mov_b32 m0, s39
	s_nop 0
	buffer_load_dwordx4 v130, s[0:3], s78 offen lds
	s_barrier
	s_waitcnt lgkmcnt(7)
	v_mfma_f32_16x16x32_bf16 v[60:63], v[142:145], v[162:165], v[60:63]
	v_mfma_f32_16x16x32_bf16 v[56:59], v[150:153], v[162:165], v[56:59]
	s_waitcnt lgkmcnt(5)
	v_mfma_f32_16x16x32_bf16 v[52:55], v[142:145], v[170:173], v[52:55]
	v_mfma_f32_16x16x32_bf16 v[48:51], v[150:153], v[170:173], v[48:51]
	s_waitcnt lgkmcnt(3)
	v_mfma_f32_16x16x32_bf16 v[44:47], v[142:145], v[180:183], v[44:47]
	v_mfma_f32_16x16x32_bf16 v[40:43], v[150:153], v[180:183], v[40:43]
	s_waitcnt lgkmcnt(1)
	v_mfma_f32_16x16x32_bf16 v[36:39], v[142:145], v[188:191], v[36:39]
	v_mfma_f32_16x16x32_bf16 v[32:35], v[150:153], v[188:191], v[32:35]
	v_mfma_f32_16x16x32_bf16 v[60:63], v[146:149], v[166:169], v[60:63]
	v_mfma_f32_16x16x32_bf16 v[56:59], v[154:157], v[166:169], v[56:59]
	v_mfma_f32_16x16x32_bf16 v[52:55], v[146:149], v[176:179], v[52:55]
	v_mfma_f32_16x16x32_bf16 v[48:51], v[154:157], v[176:179], v[48:51]
	v_mfma_f32_16x16x32_bf16 v[44:47], v[146:149], v[184:187], v[44:47]
	v_mfma_f32_16x16x32_bf16 v[40:43], v[154:157], v[184:187], v[40:43]
	s_waitcnt lgkmcnt(0)
	v_mfma_f32_16x16x32_bf16 v[36:39], v[146:149], v[192:195], v[36:39]
	v_mfma_f32_16x16x32_bf16 v[32:35], v[154:157], v[192:195], v[32:35]
	s_barrier
	s_add_i32 s78, s68, s72
	s_mov_b32 m0, s40
	s_add_i32 s79, s78, 0x8000
	buffer_load_dwordx4 v130, s[4:7], s79 offen lds
	s_add_i32 s79, s78, 0xa000
	s_mov_b32 m0, s41
	s_nop 0
	buffer_load_dwordx4 v130, s[4:7], s79 offen lds
	s_waitcnt vmcnt(10)
	s_barrier
; #define LDA(dst, b, h)                                                                                               \
;   _Pragma("unroll") for (int m = 0; m < 4; ++m) _Pragma("unroll") for (int k = 0; k < 2; ++k) dst[m][k] =            \
;       *reinterpret_cast<const bf16x8*>(SA(b, h) + lds_byte(wr * 64 + m * 16 + fr, k * 32 + fq * 8))
; #define LDB(dst, b, h)                                                                                               \
;   _Pragma("unroll") for (int n = 0; n < 2; ++n) _Pragma("unroll") for (int k = 0; k < 2; ++k) dst[n][k] =            \
;       *reinterpret_cast<const bf16x8*>(SB(b, h) + lds_byte(wc * 32 + n * 16 + fr, k * 32 + fq * 8))
; #define WAIT_V(n) asm volatile("s_waitcnt vmcnt(" #n ")" ::: "memory")
; #define WAIT_L(n) asm volatile("s_waitcnt lgkmcnt(" #n ")" ::: "memory")
; #define BAR __builtin_amdgcn_s_barrier()
; #define SCHED __builtin_amdgcn_sched_barrier(0)
; template <int EPI>
; __device__ __forceinline__ void gemm_phase(const u16* __restrict__ A, const u16* __restrict__ Bt, const int K,
;                                            const int nN, char* shm, const EpiArgs& ea) {
;     ...
;       WAIT_V(10); BAR; MMA(1, 1, At, B1); BAR;
;       LDB(B0, 1, 0); SCHED; LDA(At, 1, 0); STAGE(SA(0, 1), rA, brow + HALF, t + 2);
;       WAIT_V(10); WAIT_L(8); BAR; WAIT_L(0); MMA(0, 0, At, B0); BAR; SCHED;
;       LDB(B1, 1, 1); STAGE(SB(1, 0), rB, bcol, t + 3);
;       WAIT_V(10); BAR; WAIT_L(0); MMA(0, 1, At, B1); BAR;
;       LDA(At, 1, 1); STAGE(SA(1, 0), rA, brow, t + 3);
	v_mfma_f32_16x16x32_bf16 v[28:31], v[196:199], v[162:165], v[28:31]
	v_mfma_f32_16x16x32_bf16 v[24:27], v[204:207], v[162:165], v[24:27]
	v_mfma_f32_16x16x32_bf16 v[20:23], v[196:199], v[170:173], v[20:23]
	v_mfma_f32_16x16x32_bf16 v[16:19], v[204:207], v[170:173], v[16:19]
	v_mfma_f32_16x16x32_bf16 v[12:15], v[196:199], v[180:183], v[12:15]
	v_mfma_f32_16x16x32_bf16 v[8:11], v[204:207], v[180:183], v[8:11]
	v_mfma_f32_16x16x32_bf16 v[4:7], v[196:199], v[188:191], v[4:7]
	v_mfma_f32_16x16x32_bf16 v[0:3], v[204:207], v[188:191], v[0:3]
	v_mfma_f32_16x16x32_bf16 v[28:31], v[200:203], v[166:169], v[28:31]
	v_mfma_f32_16x16x32_bf16 v[24:27], v[208:211], v[166:169], v[24:27]
	v_mfma_f32_16x16x32_bf16 v[20:23], v[200:203], v[176:179], v[20:23]
	v_mfma_f32_16x16x32_bf16 v[16:19], v[208:211], v[176:179], v[16:19]
	v_mfma_f32_16x16x32_bf16 v[12:15], v[200:203], v[184:187], v[12:15]
	v_mfma_f32_16x16x32_bf16 v[8:11], v[208:211], v[184:187], v[8:11]
	v_mfma_f32_16x16x32_bf16 v[4:7], v[200:203], v[192:195], v[4:7]
	v_mfma_f32_16x16x32_bf16 v[0:3], v[208:211], v[192:195], v[0:3]
	s_barrier
	ds_read_b128 v[142:145], v139
	ds_read_b128 v[146:149], v139 offset:1024
	ds_read_b128 v[150:153], v139 offset:2048
	ds_read_b128 v[154:157], v139 offset:3072
	s_mov_b32 m0, s42
	s_add_i32 s79, s73, 0x8000
	ds_read_b128 v[162:165], v134 offset:32768
	ds_read_b128 v[166:169], v134 offset:33792
	ds_read_b128 v[170:173], v135 offset:32768
	ds_read_b128 v[176:179], v135 offset:33792
	ds_read_b128 v[180:183], v136 offset:32768
	ds_read_b128 v[184:187], v136 offset:33792
	ds_read_b128 v[188:191], v137 offset:32768
	ds_read_b128 v[192:195], v137 offset:33792
	buffer_load_dwordx4 v130, s[0:3], s79 offen lds
	s_add_i32 s73, s73, 0xa000
	s_mov_b32 m0, s43
	s_nop 0
	buffer_load_dwordx4 v130, s[0:3], s73 offen lds
	s_waitcnt vmcnt(10)
	s_waitcnt lgkmcnt(8)
	s_barrier
	s_waitcnt lgkmcnt(7)
	v_mfma_f32_16x16x32_bf16 v[124:127], v[142:145], v[162:165], v[124:127]
	v_mfma_f32_16x16x32_bf16 v[120:123], v[150:153], v[162:165], v[120:123]
	s_waitcnt lgkmcnt(5)
	v_mfma_f32_16x16x32_bf16 v[116:119], v[142:145], v[170:173], v[116:119]
	v_mfma_f32_16x16x32_bf16 v[112:115], v[150:153], v[170:173], v[112:115]
	s_waitcnt lgkmcnt(3)
	v_mfma_f32_16x16x32_bf16 v[108:111], v[142:145], v[180:183], v[108:111]
	v_mfma_f32_16x16x32_bf16 v[104:107], v[150:153], v[180:183], v[104:107]
	s_waitcnt lgkmcnt(1)
	v_mfma_f32_16x16x32_bf16 v[100:103], v[142:145], v[188:191], v[100:103]
	v_mfma_f32_16x16x32_bf16 v[96:99], v[150:153], v[188:191], v[96:99]
	v_mfma_f32_16x16x32_bf16 v[124:127], v[146:149], v[166:169], v[124:127]
	v_mfma_f32_16x16x32_bf16 v[120:123], v[154:157], v[166:169], v[120:123]
	v_mfma_f32_16x16x32_bf16 v[116:119], v[146:149], v[176:179], v[116:119]
	v_mfma_f32_16x16x32_bf16 v[112:115], v[154:157], v[176:179], v[112:115]
	v_mfma_f32_16x16x32_bf16 v[108:111], v[146:149], v[184:187], v[108:111]
	v_mfma_f32_16x16x32_bf16 v[104:107], v[154:157], v[184:187], v[104:107]
	s_waitcnt lgkmcnt(0)
	v_mfma_f32_16x16x32_bf16 v[100:103], v[146:149], v[192:195], v[100:103]
	v_mfma_f32_16x16x32_bf16 v[96:99], v[154:157], v[192:195], v[96:99]
	s_barrier
	s_mov_b32 m0, s48
	s_add_i32 s73, s74, 0xc000
	ds_read_b128 v[196:199], v140
	ds_read_b128 v[200:203], v140 offset:1024
	ds_read_b128 v[204:207], v140 offset:2048
	ds_read_b128 v[208:211], v140 offset:3072
	buffer_load_dwordx4 v130, s[4:7], s73 offen lds
	s_add_i32 s74, s74, 0xe000
	s_mov_b32 m0, s49
	s_nop 0
	buffer_load_dwordx4 v130, s[4:7], s74 offen lds
	s_waitcnt vmcnt(10)
	s_barrier
	s_waitcnt lgkmcnt(3)
	v_mfma_f32_16x16x32_bf16 v[92:95], v[196:199], v[162:165], v[92:95]
	s_waitcnt lgkmcnt(1)
	v_mfma_f32_16x16x32_bf16 v[88:91], v[204:207], v[162:165], v[88:91]
	v_mfma_f32_16x16x32_bf16 v[84:87], v[196:199], v[170:173], v[84:87]
	v_mfma_f32_16x16x32_bf16 v[80:83], v[204:207], v[170:173], v[80:83]
	v_mfma_f32_16x16x32_bf16 v[76:79], v[196:199], v[180:183], v[76:79]
	v_mfma_f32_16x16x32_bf16 v[72:75], v[204:207], v[180:183], v[72:75]
	v_mfma_f32_16x16x32_bf16 v[68:71], v[196:199], v[188:191], v[68:71]
	v_mfma_f32_16x16x32_bf16 v[64:67], v[204:207], v[188:191], v[64:67]
	v_mfma_f32_16x16x32_bf16 v[92:95], v[200:203], v[166:169], v[92:95]
	s_waitcnt lgkmcnt(0)
	v_mfma_f32_16x16x32_bf16 v[88:91], v[208:211], v[166:169], v[88:91]
	v_mfma_f32_16x16x32_bf16 v[84:87], v[200:203], v[176:179], v[84:87]
	v_mfma_f32_16x16x32_bf16 v[80:83], v[208:211], v[176:179], v[80:83]
	v_mfma_f32_16x16x32_bf16 v[76:79], v[200:203], v[184:187], v[76:79]
	v_mfma_f32_16x16x32_bf16 v[72:75], v[208:211], v[184:187], v[72:75]
	v_mfma_f32_16x16x32_bf16 v[68:71], v[200:203], v[192:195], v[68:71]
	v_mfma_f32_16x16x32_bf16 v[64:67], v[208:211], v[192:195], v[64:67]
	s_mov_b32 m0, s52
	s_add_i32 s73, s75, 0xc000
	s_barrier
	ds_read_b128 v[162:165], v134 offset:49152
	ds_read_b128 v[166:169], v134 offset:50176
	ds_read_b128 v[170:173], v135 offset:49152
	ds_read_b128 v[176:179], v135 offset:50176
	ds_read_b128 v[180:183], v136 offset:49152
	ds_read_b128 v[184:187], v136 offset:50176
	ds_read_b128 v[188:191], v137 offset:49152
	ds_read_b128 v[192:195], v137 offset:50176
	buffer_load_dwordx4 v130, s[0:3], s73 offen lds
	s_add_i32 s75, s75, 0xe000
	s_mov_b32 m0, s53
	s_nop 0
	buffer_load_dwordx4 v130, s[0:3], s75 offen lds
	s_barrier
; #define LDA(dst, b, h)                                                                                               \
;   _Pragma("unroll") for (int m = 0; m < 4; ++m) _Pragma("unroll") for (int k = 0; k < 2; ++k) dst[m][k] =            \
;       *reinterpret_cast<const bf16x8*>(SA(b, h) + lds_byte(wr * 64 + m * 16 + fr, k * 32 + fq * 8))
; #define LDB(dst, b, h)                                                                                               \
;   _Pragma("unroll") for (int n = 0; n < 2; ++n) _Pragma("unroll") for (int k = 0; k < 2; ++k) dst[n][k] =            \
;       *reinterpret_cast<const bf16x8*>(SB(b, h) + lds_byte(wc * 32 + n * 16 + fr, k * 32 + fq * 8))
; #define WAIT_V(n) asm volatile("s_waitcnt vmcnt(" #n ")" ::: "memory")
; #define WAIT_L(n) asm volatile("s_waitcnt lgkmcnt(" #n ")" ::: "memory")
; #define BAR __builtin_amdgcn_s_barrier()
; #define SCHED __builtin_amdgcn_sched_barrier(0)
; template <int EPI>
; __device__ __forceinline__ void gemm_phase(const u16* __restrict__ A, const u16* __restrict__ Bt, const int K,
;                                            const int nN, char* shm, const EpiArgs& ea) {
;     ...
;       BAR; WAIT_L(0); MMA(1, 0, At, B0); BAR; SCHED;
;       STAGE(SB(1, 1), rB, bcol + HALF, t + 3);
;       WAIT_V(10); BAR; MMA(1, 1, At, B1); BAR;
;     }
;     float eC = 0.f, eB = 0.f;
;     float2 eS = make_float2(0.f, 0.f);
;     if (EPI == EPI_IN || EPI == EPI_SWIGLU_LN) {
;       if (wr == 0) {
;         eC = ea.c1[bcol + tid];
;         eS = *(const float2*)(ea.st_in + (size_t)(brow + tid) * 2);
;       } else {
;         eC = ea.c2[bcol + tid - 256];
;         if (EPI == EPI_IN) eB = ea.bias[bcol + tid - 256];
;       }
;     }
;     {
;       LDB(B0, 0, 0); LDA(At, 0, 0); STAGE(SA(1, 1), rA, brow + HALF, nt - 1);
;       WAIT_V(10); BAR; WAIT_L(0); MMA(0, 0, At, B0); BAR;
;       LDB(B1, 0, 1); WAIT_V(8); BAR; WAIT_L(0); MMA(0, 1, At, B1); BAR;
	s_waitcnt lgkmcnt(7)
	v_mfma_f32_16x16x32_bf16 v[60:63], v[142:145], v[162:165], v[60:63]
	v_mfma_f32_16x16x32_bf16 v[56:59], v[150:153], v[162:165], v[56:59]
	s_waitcnt lgkmcnt(5)
	v_mfma_f32_16x16x32_bf16 v[52:55], v[142:145], v[170:173], v[52:55]
	v_mfma_f32_16x16x32_bf16 v[48:51], v[150:153], v[170:173], v[48:51]
	s_waitcnt lgkmcnt(3)
	v_mfma_f32_16x16x32_bf16 v[44:47], v[142:145], v[180:183], v[44:47]
	v_mfma_f32_16x16x32_bf16 v[40:43], v[150:153], v[180:183], v[40:43]
	s_waitcnt lgkmcnt(1)
	v_mfma_f32_16x16x32_bf16 v[36:39], v[142:145], v[188:191], v[36:39]
	v_mfma_f32_16x16x32_bf16 v[32:35], v[150:153], v[188:191], v[32:35]
	v_mfma_f32_16x16x32_bf16 v[60:63], v[146:149], v[166:169], v[60:63]
	v_mfma_f32_16x16x32_bf16 v[56:59], v[154:157], v[166:169], v[56:59]
	v_mfma_f32_16x16x32_bf16 v[52:55], v[146:149], v[176:179], v[52:55]
	v_mfma_f32_16x16x32_bf16 v[48:51], v[154:157], v[176:179], v[48:51]
	v_mfma_f32_16x16x32_bf16 v[44:47], v[146:149], v[184:187], v[44:47]
	v_mfma_f32_16x16x32_bf16 v[40:43], v[154:157], v[184:187], v[40:43]
	s_waitcnt lgkmcnt(0)
	v_mfma_f32_16x16x32_bf16 v[36:39], v[146:149], v[192:195], v[36:39]
	v_mfma_f32_16x16x32_bf16 v[32:35], v[154:157], v[192:195], v[32:35]
	s_barrier
	s_mov_b32 m0, s54
	s_add_i32 s73, s78, 0xc000
	buffer_load_dwordx4 v130, s[4:7], s73 offen lds
	s_add_i32 s78, s78, 0xe000
	s_mov_b32 m0, s55
	s_nop 0
	buffer_load_dwordx4 v130, s[4:7], s78 offen lds
	s_waitcnt vmcnt(10)
	s_barrier
	v_mfma_f32_16x16x32_bf16 v[28:31], v[196:199], v[162:165], v[28:31]
	v_mfma_f32_16x16x32_bf16 v[24:27], v[204:207], v[162:165], v[24:27]
	v_mfma_f32_16x16x32_bf16 v[20:23], v[196:199], v[170:173], v[20:23]
	v_mfma_f32_16x16x32_bf16 v[16:19], v[204:207], v[170:173], v[16:19]
	v_mfma_f32_16x16x32_bf16 v[12:15], v[196:199], v[180:183], v[12:15]
	v_mfma_f32_16x16x32_bf16 v[8:11], v[204:207], v[180:183], v[8:11]
	v_mfma_f32_16x16x32_bf16 v[4:7], v[196:199], v[188:191], v[4:7]
	v_mfma_f32_16x16x32_bf16 v[0:3], v[204:207], v[188:191], v[0:3]
	v_mfma_f32_16x16x32_bf16 v[28:31], v[200:203], v[166:169], v[28:31]
	v_mfma_f32_16x16x32_bf16 v[24:27], v[208:211], v[166:169], v[24:27]
	v_mfma_f32_16x16x32_bf16 v[20:23], v[200:203], v[176:179], v[20:23]
	v_mfma_f32_16x16x32_bf16 v[16:19], v[208:211], v[176:179], v[16:19]
	v_mfma_f32_16x16x32_bf16 v[12:15], v[200:203], v[184:187], v[12:15]
	v_mfma_f32_16x16x32_bf16 v[8:11], v[208:211], v[184:187], v[8:11]
	v_mfma_f32_16x16x32_bf16 v[4:7], v[200:203], v[192:195], v[4:7]
	v_mfma_f32_16x16x32_bf16 v[0:3], v[208:211], v[192:195], v[0:3]
	s_add_i32 s71, s71, 2
	s_add_i32 s72, s72, 0x8000
	s_cmp_lt_u32 s71, 28
	s_barrier
	s_cbranch_scc1 .LBB0_172
	s_mov_b32 m0, s57
	s_add_i32 s6, s67, 0x7c000
	ds_read_b128 v[142:145], v133
	ds_read_b128 v[146:149], v133 offset:1024
	ds_read_b128 v[150:153], v133 offset:2048
	ds_read_b128 v[154:157], v133 offset:3072
	ds_read_b128 v[162:165], v134
	ds_read_b128 v[166:169], v134 offset:1024
	ds_read_b128 v[170:173], v135
	ds_read_b128 v[176:179], v135 offset:1024
	ds_read_b128 v[180:183], v136
	ds_read_b128 v[184:187], v136 offset:1024
	ds_read_b128 v[188:191], v137
	ds_read_b128 v[192:195], v137 offset:1024
	buffer_load_dwordx4 v130, s[0:3], s6 offen lds
	s_add_i32 s67, s67, 0x7e000
	s_mov_b32 m0, s58
	s_nop 0
	buffer_load_dwordx4 v130, s[0:3], s67 offen lds
	s_waitcnt vmcnt(10)
	s_barrier
	s_waitcnt lgkmcnt(7)
	v_mfma_f32_16x16x32_bf16 v[124:127], v[142:145], v[162:165], v[124:127]
	v_mfma_f32_16x16x32_bf16 v[120:123], v[150:153], v[162:165], v[120:123]
	s_waitcnt lgkmcnt(5)
	v_mfma_f32_16x16x32_bf16 v[116:119], v[142:145], v[170:173], v[116:119]
	v_mfma_f32_16x16x32_bf16 v[112:115], v[150:153], v[170:173], v[112:115]
	s_waitcnt lgkmcnt(3)
	v_mfma_f32_16x16x32_bf16 v[108:111], v[142:145], v[180:183], v[108:111]
	v_mfma_f32_16x16x32_bf16 v[104:107], v[150:153], v[180:183], v[104:107]
	s_waitcnt lgkmcnt(1)
	v_mfma_f32_16x16x32_bf16 v[100:103], v[142:145], v[188:191], v[100:103]
	v_mfma_f32_16x16x32_bf16 v[96:99], v[150:153], v[188:191], v[96:99]
	v_mfma_f32_16x16x32_bf16 v[124:127], v[146:149], v[166:169], v[124:127]
	v_mfma_f32_16x16x32_bf16 v[120:123], v[154:157], v[166:169], v[120:123]
	v_mfma_f32_16x16x32_bf16 v[116:119], v[146:149], v[176:179], v[116:119]
	v_mfma_f32_16x16x32_bf16 v[112:115], v[154:157], v[176:179], v[112:115]
	v_mfma_f32_16x16x32_bf16 v[108:111], v[146:149], v[184:187], v[108:111]
	v_mfma_f32_16x16x32_bf16 v[104:107], v[154:157], v[184:187], v[104:107]
	s_waitcnt lgkmcnt(0)
	v_mfma_f32_16x16x32_bf16 v[100:103], v[146:149], v[192:195], v[100:103]
	v_mfma_f32_16x16x32_bf16 v[96:99], v[154:157], v[192:195], v[96:99]
	s_barrier
	ds_read_b128 v[196:199], v138
	ds_read_b128 v[200:203], v138 offset:1024
	ds_read_b128 v[204:207], v138 offset:2048
	ds_read_b128 v[208:211], v138 offset:3072
	s_waitcnt vmcnt(8)
	s_barrier
	s_waitcnt lgkmcnt(3)
	v_mfma_f32_16x16x32_bf16 v[76:79], v[196:199], v[180:183], v[76:79]
	s_waitcnt lgkmcnt(1)
	v_mfma_f32_16x16x32_bf16 v[72:75], v[204:207], v[180:183], v[72:75]
	v_mfma_f32_16x16x32_bf16 v[68:71], v[196:199], v[188:191], v[68:71]
	v_mfma_f32_16x16x32_bf16 v[64:67], v[204:207], v[188:191], v[64:67]
	v_mfma_f32_16x16x32_bf16 v[92:95], v[196:199], v[162:165], v[92:95]
	v_mfma_f32_16x16x32_bf16 v[88:91], v[204:207], v[162:165], v[88:91]
	v_mfma_f32_16x16x32_bf16 v[84:87], v[196:199], v[170:173], v[84:87]
	v_mfma_f32_16x16x32_bf16 v[80:83], v[204:207], v[170:173], v[80:83]
	v_mfma_f32_16x16x32_bf16 v[76:79], v[200:203], v[184:187], v[76:79]
	s_waitcnt lgkmcnt(0)
	v_mfma_f32_16x16x32_bf16 v[72:75], v[208:211], v[184:187], v[72:75]
	v_mfma_f32_16x16x32_bf16 v[68:71], v[200:203], v[192:195], v[68:71]
	v_mfma_f32_16x16x32_bf16 v[64:67], v[208:211], v[192:195], v[64:67]
	v_mfma_f32_16x16x32_bf16 v[212:215], v[200:203], v[166:169], v[92:95]
	v_mfma_f32_16x16x32_bf16 v[162:165], v[208:211], v[166:169], v[88:91]
	v_mfma_f32_16x16x32_bf16 v[166:169], v[200:203], v[176:179], v[84:87]
	v_mfma_f32_16x16x32_bf16 v[170:173], v[208:211], v[176:179], v[80:83]
	s_barrier
; #define LDA(dst, b, h)                                                                                               \
;   _Pragma("unroll") for (int m = 0; m < 4; ++m) _Pragma("unroll") for (int k = 0; k < 2; ++k) dst[m][k] =            \
;       *reinterpret_cast<const bf16x8*>(SA(b, h) + lds_byte(wr * 64 + m * 16 + fr, k * 32 + fq * 8))
; #define LDB(dst, b, h)                                                                                               \
;   _Pragma("unroll") for (int n = 0; n < 2; ++n) _Pragma("unroll") for (int k = 0; k < 2; ++k) dst[n][k] =            \
;       *reinterpret_cast<const bf16x8*>(SB(b, h) + lds_byte(wc * 32 + n * 16 + fr, k * 32 + fq * 8))
; #define WAIT_V(n) asm volatile("s_waitcnt vmcnt(" #n ")" ::: "memory")
; #define WAIT_L(n) asm volatile("s_waitcnt lgkmcnt(" #n ")" ::: "memory")
; #define BAR __builtin_amdgcn_s_barrier()
; template <int EPI>
; __device__ __forceinline__ void gemm_phase(const u16* __restrict__ A, const u16* __restrict__ Bt, const int K,
;                                            const int nN, char* shm, const EpiArgs& ea) {
;     ...
;       LDA(At, 0, 1); WAIT_V(4); BAR; WAIT_L(0); MMA(1, 0, At, B0); MMA(1, 1, At, B1); BAR;
;     }
;     {
;       LDB(B0, 1, 0); LDA(At, 1, 0); WAIT_V(2); BAR; WAIT_L(0); MMA(0, 0, At, B0); BAR;
	s_nop 0
	ds_read_b128 v[80:83], v134 offset:16384
	ds_read_b128 v[84:87], v134 offset:17408
	ds_read_b128 v[88:91], v135 offset:16384
	ds_read_b128 v[92:95], v135 offset:17408
	ds_read_b128 v[176:179], v136 offset:16384
	ds_read_b128 v[180:183], v136 offset:17408
	ds_read_b128 v[184:187], v137 offset:16384
	ds_read_b128 v[188:191], v137 offset:17408
	s_waitcnt vmcnt(4)
	s_barrier
	s_waitcnt lgkmcnt(7)
	v_mfma_f32_16x16x32_bf16 v[60:63], v[142:145], v[80:83], v[60:63]
	v_mfma_f32_16x16x32_bf16 v[56:59], v[150:153], v[80:83], v[56:59]
	s_waitcnt lgkmcnt(5)
	v_mfma_f32_16x16x32_bf16 v[52:55], v[142:145], v[88:91], v[52:55]
	v_mfma_f32_16x16x32_bf16 v[48:51], v[150:153], v[88:91], v[48:51]
	s_waitcnt lgkmcnt(3)
	v_mfma_f32_16x16x32_bf16 v[44:47], v[142:145], v[176:179], v[44:47]
	v_mfma_f32_16x16x32_bf16 v[40:43], v[150:153], v[176:179], v[40:43]
	s_waitcnt lgkmcnt(1)
	v_mfma_f32_16x16x32_bf16 v[36:39], v[142:145], v[184:187], v[36:39]
	v_mfma_f32_16x16x32_bf16 v[32:35], v[150:153], v[184:187], v[32:35]
	v_mfma_f32_16x16x32_bf16 v[60:63], v[146:149], v[84:87], v[60:63]
	v_mfma_f32_16x16x32_bf16 v[56:59], v[154:157], v[84:87], v[56:59]
	v_mfma_f32_16x16x32_bf16 v[52:55], v[146:149], v[92:95], v[52:55]
	v_mfma_f32_16x16x32_bf16 v[48:51], v[154:157], v[92:95], v[48:51]
	v_mfma_f32_16x16x32_bf16 v[44:47], v[146:149], v[180:183], v[44:47]
	v_mfma_f32_16x16x32_bf16 v[40:43], v[154:157], v[180:183], v[40:43]
	s_waitcnt lgkmcnt(0)
	v_mfma_f32_16x16x32_bf16 v[36:39], v[146:149], v[188:191], v[36:39]
	v_mfma_f32_16x16x32_bf16 v[32:35], v[154:157], v[188:191], v[32:35]
	v_mfma_f32_16x16x32_bf16 v[12:15], v[196:199], v[176:179], v[12:15]
	v_mfma_f32_16x16x32_bf16 v[8:11], v[204:207], v[176:179], v[8:11]
	v_mfma_f32_16x16x32_bf16 v[4:7], v[196:199], v[184:187], v[4:7]
	v_mfma_f32_16x16x32_bf16 v[0:3], v[204:207], v[184:187], v[0:3]
	v_mfma_f32_16x16x32_bf16 v[28:31], v[196:199], v[80:83], v[28:31]
	v_mfma_f32_16x16x32_bf16 v[24:27], v[204:207], v[80:83], v[24:27]
	v_mfma_f32_16x16x32_bf16 v[20:23], v[196:199], v[88:91], v[20:23]
	v_mfma_f32_16x16x32_bf16 v[16:19], v[204:207], v[88:91], v[16:19]
	v_mfma_f32_16x16x32_bf16 v[12:15], v[200:203], v[180:183], v[12:15]
	v_mfma_f32_16x16x32_bf16 v[8:11], v[208:211], v[180:183], v[8:11]
	v_mfma_f32_16x16x32_bf16 v[4:7], v[200:203], v[188:191], v[4:7]
	v_mfma_f32_16x16x32_bf16 v[0:3], v[208:211], v[188:191], v[0:3]
	v_mfma_f32_16x16x32_bf16 v[142:145], v[200:203], v[84:87], v[28:31]
	v_mfma_f32_16x16x32_bf16 v[146:149], v[208:211], v[84:87], v[24:27]
	v_mfma_f32_16x16x32_bf16 v[150:153], v[200:203], v[92:95], v[20:23]
	v_mfma_f32_16x16x32_bf16 v[154:157], v[208:211], v[92:95], v[16:19]
	s_barrier
	s_nop 0
	ds_read_b128 v[16:19], v139
	ds_read_b128 v[20:23], v139 offset:1024
	ds_read_b128 v[176:179], v139 offset:2048
	ds_read_b128 v[180:183], v139 offset:3072
	ds_read_b128 v[24:27], v134 offset:32768
	ds_read_b128 v[28:31], v134 offset:33792
	ds_read_b128 v[184:187], v135 offset:32768
	ds_read_b128 v[188:191], v135 offset:33792
	ds_read_b128 v[192:195], v136 offset:32768
	ds_read_b128 v[196:199], v136 offset:33792
	ds_read_b128 v[200:203], v137 offset:32768
	ds_read_b128 v[204:207], v137 offset:33792
	s_waitcnt vmcnt(2)
	s_barrier
	s_waitcnt lgkmcnt(7)
	v_mfma_f32_16x16x32_bf16 v[80:83], v[16:19], v[24:27], v[124:127]
	s_waitcnt lgkmcnt(6)
	v_mfma_f32_16x16x32_bf16 v[124:127], v[20:23], v[28:31], v[80:83]
	v_mfma_f32_16x16x32_bf16 v[80:83], v[176:179], v[24:27], v[120:123]
	v_mfma_f32_16x16x32_bf16 v[120:123], v[180:183], v[28:31], v[80:83]
	s_waitcnt lgkmcnt(5)
	v_mfma_f32_16x16x32_bf16 v[80:83], v[16:19], v[184:187], v[116:119]
	s_waitcnt lgkmcnt(4)
	v_mfma_f32_16x16x32_bf16 v[116:119], v[20:23], v[188:191], v[80:83]
	v_mfma_f32_16x16x32_bf16 v[80:83], v[176:179], v[184:187], v[112:115]
	v_mfma_f32_16x16x32_bf16 v[112:115], v[180:183], v[188:191], v[80:83]
	s_waitcnt lgkmcnt(3)
	v_mfma_f32_16x16x32_bf16 v[80:83], v[16:19], v[192:195], v[108:111]
	s_waitcnt lgkmcnt(2)
	v_mfma_f32_16x16x32_bf16 v[92:95], v[20:23], v[196:199], v[80:83]
	v_mfma_f32_16x16x32_bf16 v[80:83], v[176:179], v[192:195], v[104:107]
	v_mfma_f32_16x16x32_bf16 v[88:91], v[180:183], v[196:199], v[80:83]
	s_waitcnt lgkmcnt(1)
	v_mfma_f32_16x16x32_bf16 v[80:83], v[16:19], v[200:203], v[100:103]
	s_waitcnt lgkmcnt(0)
	v_mfma_f32_16x16x32_bf16 v[84:87], v[20:23], v[204:207], v[80:83]
	v_mfma_f32_16x16x32_bf16 v[80:83], v[176:179], v[200:203], v[96:99]
	v_mfma_f32_16x16x32_bf16 v[80:83], v[180:183], v[204:207], v[80:83]
	s_barrier
; #define LDA(dst, b, h)                                                                                               \
;   _Pragma("unroll") for (int m = 0; m < 4; ++m) _Pragma("unroll") for (int k = 0; k < 2; ++k) dst[m][k] =            \
;       *reinterpret_cast<const bf16x8*>(SA(b, h) + lds_byte(wr * 64 + m * 16 + fr, k * 32 + fq * 8))
; #define LDB(dst, b, h)                                                                                               \
;   _Pragma("unroll") for (int n = 0; n < 2; ++n) _Pragma("unroll") for (int k = 0; k < 2; ++k) dst[n][k] =            \
;       *reinterpret_cast<const bf16x8*>(SB(b, h) + lds_byte(wc * 32 + n * 16 + fr, k * 32 + fq * 8))
; #define WAIT_V(n) asm volatile("s_waitcnt vmcnt(" #n ")" ::: "memory")
; #define WAIT_L(n) asm volatile("s_waitcnt lgkmcnt(" #n ")" ::: "memory")
; #define BAR __builtin_amdgcn_s_barrier()
; template <int EPI>
; __device__ __forceinline__ void gemm_phase(const u16* __restrict__ A, const u16* __restrict__ Bt, const int K,
;                                            const int nN, char* shm, const EpiArgs& ea) {
;     ...
;       LDB(B0, 1, 0); LDA(At, 1, 0); WAIT_V(2); BAR; WAIT_L(0); MMA(0, 0, At, B0); BAR;
;       LDB(B1, 1, 1); WAIT_V(0); BAR; WAIT_L(0); MMA(0, 1, At, B1); BAR;
;       LDA(At, 1, 1); BAR; WAIT_L(0); MMA(1, 0, At, B0); MMA(1, 1, At, B1); BAR;
;     }
;     if (wr == 0) BAR;
	ds_read_b128 v[208:211], v140
	ds_read_b128 v[216:219], v140 offset:1024
	ds_read_b128 v[220:223], v140 offset:2048
	ds_read_b128 v[224:227], v140 offset:3072
	s_waitcnt vmcnt(0)
	s_barrier
	s_waitcnt lgkmcnt(3)
	v_mfma_f32_16x16x32_bf16 v[96:99], v[208:211], v[24:27], v[212:215]
	s_waitcnt lgkmcnt(1)
	v_mfma_f32_16x16x32_bf16 v[24:27], v[220:223], v[24:27], v[162:165]
	s_waitcnt lgkmcnt(0)
	v_mfma_f32_16x16x32_bf16 v[104:107], v[224:227], v[28:31], v[24:27]
	v_mfma_f32_16x16x32_bf16 v[24:27], v[208:211], v[184:187], v[166:169]
	v_mfma_f32_16x16x32_bf16 v[100:103], v[216:219], v[188:191], v[24:27]
	v_mfma_f32_16x16x32_bf16 v[24:27], v[220:223], v[184:187], v[170:173]
	v_mfma_f32_16x16x32_bf16 v[108:111], v[216:219], v[28:31], v[96:99]
	v_mfma_f32_16x16x32_bf16 v[96:99], v[224:227], v[188:191], v[24:27]
	v_mfma_f32_16x16x32_bf16 v[24:27], v[208:211], v[192:195], v[76:79]
	v_mfma_f32_16x16x32_bf16 v[76:79], v[216:219], v[196:199], v[24:27]
	v_mfma_f32_16x16x32_bf16 v[24:27], v[220:223], v[192:195], v[72:75]
	v_mfma_f32_16x16x32_bf16 v[72:75], v[224:227], v[196:199], v[24:27]
	v_mfma_f32_16x16x32_bf16 v[24:27], v[208:211], v[200:203], v[68:71]
	v_mfma_f32_16x16x32_bf16 v[68:71], v[216:219], v[204:207], v[24:27]
	v_mfma_f32_16x16x32_bf16 v[24:27], v[220:223], v[200:203], v[64:67]
	v_mfma_f32_16x16x32_bf16 v[64:67], v[224:227], v[204:207], v[24:27]
	s_barrier
	ds_read_b128 v[162:165], v134 offset:49152
	ds_read_b128 v[166:169], v134 offset:50176
	ds_read_b128 v[170:173], v135 offset:49152
	ds_read_b128 v[184:187], v135 offset:50176
	ds_read_b128 v[188:191], v136 offset:49152
	ds_read_b128 v[192:195], v136 offset:50176
	ds_read_b128 v[196:199], v137 offset:49152
	ds_read_b128 v[200:203], v137 offset:50176
	s_barrier
	s_waitcnt lgkmcnt(7)
	v_mfma_f32_16x16x32_bf16 v[24:27], v[16:19], v[162:165], v[60:63]
	s_waitcnt lgkmcnt(6)
	v_mfma_f32_16x16x32_bf16 v[60:63], v[20:23], v[166:169], v[24:27]
	v_mfma_f32_16x16x32_bf16 v[24:27], v[176:179], v[162:165], v[56:59]
	v_mfma_f32_16x16x32_bf16 v[56:59], v[180:183], v[166:169], v[24:27]
	s_waitcnt lgkmcnt(5)
	v_mfma_f32_16x16x32_bf16 v[24:27], v[16:19], v[170:173], v[52:55]
	s_waitcnt lgkmcnt(4)
	v_mfma_f32_16x16x32_bf16 v[52:55], v[20:23], v[184:187], v[24:27]
	v_mfma_f32_16x16x32_bf16 v[24:27], v[176:179], v[170:173], v[48:51]
	v_mfma_f32_16x16x32_bf16 v[48:51], v[180:183], v[184:187], v[24:27]
	s_waitcnt lgkmcnt(3)
	v_mfma_f32_16x16x32_bf16 v[24:27], v[16:19], v[188:191], v[44:47]
	s_waitcnt lgkmcnt(1)
	v_mfma_f32_16x16x32_bf16 v[16:19], v[16:19], v[196:199], v[36:39]
	v_mfma_f32_16x16x32_bf16 v[28:31], v[20:23], v[192:195], v[24:27]
	v_mfma_f32_16x16x32_bf16 v[24:27], v[176:179], v[188:191], v[40:43]
	s_waitcnt lgkmcnt(0)
	v_mfma_f32_16x16x32_bf16 v[20:23], v[20:23], v[200:203], v[16:19]
	v_mfma_f32_16x16x32_bf16 v[16:19], v[176:179], v[196:199], v[32:35]
	v_mfma_f32_16x16x32_bf16 v[24:27], v[180:183], v[192:195], v[24:27]
	v_mfma_f32_16x16x32_bf16 v[16:19], v[180:183], v[200:203], v[16:19]
	v_mfma_f32_16x16x32_bf16 v[32:35], v[208:211], v[162:165], v[142:145]
	v_mfma_f32_16x16x32_bf16 v[44:47], v[216:219], v[166:169], v[32:35]
	v_mfma_f32_16x16x32_bf16 v[32:35], v[220:223], v[162:165], v[146:149]
	v_mfma_f32_16x16x32_bf16 v[40:43], v[224:227], v[166:169], v[32:35]
	v_mfma_f32_16x16x32_bf16 v[32:35], v[208:211], v[170:173], v[150:153]
	v_mfma_f32_16x16x32_bf16 v[36:39], v[216:219], v[184:187], v[32:35]
	v_mfma_f32_16x16x32_bf16 v[32:35], v[220:223], v[170:173], v[154:157]
	v_mfma_f32_16x16x32_bf16 v[12:15], v[208:211], v[188:191], v[12:15]
	v_mfma_f32_16x16x32_bf16 v[8:11], v[220:223], v[188:191], v[8:11]
	v_mfma_f32_16x16x32_bf16 v[4:7], v[208:211], v[196:199], v[4:7]
	v_mfma_f32_16x16x32_bf16 v[0:3], v[220:223], v[196:199], v[0:3]
	v_mfma_f32_16x16x32_bf16 v[32:35], v[224:227], v[184:187], v[32:35]
	v_mfma_f32_16x16x32_bf16 v[12:15], v[216:219], v[192:195], v[12:15]
	v_mfma_f32_16x16x32_bf16 v[8:11], v[224:227], v[192:195], v[8:11]
	v_mfma_f32_16x16x32_bf16 v[4:7], v[216:219], v[200:203], v[4:7]
	v_mfma_f32_16x16x32_bf16 v[0:3], v[224:227], v[200:203], v[0:3]
	s_andn2_b64 vcc, exec, s[26:27]
	s_barrier
	s_cbranch_vccnz .LBB0_175
	s_barrier

; #define LDA(dst, b, h)                                                                                               \
;   _Pragma("unroll") for (int m = 0; m < 4; ++m) _Pragma("unroll") for (int k = 0; k < 2; ++k) dst[m][k] =            \
;       *reinterpret_cast<const bf16x8*>(SA(b, h) + lds_byte(wr * 64 + m * 16 + fr, k * 32 + fq * 8))
; #define LDB(dst, b, h)                                                                                               \
;   _Pragma("unroll") for (int n = 0; n < 2; ++n) _Pragma("unroll") for (int k = 0; k < 2; ++k) dst[n][k] =            \
;       *reinterpret_cast<const bf16x8*>(SB(b, h) + lds_byte(wc * 32 + n * 16 + fr, k * 32 + fq * 8))
; #define WAIT_V(n) asm volatile("s_waitcnt vmcnt(" #n ")" ::: "memory")
; #define WAIT_L(n) asm volatile("s_waitcnt lgkmcnt(" #n ")" ::: "memory")
; #define BAR __builtin_amdgcn_s_barrier()
; #define SCHED __builtin_amdgcn_sched_barrier(0)
; template <int EPI>
; __device__ __forceinline__ void gemm_phase(const u16* __restrict__ A, const u16* __restrict__ Bt, const int K,
;                                            const int nN, char* shm, const EpiArgs& ea) {
;     ...
;     for (int t = 0; t < nt - 2; t += 2) {
;       LDB(B0, 0, 0); SCHED; LDA(At, 0, 0); STAGE(SA(1, 1), rA, brow + HALF, t + 1);
;       WAIT_V(10); WAIT_L(8); BAR; WAIT_L(0); MMA(0, 0, At, B0); BAR; SCHED;
;       LDB(B1, 0, 1); STAGE(SB(0, 0), rB, bcol, t + 2);
;       WAIT_V(10); BAR; WAIT_L(0); MMA(0, 1, At, B1); BAR;
;       LDA(At, 0, 1); STAGE(SA(0, 0), rA, brow, t + 2);
;       BAR; WAIT_L(0); MMA(1, 0, At, B0); BAR; SCHED;
;       STAGE(SB(0, 1), rB, bcol + HALF, t + 2);
;       WAIT_V(10); BAR; MMA(1, 1, At, B1); BAR;
.LBB0_231:
	ds_read_b128 v[130:133], v138
	ds_read_b128 v[146:149], v138 offset:1024
	ds_read_b128 v[150:153], v138 offset:2048
	ds_read_b128 v[154:157], v138 offset:3072
	s_add_i32 s78, s70, s75
	s_mov_b32 m0, s48
	s_add_i32 s26, s78, 0x4000
	ds_read_b128 v[162:165], v139
	ds_read_b128 v[166:169], v139 offset:1024
	ds_read_b128 v[170:173], v140
	ds_read_b128 v[176:179], v140 offset:1024
	ds_read_b128 v[180:183], v141
	ds_read_b128 v[184:187], v141 offset:1024
	ds_read_b128 v[188:191], v142
	ds_read_b128 v[192:195], v142 offset:1024
	buffer_load_dwordx4 v134, s[0:3], s26 offen lds
	s_add_i32 s26, s78, 0x6000
	s_mov_b32 m0, s49
	s_nop 0
	buffer_load_dwordx4 v134, s[0:3], s26 offen lds
	s_waitcnt vmcnt(10)
	s_waitcnt lgkmcnt(8)
	s_barrier
	s_waitcnt lgkmcnt(7)
	v_mfma_f32_16x16x32_bf16 v[124:127], v[130:133], v[162:165], v[124:127]
	v_mfma_f32_16x16x32_bf16 v[120:123], v[150:153], v[162:165], v[120:123]
	s_waitcnt lgkmcnt(5)
	v_mfma_f32_16x16x32_bf16 v[116:119], v[130:133], v[170:173], v[116:119]
	v_mfma_f32_16x16x32_bf16 v[112:115], v[150:153], v[170:173], v[112:115]
	s_waitcnt lgkmcnt(3)
	v_mfma_f32_16x16x32_bf16 v[108:111], v[130:133], v[180:183], v[108:111]
	v_mfma_f32_16x16x32_bf16 v[104:107], v[150:153], v[180:183], v[104:107]
	s_waitcnt lgkmcnt(1)
	v_mfma_f32_16x16x32_bf16 v[100:103], v[130:133], v[188:191], v[100:103]
	v_mfma_f32_16x16x32_bf16 v[96:99], v[150:153], v[188:191], v[96:99]
	v_mfma_f32_16x16x32_bf16 v[124:127], v[146:149], v[166:169], v[124:127]
	v_mfma_f32_16x16x32_bf16 v[120:123], v[154:157], v[166:169], v[120:123]
	v_mfma_f32_16x16x32_bf16 v[116:119], v[146:149], v[176:179], v[116:119]
	v_mfma_f32_16x16x32_bf16 v[112:115], v[154:157], v[176:179], v[112:115]
	v_mfma_f32_16x16x32_bf16 v[108:111], v[146:149], v[184:187], v[108:111]
	v_mfma_f32_16x16x32_bf16 v[104:107], v[154:157], v[184:187], v[104:107]
	s_waitcnt lgkmcnt(0)
	v_mfma_f32_16x16x32_bf16 v[100:103], v[146:149], v[192:195], v[100:103]
	v_mfma_f32_16x16x32_bf16 v[96:99], v[154:157], v[192:195], v[96:99]
	s_barrier
	s_add_i32 s79, s73, s75
	s_mov_b32 m0, s52
	s_add_i32 s80, s79, 0x8000
	s_mov_b32 s26, s2
	s_mov_b32 s27, s3
	ds_read_b128 v[196:199], v143
	ds_read_b128 v[200:203], v143 offset:1024
	ds_read_b128 v[204:207], v143 offset:2048
	ds_read_b128 v[208:211], v143 offset:3072
	buffer_load_dwordx4 v134, s[24:27], s80 offen lds
	s_add_i32 s80, s79, 0xa000
	s_mov_b32 m0, s53
	s_nop 0
	buffer_load_dwordx4 v134, s[24:27], s80 offen lds
	s_waitcnt vmcnt(10)
	s_barrier
	s_waitcnt lgkmcnt(3)
	v_mfma_f32_16x16x32_bf16 v[92:95], v[196:199], v[162:165], v[92:95]
	s_waitcnt lgkmcnt(1)
	v_mfma_f32_16x16x32_bf16 v[88:91], v[204:207], v[162:165], v[88:91]
	v_mfma_f32_16x16x32_bf16 v[84:87], v[196:199], v[170:173], v[84:87]
	v_mfma_f32_16x16x32_bf16 v[80:83], v[204:207], v[170:173], v[80:83]
	v_mfma_f32_16x16x32_bf16 v[76:79], v[196:199], v[180:183], v[76:79]
	v_mfma_f32_16x16x32_bf16 v[72:75], v[204:207], v[180:183], v[72:75]
	v_mfma_f32_16x16x32_bf16 v[68:71], v[196:199], v[188:191], v[68:71]
	v_mfma_f32_16x16x32_bf16 v[64:67], v[204:207], v[188:191], v[64:67]
	v_mfma_f32_16x16x32_bf16 v[92:95], v[200:203], v[166:169], v[92:95]
	s_waitcnt lgkmcnt(0)
	v_mfma_f32_16x16x32_bf16 v[88:91], v[208:211], v[166:169], v[88:91]
	v_mfma_f32_16x16x32_bf16 v[84:87], v[200:203], v[176:179], v[84:87]
	v_mfma_f32_16x16x32_bf16 v[80:83], v[208:211], v[176:179], v[80:83]
	v_mfma_f32_16x16x32_bf16 v[76:79], v[200:203], v[184:187], v[76:79]
	v_mfma_f32_16x16x32_bf16 v[72:75], v[208:211], v[184:187], v[72:75]
	v_mfma_f32_16x16x32_bf16 v[68:71], v[200:203], v[192:195], v[68:71]
	v_mfma_f32_16x16x32_bf16 v[64:67], v[208:211], v[192:195], v[64:67]
	s_add_i32 s80, s72, s75
	s_mov_b32 m0, s43
	s_add_i32 s81, s80, 0x8000
	s_barrier
	ds_read_b128 v[162:165], v139 offset:16384
	ds_read_b128 v[166:169], v139 offset:17408
	ds_read_b128 v[170:173], v140 offset:16384
	ds_read_b128 v[176:179], v140 offset:17408
	ds_read_b128 v[180:183], v141 offset:16384
	ds_read_b128 v[184:187], v141 offset:17408
	ds_read_b128 v[188:191], v142 offset:16384
	ds_read_b128 v[192:195], v142 offset:17408
	buffer_load_dwordx4 v134, s[0:3], s81 offen lds
	s_add_i32 s81, s80, 0xa000
	s_mov_b32 m0, s54
	s_nop 0
	buffer_load_dwordx4 v134, s[0:3], s81 offen lds
	s_barrier
	s_waitcnt lgkmcnt(7)
	v_mfma_f32_16x16x32_bf16 v[60:63], v[130:133], v[162:165], v[60:63]
	v_mfma_f32_16x16x32_bf16 v[56:59], v[150:153], v[162:165], v[56:59]
	s_waitcnt lgkmcnt(5)
	v_mfma_f32_16x16x32_bf16 v[52:55], v[130:133], v[170:173], v[52:55]
	v_mfma_f32_16x16x32_bf16 v[48:51], v[150:153], v[170:173], v[48:51]
	s_waitcnt lgkmcnt(3)
	v_mfma_f32_16x16x32_bf16 v[44:47], v[130:133], v[180:183], v[44:47]
	v_mfma_f32_16x16x32_bf16 v[40:43], v[150:153], v[180:183], v[40:43]
	s_waitcnt lgkmcnt(1)
	v_mfma_f32_16x16x32_bf16 v[36:39], v[130:133], v[188:191], v[36:39]
	v_mfma_f32_16x16x32_bf16 v[32:35], v[150:153], v[188:191], v[32:35]
	v_mfma_f32_16x16x32_bf16 v[60:63], v[146:149], v[166:169], v[60:63]
	v_mfma_f32_16x16x32_bf16 v[56:59], v[154:157], v[166:169], v[56:59]
	v_mfma_f32_16x16x32_bf16 v[52:55], v[146:149], v[176:179], v[52:55]
	v_mfma_f32_16x16x32_bf16 v[48:51], v[154:157], v[176:179], v[48:51]
	v_mfma_f32_16x16x32_bf16 v[44:47], v[146:149], v[184:187], v[44:47]
	v_mfma_f32_16x16x32_bf16 v[40:43], v[154:157], v[184:187], v[40:43]
	s_waitcnt lgkmcnt(0)
	v_mfma_f32_16x16x32_bf16 v[36:39], v[146:149], v[192:195], v[36:39]
	v_mfma_f32_16x16x32_bf16 v[32:35], v[154:157], v[192:195], v[32:35]
	s_barrier
	s_add_i32 s81, s71, s75
	s_mov_b32 m0, s55
	s_add_i32 s82, s81, 0x8000
	buffer_load_dwordx4 v134, s[24:27], s82 offen lds
	s_add_i32 s82, s81, 0xa000
	s_mov_b32 m0, s56
	s_nop 0
	buffer_load_dwordx4 v134, s[24:27], s82 offen lds
	s_waitcnt vmcnt(10)
	s_barrier
; #define LDA(dst, b, h)                                                                                               \
;   _Pragma("unroll") for (int m = 0; m < 4; ++m) _Pragma("unroll") for (int k = 0; k < 2; ++k) dst[m][k] =            \
;       *reinterpret_cast<const bf16x8*>(SA(b, h) + lds_byte(wr * 64 + m * 16 + fr, k * 32 + fq * 8))
; #define LDB(dst, b, h)                                                                                               \
;   _Pragma("unroll") for (int n = 0; n < 2; ++n) _Pragma("unroll") for (int k = 0; k < 2; ++k) dst[n][k] =            \
;       *reinterpret_cast<const bf16x8*>(SB(b, h) + lds_byte(wc * 32 + n * 16 + fr, k * 32 + fq * 8))
; #define WAIT_V(n) asm volatile("s_waitcnt vmcnt(" #n ")" ::: "memory")
; #define WAIT_L(n) asm volatile("s_waitcnt lgkmcnt(" #n ")" ::: "memory")
; #define BAR __builtin_amdgcn_s_barrier()
; #define SCHED __builtin_amdgcn_sched_barrier(0)
; template <int EPI>
; __device__ __forceinline__ void gemm_phase(const u16* __restrict__ A, const u16* __restrict__ Bt, const int K,
;                                            const int nN, char* shm, const EpiArgs& ea) {
;     ...
;       WAIT_V(10); BAR; MMA(1, 1, At, B1); BAR;
;       LDB(B0, 1, 0); SCHED; LDA(At, 1, 0); STAGE(SA(0, 1), rA, brow + HALF, t + 2);
;       WAIT_V(10); WAIT_L(8); BAR; WAIT_L(0); MMA(0, 0, At, B0); BAR; SCHED;
;       LDB(B1, 1, 1); STAGE(SB(1, 0), rB, bcol, t + 3);
;       WAIT_V(10); BAR; WAIT_L(0); MMA(0, 1, At, B1); BAR;
;       LDA(At, 1, 1); STAGE(SA(1, 0), rA, brow, t + 3);
	v_mfma_f32_16x16x32_bf16 v[28:31], v[196:199], v[162:165], v[28:31]
	v_mfma_f32_16x16x32_bf16 v[24:27], v[204:207], v[162:165], v[24:27]
	v_mfma_f32_16x16x32_bf16 v[20:23], v[196:199], v[170:173], v[20:23]
	v_mfma_f32_16x16x32_bf16 v[16:19], v[204:207], v[170:173], v[16:19]
	v_mfma_f32_16x16x32_bf16 v[12:15], v[196:199], v[180:183], v[12:15]
	v_mfma_f32_16x16x32_bf16 v[8:11], v[204:207], v[180:183], v[8:11]
	v_mfma_f32_16x16x32_bf16 v[4:7], v[196:199], v[188:191], v[4:7]
	v_mfma_f32_16x16x32_bf16 v[0:3], v[204:207], v[188:191], v[0:3]
	v_mfma_f32_16x16x32_bf16 v[28:31], v[200:203], v[166:169], v[28:31]
	v_mfma_f32_16x16x32_bf16 v[24:27], v[208:211], v[166:169], v[24:27]
	v_mfma_f32_16x16x32_bf16 v[20:23], v[200:203], v[176:179], v[20:23]
	v_mfma_f32_16x16x32_bf16 v[16:19], v[208:211], v[176:179], v[16:19]
	v_mfma_f32_16x16x32_bf16 v[12:15], v[200:203], v[184:187], v[12:15]
	v_mfma_f32_16x16x32_bf16 v[8:11], v[208:211], v[184:187], v[8:11]
	v_mfma_f32_16x16x32_bf16 v[4:7], v[200:203], v[192:195], v[4:7]
	v_mfma_f32_16x16x32_bf16 v[0:3], v[208:211], v[192:195], v[0:3]
	s_barrier
	ds_read_b128 v[130:133], v144
	ds_read_b128 v[146:149], v144 offset:1024
	ds_read_b128 v[150:153], v144 offset:2048
	ds_read_b128 v[154:157], v144 offset:3072
	s_mov_b32 m0, s57
	s_add_i32 s82, s78, 0x8000
	ds_read_b128 v[162:165], v139 offset:32768
	ds_read_b128 v[166:169], v139 offset:33792
	ds_read_b128 v[170:173], v140 offset:32768
	ds_read_b128 v[176:179], v140 offset:33792
	ds_read_b128 v[180:183], v141 offset:32768
	ds_read_b128 v[184:187], v141 offset:33792
	ds_read_b128 v[188:191], v142 offset:32768
	ds_read_b128 v[192:195], v142 offset:33792
	buffer_load_dwordx4 v134, s[0:3], s82 offen lds
	s_add_i32 s78, s78, 0xa000
	s_mov_b32 m0, s58
	s_nop 0
	buffer_load_dwordx4 v134, s[0:3], s78 offen lds
	s_waitcnt vmcnt(10)
	s_waitcnt lgkmcnt(8)
	s_barrier
	s_waitcnt lgkmcnt(7)
	v_mfma_f32_16x16x32_bf16 v[124:127], v[130:133], v[162:165], v[124:127]
	v_mfma_f32_16x16x32_bf16 v[120:123], v[150:153], v[162:165], v[120:123]
	s_waitcnt lgkmcnt(5)
	v_mfma_f32_16x16x32_bf16 v[116:119], v[130:133], v[170:173], v[116:119]
	v_mfma_f32_16x16x32_bf16 v[112:115], v[150:153], v[170:173], v[112:115]
	s_waitcnt lgkmcnt(3)
	v_mfma_f32_16x16x32_bf16 v[108:111], v[130:133], v[180:183], v[108:111]
	v_mfma_f32_16x16x32_bf16 v[104:107], v[150:153], v[180:183], v[104:107]
	s_waitcnt lgkmcnt(1)
	v_mfma_f32_16x16x32_bf16 v[100:103], v[130:133], v[188:191], v[100:103]
	v_mfma_f32_16x16x32_bf16 v[96:99], v[150:153], v[188:191], v[96:99]
	v_mfma_f32_16x16x32_bf16 v[124:127], v[146:149], v[166:169], v[124:127]
	v_mfma_f32_16x16x32_bf16 v[120:123], v[154:157], v[166:169], v[120:123]
	v_mfma_f32_16x16x32_bf16 v[116:119], v[146:149], v[176:179], v[116:119]
	v_mfma_f32_16x16x32_bf16 v[112:115], v[154:157], v[176:179], v[112:115]
	v_mfma_f32_16x16x32_bf16 v[108:111], v[146:149], v[184:187], v[108:111]
	v_mfma_f32_16x16x32_bf16 v[104:107], v[154:157], v[184:187], v[104:107]
	s_waitcnt lgkmcnt(0)
	v_mfma_f32_16x16x32_bf16 v[100:103], v[146:149], v[192:195], v[100:103]
	v_mfma_f32_16x16x32_bf16 v[96:99], v[154:157], v[192:195], v[96:99]
	s_barrier
	s_mov_b32 m0, s59
	s_add_i32 s78, s79, 0xc000
	ds_read_b128 v[196:199], v145
	ds_read_b128 v[200:203], v145 offset:1024
	ds_read_b128 v[204:207], v145 offset:2048
	ds_read_b128 v[208:211], v145 offset:3072
	buffer_load_dwordx4 v134, s[24:27], s78 offen lds
	s_add_i32 s79, s79, 0xe000
	s_mov_b32 m0, s60
	s_nop 0
	buffer_load_dwordx4 v134, s[24:27], s79 offen lds
	s_waitcnt vmcnt(10)
	s_barrier
	s_waitcnt lgkmcnt(3)
	v_mfma_f32_16x16x32_bf16 v[92:95], v[196:199], v[162:165], v[92:95]
	s_waitcnt lgkmcnt(1)
	v_mfma_f32_16x16x32_bf16 v[88:91], v[204:207], v[162:165], v[88:91]
	v_mfma_f32_16x16x32_bf16 v[84:87], v[196:199], v[170:173], v[84:87]
	v_mfma_f32_16x16x32_bf16 v[80:83], v[204:207], v[170:173], v[80:83]
	v_mfma_f32_16x16x32_bf16 v[76:79], v[196:199], v[180:183], v[76:79]
	v_mfma_f32_16x16x32_bf16 v[72:75], v[204:207], v[180:183], v[72:75]
	v_mfma_f32_16x16x32_bf16 v[68:71], v[196:199], v[188:191], v[68:71]
	v_mfma_f32_16x16x32_bf16 v[64:67], v[204:207], v[188:191], v[64:67]
	v_mfma_f32_16x16x32_bf16 v[92:95], v[200:203], v[166:169], v[92:95]
	s_waitcnt lgkmcnt(0)
	v_mfma_f32_16x16x32_bf16 v[88:91], v[208:211], v[166:169], v[88:91]
	v_mfma_f32_16x16x32_bf16 v[84:87], v[200:203], v[176:179], v[84:87]
	v_mfma_f32_16x16x32_bf16 v[80:83], v[208:211], v[176:179], v[80:83]
	v_mfma_f32_16x16x32_bf16 v[76:79], v[200:203], v[184:187], v[76:79]
	v_mfma_f32_16x16x32_bf16 v[72:75], v[208:211], v[184:187], v[72:75]
	v_mfma_f32_16x16x32_bf16 v[68:71], v[200:203], v[192:195], v[68:71]
	v_mfma_f32_16x16x32_bf16 v[64:67], v[208:211], v[192:195], v[64:67]
	s_mov_b32 m0, s61
	s_add_i32 s78, s80, 0xc000
	s_barrier
	ds_read_b128 v[162:165], v139 offset:49152
	ds_read_b128 v[166:169], v139 offset:50176
	ds_read_b128 v[170:173], v140 offset:49152
	ds_read_b128 v[176:179], v140 offset:50176
	ds_read_b128 v[180:183], v141 offset:49152
	ds_read_b128 v[184:187], v141 offset:50176
	ds_read_b128 v[188:191], v142 offset:49152
	ds_read_b128 v[192:195], v142 offset:50176
	buffer_load_dwordx4 v134, s[0:3], s78 offen lds
	s_add_i32 s80, s80, 0xe000
	s_mov_b32 m0, s62
	s_nop 0
	buffer_load_dwordx4 v134, s[0:3], s80 offen lds
	s_barrier
; #define LDA(dst, b, h)                                                                                               \
;   _Pragma("unroll") for (int m = 0; m < 4; ++m) _Pragma("unroll") for (int k = 0; k < 2; ++k) dst[m][k] =            \
;       *reinterpret_cast<const bf16x8*>(SA(b, h) + lds_byte(wr * 64 + m * 16 + fr, k * 32 + fq * 8))
; #define LDB(dst, b, h)                                                                                               \
;   _Pragma("unroll") for (int n = 0; n < 2; ++n) _Pragma("unroll") for (int k = 0; k < 2; ++k) dst[n][k] =            \
;       *reinterpret_cast<const bf16x8*>(SB(b, h) + lds_byte(wc * 32 + n * 16 + fr, k * 32 + fq * 8))
; #define WAIT_V(n) asm volatile("s_waitcnt vmcnt(" #n ")" ::: "memory")
; #define WAIT_L(n) asm volatile("s_waitcnt lgkmcnt(" #n ")" ::: "memory")
; #define BAR __builtin_amdgcn_s_barrier()
; #define SCHED __builtin_amdgcn_sched_barrier(0)
; template <int EPI>
; __device__ __forceinline__ void gemm_phase(const u16* __restrict__ A, const u16* __restrict__ Bt, const int K,
;                                            const int nN, char* shm, const EpiArgs& ea) {
;     ...
;       BAR; WAIT_L(0); MMA(1, 0, At, B0); BAR; SCHED;
;       STAGE(SB(1, 1), rB, bcol + HALF, t + 3);
;       WAIT_V(10); BAR; MMA(1, 1, At, B1); BAR;
;     }
;     float eC = 0.f, eB = 0.f;
;     float2 eS = make_float2(0.f, 0.f);
;     if (EPI == EPI_IN || EPI == EPI_SWIGLU_LN) {
;       if (wr == 0) {
;         eC = ea.c1[bcol + tid];
;         eS = *(const float2*)(ea.st_in + (size_t)(brow + tid) * 2);
;       } else {
;         eC = ea.c2[bcol + tid - 256];
;         if (EPI == EPI_IN) eB = ea.bias[bcol + tid - 256];
;       }
;     }
;     {
;       LDB(B0, 0, 0); LDA(At, 0, 0); STAGE(SA(1, 1), rA, brow + HALF, nt - 1);
;       WAIT_V(10); BAR; WAIT_L(0); MMA(0, 0, At, B0); BAR;
;       LDB(B1, 0, 1); WAIT_V(8); BAR; WAIT_L(0); MMA(0, 1, At, B1); BAR;
	s_waitcnt lgkmcnt(7)
	v_mfma_f32_16x16x32_bf16 v[60:63], v[130:133], v[162:165], v[60:63]
	v_mfma_f32_16x16x32_bf16 v[56:59], v[150:153], v[162:165], v[56:59]
	s_waitcnt lgkmcnt(5)
	v_mfma_f32_16x16x32_bf16 v[52:55], v[130:133], v[170:173], v[52:55]
	v_mfma_f32_16x16x32_bf16 v[48:51], v[150:153], v[170:173], v[48:51]
	s_waitcnt lgkmcnt(3)
	v_mfma_f32_16x16x32_bf16 v[44:47], v[130:133], v[180:183], v[44:47]
	v_mfma_f32_16x16x32_bf16 v[40:43], v[150:153], v[180:183], v[40:43]
	s_waitcnt lgkmcnt(1)
	v_mfma_f32_16x16x32_bf16 v[36:39], v[130:133], v[188:191], v[36:39]
	v_mfma_f32_16x16x32_bf16 v[32:35], v[150:153], v[188:191], v[32:35]
	v_mfma_f32_16x16x32_bf16 v[60:63], v[146:149], v[166:169], v[60:63]
	v_mfma_f32_16x16x32_bf16 v[56:59], v[154:157], v[166:169], v[56:59]
	v_mfma_f32_16x16x32_bf16 v[52:55], v[146:149], v[176:179], v[52:55]
	v_mfma_f32_16x16x32_bf16 v[48:51], v[154:157], v[176:179], v[48:51]
	v_mfma_f32_16x16x32_bf16 v[44:47], v[146:149], v[184:187], v[44:47]
	v_mfma_f32_16x16x32_bf16 v[40:43], v[154:157], v[184:187], v[40:43]
	s_waitcnt lgkmcnt(0)
	v_mfma_f32_16x16x32_bf16 v[36:39], v[146:149], v[192:195], v[36:39]
	v_mfma_f32_16x16x32_bf16 v[32:35], v[154:157], v[192:195], v[32:35]
	s_barrier
	s_mov_b32 m0, s63
	s_add_i32 s78, s81, 0xc000
	buffer_load_dwordx4 v134, s[24:27], s78 offen lds
	s_add_i32 s81, s81, 0xe000
	s_mov_b32 m0, s64
	s_nop 0
	buffer_load_dwordx4 v134, s[24:27], s81 offen lds
	s_waitcnt vmcnt(10)
	s_barrier
	v_mfma_f32_16x16x32_bf16 v[28:31], v[196:199], v[162:165], v[28:31]
	v_mfma_f32_16x16x32_bf16 v[24:27], v[204:207], v[162:165], v[24:27]
	v_mfma_f32_16x16x32_bf16 v[20:23], v[196:199], v[170:173], v[20:23]
	v_mfma_f32_16x16x32_bf16 v[16:19], v[204:207], v[170:173], v[16:19]
	v_mfma_f32_16x16x32_bf16 v[12:15], v[196:199], v[180:183], v[12:15]
	v_mfma_f32_16x16x32_bf16 v[8:11], v[204:207], v[180:183], v[8:11]
	v_mfma_f32_16x16x32_bf16 v[4:7], v[196:199], v[188:191], v[4:7]
	v_mfma_f32_16x16x32_bf16 v[0:3], v[204:207], v[188:191], v[0:3]
	v_mfma_f32_16x16x32_bf16 v[28:31], v[200:203], v[166:169], v[28:31]
	v_mfma_f32_16x16x32_bf16 v[24:27], v[208:211], v[166:169], v[24:27]
	v_mfma_f32_16x16x32_bf16 v[20:23], v[200:203], v[176:179], v[20:23]
	v_mfma_f32_16x16x32_bf16 v[16:19], v[208:211], v[176:179], v[16:19]
	v_mfma_f32_16x16x32_bf16 v[12:15], v[200:203], v[184:187], v[12:15]
	v_mfma_f32_16x16x32_bf16 v[8:11], v[208:211], v[184:187], v[8:11]
	v_mfma_f32_16x16x32_bf16 v[4:7], v[200:203], v[192:195], v[4:7]
	v_mfma_f32_16x16x32_bf16 v[0:3], v[208:211], v[192:195], v[0:3]
	s_add_i32 s74, s74, 2
	s_add_i32 s75, s75, 0x8000
	s_cmpk_lt_u32 s74, 0x54
	s_barrier
	s_cbranch_scc1 .LBB0_231
	s_mov_b32 m0, s48
	s_add_i32 s26, s70, 0x15c000
	ds_read_b128 v[130:133], v138
	ds_read_b128 v[146:149], v138 offset:1024
	ds_read_b128 v[150:153], v138 offset:2048
	ds_read_b128 v[154:157], v138 offset:3072
	ds_read_b128 v[162:165], v139
	ds_read_b128 v[166:169], v139 offset:1024
	ds_read_b128 v[170:173], v140
	ds_read_b128 v[176:179], v140 offset:1024
	ds_read_b128 v[180:183], v141
	ds_read_b128 v[184:187], v141 offset:1024
	ds_read_b128 v[188:191], v142
	ds_read_b128 v[192:195], v142 offset:1024
	buffer_load_dwordx4 v134, s[0:3], s26 offen lds
	s_add_i32 s70, s70, 0x15e000
	s_mov_b32 m0, s49
	s_nop 0
	buffer_load_dwordx4 v134, s[0:3], s70 offen lds
	s_waitcnt vmcnt(10)
	s_barrier
	s_waitcnt lgkmcnt(7)
	v_mfma_f32_16x16x32_bf16 v[124:127], v[130:133], v[162:165], v[124:127]
	s_waitcnt lgkmcnt(5)
	v_mfma_f32_16x16x32_bf16 v[116:119], v[130:133], v[170:173], v[116:119]
	v_mfma_f32_16x16x32_bf16 v[112:115], v[150:153], v[170:173], v[112:115]
	s_waitcnt lgkmcnt(1)
	v_mfma_f32_16x16x32_bf16 v[100:103], v[130:133], v[188:191], v[100:103]
	v_mfma_f32_16x16x32_bf16 v[96:99], v[150:153], v[188:191], v[96:99]
	v_mfma_f32_16x16x32_bf16 v[124:127], v[146:149], v[166:169], v[124:127]
	v_mfma_f32_16x16x32_bf16 v[120:123], v[150:153], v[162:165], v[120:123]
	v_mfma_f32_16x16x32_bf16 v[116:119], v[146:149], v[176:179], v[116:119]
	v_mfma_f32_16x16x32_bf16 v[112:115], v[154:157], v[176:179], v[112:115]
	v_mfma_f32_16x16x32_bf16 v[108:111], v[130:133], v[180:183], v[108:111]
	v_mfma_f32_16x16x32_bf16 v[104:107], v[150:153], v[180:183], v[104:107]
	s_waitcnt lgkmcnt(0)
	v_mfma_f32_16x16x32_bf16 v[100:103], v[146:149], v[192:195], v[100:103]
	v_mfma_f32_16x16x32_bf16 v[96:99], v[154:157], v[192:195], v[96:99]
	v_mfma_f32_16x16x32_bf16 v[196:199], v[154:157], v[166:169], v[120:123]
	v_mfma_f32_16x16x32_bf16 v[200:203], v[146:149], v[184:187], v[108:111]
	v_mfma_f32_16x16x32_bf16 v[204:207], v[154:157], v[184:187], v[104:107]
	s_barrier
	s_nop 0
	ds_read_b128 v[104:107], v143
	ds_read_b128 v[108:111], v143 offset:1024
	ds_read_b128 v[120:123], v143 offset:2048
	ds_read_b128 v[208:211], v143 offset:3072
	s_waitcnt vmcnt(8)
	s_barrier
	s_waitcnt lgkmcnt(3)
	v_mfma_f32_16x16x32_bf16 v[84:87], v[104:107], v[170:173], v[84:87]
	s_waitcnt lgkmcnt(1)
	v_mfma_f32_16x16x32_bf16 v[80:83], v[120:123], v[170:173], v[80:83]
	v_mfma_f32_16x16x32_bf16 v[68:71], v[104:107], v[188:191], v[68:71]
	v_mfma_f32_16x16x32_bf16 v[92:95], v[104:107], v[162:165], v[92:95]
	v_mfma_f32_16x16x32_bf16 v[88:91], v[120:123], v[162:165], v[88:91]
	v_mfma_f32_16x16x32_bf16 v[84:87], v[108:111], v[176:179], v[84:87]
	s_waitcnt lgkmcnt(0)
	v_mfma_f32_16x16x32_bf16 v[80:83], v[208:211], v[176:179], v[80:83]
	v_mfma_f32_16x16x32_bf16 v[76:79], v[104:107], v[180:183], v[76:79]
	v_mfma_f32_16x16x32_bf16 v[72:75], v[120:123], v[180:183], v[72:75]
	v_mfma_f32_16x16x32_bf16 v[68:71], v[108:111], v[192:195], v[68:71]
	v_mfma_f32_16x16x32_bf16 v[64:67], v[120:123], v[188:191], v[64:67]
	v_mfma_f32_16x16x32_bf16 v[212:215], v[108:111], v[166:169], v[92:95]
	v_mfma_f32_16x16x32_bf16 v[162:165], v[208:211], v[166:169], v[88:91]
	v_mfma_f32_16x16x32_bf16 v[166:169], v[108:111], v[184:187], v[76:79]
	v_mfma_f32_16x16x32_bf16 v[170:173], v[208:211], v[184:187], v[72:75]
	v_mfma_f32_16x16x32_bf16 v[176:179], v[208:211], v[192:195], v[64:67]
	s_barrier
; #define LDA(dst, b, h)                                                                                               \
;   _Pragma("unroll") for (int m = 0; m < 4; ++m) _Pragma("unroll") for (int k = 0; k < 2; ++k) dst[m][k] =            \
;       *reinterpret_cast<const bf16x8*>(SA(b, h) + lds_byte(wr * 64 + m * 16 + fr, k * 32 + fq * 8))
; #define LDB(dst, b, h)                                                                                               \
;   _Pragma("unroll") for (int n = 0; n < 2; ++n) _Pragma("unroll") for (int k = 0; k < 2; ++k) dst[n][k] =            \
;       *reinterpret_cast<const bf16x8*>(SB(b, h) + lds_byte(wc * 32 + n * 16 + fr, k * 32 + fq * 8))
; #define WAIT_V(n) asm volatile("s_waitcnt vmcnt(" #n ")" ::: "memory")
; #define WAIT_L(n) asm volatile("s_waitcnt lgkmcnt(" #n ")" ::: "memory")
; #define BAR __builtin_amdgcn_s_barrier()
; template <int EPI>
; __device__ __forceinline__ void gemm_phase(const u16* __restrict__ A, const u16* __restrict__ Bt, const int K,
;                                            const int nN, char* shm, const EpiArgs& ea) {
;     ...
;       LDA(At, 0, 1); WAIT_V(4); BAR; WAIT_L(0); MMA(1, 0, At, B0); MMA(1, 1, At, B1); BAR;
;     }
;     {
;       LDB(B0, 1, 0); LDA(At, 1, 0); WAIT_V(2); BAR; WAIT_L(0); MMA(0, 0, At, B0); BAR;
	s_nop 0
	ds_read_b128 v[64:67], v139 offset:16384
	ds_read_b128 v[72:75], v139 offset:17408
	ds_read_b128 v[76:79], v140 offset:16384
	ds_read_b128 v[88:91], v140 offset:17408
	ds_read_b128 v[92:95], v141 offset:16384
	ds_read_b128 v[180:183], v141 offset:17408
	ds_read_b128 v[184:187], v142 offset:16384
	ds_read_b128 v[188:191], v142 offset:17408
	s_waitcnt vmcnt(4)
	s_barrier
	s_waitcnt lgkmcnt(7)
	v_mfma_f32_16x16x32_bf16 v[60:63], v[130:133], v[64:67], v[60:63]
	s_waitcnt lgkmcnt(5)
	v_mfma_f32_16x16x32_bf16 v[52:55], v[130:133], v[76:79], v[52:55]
	v_mfma_f32_16x16x32_bf16 v[48:51], v[150:153], v[76:79], v[48:51]
	s_waitcnt lgkmcnt(1)
	v_mfma_f32_16x16x32_bf16 v[36:39], v[130:133], v[184:187], v[36:39]
	v_mfma_f32_16x16x32_bf16 v[32:35], v[150:153], v[184:187], v[32:35]
	v_mfma_f32_16x16x32_bf16 v[60:63], v[146:149], v[72:75], v[60:63]
	v_mfma_f32_16x16x32_bf16 v[56:59], v[150:153], v[64:67], v[56:59]
	v_mfma_f32_16x16x32_bf16 v[52:55], v[146:149], v[88:91], v[52:55]
	v_mfma_f32_16x16x32_bf16 v[48:51], v[154:157], v[88:91], v[48:51]
	v_mfma_f32_16x16x32_bf16 v[44:47], v[130:133], v[92:95], v[44:47]
	v_mfma_f32_16x16x32_bf16 v[40:43], v[150:153], v[92:95], v[40:43]
	s_waitcnt lgkmcnt(0)
	v_mfma_f32_16x16x32_bf16 v[36:39], v[146:149], v[188:191], v[36:39]
	v_mfma_f32_16x16x32_bf16 v[32:35], v[154:157], v[188:191], v[32:35]
	v_mfma_f32_16x16x32_bf16 v[192:195], v[154:157], v[72:75], v[56:59]
	v_mfma_f32_16x16x32_bf16 v[216:219], v[146:149], v[180:183], v[44:47]
	v_mfma_f32_16x16x32_bf16 v[220:223], v[154:157], v[180:183], v[40:43]
	v_mfma_f32_16x16x32_bf16 v[20:23], v[104:107], v[76:79], v[20:23]
	v_mfma_f32_16x16x32_bf16 v[16:19], v[120:123], v[76:79], v[16:19]
	v_mfma_f32_16x16x32_bf16 v[4:7], v[104:107], v[184:187], v[4:7]
	v_mfma_f32_16x16x32_bf16 v[28:31], v[104:107], v[64:67], v[28:31]
	v_mfma_f32_16x16x32_bf16 v[24:27], v[120:123], v[64:67], v[24:27]
	v_mfma_f32_16x16x32_bf16 v[20:23], v[108:111], v[88:91], v[20:23]
	v_mfma_f32_16x16x32_bf16 v[16:19], v[208:211], v[88:91], v[16:19]
	v_mfma_f32_16x16x32_bf16 v[12:15], v[104:107], v[92:95], v[12:15]
	v_mfma_f32_16x16x32_bf16 v[8:11], v[120:123], v[92:95], v[8:11]
	v_mfma_f32_16x16x32_bf16 v[4:7], v[108:111], v[188:191], v[4:7]
	v_mfma_f32_16x16x32_bf16 v[0:3], v[120:123], v[184:187], v[0:3]
	v_mfma_f32_16x16x32_bf16 v[130:133], v[108:111], v[72:75], v[28:31]
	v_mfma_f32_16x16x32_bf16 v[146:149], v[208:211], v[72:75], v[24:27]
	v_mfma_f32_16x16x32_bf16 v[150:153], v[108:111], v[180:183], v[12:15]
	v_mfma_f32_16x16x32_bf16 v[154:157], v[208:211], v[180:183], v[8:11]
	v_mfma_f32_16x16x32_bf16 v[180:183], v[208:211], v[188:191], v[0:3]
	s_barrier
	s_nop 0
	ds_read_b128 v[0:3], v144
	ds_read_b128 v[8:11], v144 offset:1024
	ds_read_b128 v[12:15], v144 offset:2048
	ds_read_b128 v[184:187], v144 offset:3072
	ds_read_b128 v[24:27], v139 offset:32768
	ds_read_b128 v[28:31], v139 offset:33792
	ds_read_b128 v[40:43], v140 offset:32768
	ds_read_b128 v[44:47], v140 offset:33792
	ds_read_b128 v[56:59], v141 offset:32768
	ds_read_b128 v[64:67], v141 offset:33792
	ds_read_b128 v[188:191], v142 offset:32768
	ds_read_b128 v[208:211], v142 offset:33792
	s_waitcnt vmcnt(2)
	s_barrier
	s_waitcnt lgkmcnt(7)
	v_mfma_f32_16x16x32_bf16 v[72:75], v[0:3], v[24:27], v[124:127]
	s_waitcnt lgkmcnt(6)
	v_mfma_f32_16x16x32_bf16 v[120:123], v[8:11], v[28:31], v[72:75]
	v_mfma_f32_16x16x32_bf16 v[72:75], v[12:15], v[24:27], v[196:199]
	v_mfma_f32_16x16x32_bf16 v[124:127], v[184:187], v[28:31], v[72:75]
	s_waitcnt lgkmcnt(5)
	v_mfma_f32_16x16x32_bf16 v[72:75], v[0:3], v[40:43], v[116:119]
	s_waitcnt lgkmcnt(4)
	v_mfma_f32_16x16x32_bf16 v[104:107], v[8:11], v[44:47], v[72:75]
	v_mfma_f32_16x16x32_bf16 v[72:75], v[12:15], v[40:43], v[112:115]
	v_mfma_f32_16x16x32_bf16 v[108:111], v[184:187], v[44:47], v[72:75]
	s_waitcnt lgkmcnt(3)
	v_mfma_f32_16x16x32_bf16 v[72:75], v[0:3], v[56:59], v[200:203]
	s_waitcnt lgkmcnt(2)
	v_mfma_f32_16x16x32_bf16 v[88:91], v[8:11], v[64:67], v[72:75]
	v_mfma_f32_16x16x32_bf16 v[72:75], v[12:15], v[56:59], v[204:207]
	v_mfma_f32_16x16x32_bf16 v[92:95], v[184:187], v[64:67], v[72:75]
	s_waitcnt lgkmcnt(1)
	v_mfma_f32_16x16x32_bf16 v[72:75], v[0:3], v[188:191], v[100:103]
	v_mfma_f32_16x16x32_bf16 v[76:79], v[12:15], v[188:191], v[96:99]
	s_waitcnt lgkmcnt(0)
	v_mfma_f32_16x16x32_bf16 v[72:75], v[8:11], v[208:211], v[72:75]
	v_mfma_f32_16x16x32_bf16 v[76:79], v[184:187], v[208:211], v[76:79]
	s_barrier
; #define LDA(dst, b, h)                                                                                               \
;   _Pragma("unroll") for (int m = 0; m < 4; ++m) _Pragma("unroll") for (int k = 0; k < 2; ++k) dst[m][k] =            \
;       *reinterpret_cast<const bf16x8*>(SA(b, h) + lds_byte(wr * 64 + m * 16 + fr, k * 32 + fq * 8))
; #define LDB(dst, b, h)                                                                                               \
;   _Pragma("unroll") for (int n = 0; n < 2; ++n) _Pragma("unroll") for (int k = 0; k < 2; ++k) dst[n][k] =            \
;       *reinterpret_cast<const bf16x8*>(SB(b, h) + lds_byte(wc * 32 + n * 16 + fr, k * 32 + fq * 8))
; #define WAIT_V(n) asm volatile("s_waitcnt vmcnt(" #n ")" ::: "memory")
; #define WAIT_L(n) asm volatile("s_waitcnt lgkmcnt(" #n ")" ::: "memory")
; #define BAR __builtin_amdgcn_s_barrier()
; template <int EPI>
; __device__ __forceinline__ void gemm_phase(const u16* __restrict__ A, const u16* __restrict__ Bt, const int K,
;                                            const int nN, char* shm, const EpiArgs& ea) {
;     ...
;       LDB(B0, 1, 0); LDA(At, 1, 0); WAIT_V(2); BAR; WAIT_L(0); MMA(0, 0, At, B0); BAR;
;       LDB(B1, 1, 1); WAIT_V(0); BAR; WAIT_L(0); MMA(0, 1, At, B1); BAR;
;       LDA(At, 1, 1); BAR; WAIT_L(0); MMA(1, 0, At, B0); MMA(1, 1, At, B1); BAR;
;     }
;     if (wr == 0) BAR;
	ds_read_b128 v[196:199], v145
	ds_read_b128 v[200:203], v145 offset:1024
	ds_read_b128 v[204:207], v145 offset:2048
	ds_read_b128 v[224:227], v145 offset:3072
	s_waitcnt vmcnt(0)
	s_barrier
	s_waitcnt lgkmcnt(3)
	v_mfma_f32_16x16x32_bf16 v[96:99], v[196:199], v[24:27], v[212:215]
	s_waitcnt lgkmcnt(1)
	v_mfma_f32_16x16x32_bf16 v[24:27], v[204:207], v[24:27], v[162:165]
	s_waitcnt lgkmcnt(0)
	v_mfma_f32_16x16x32_bf16 v[116:119], v[224:227], v[28:31], v[24:27]
	v_mfma_f32_16x16x32_bf16 v[24:27], v[196:199], v[40:43], v[84:87]
	v_mfma_f32_16x16x32_bf16 v[112:115], v[200:203], v[28:31], v[96:99]
	v_mfma_f32_16x16x32_bf16 v[96:99], v[200:203], v[44:47], v[24:27]
	v_mfma_f32_16x16x32_bf16 v[24:27], v[204:207], v[40:43], v[80:83]
	v_mfma_f32_16x16x32_bf16 v[100:103], v[224:227], v[44:47], v[24:27]
	v_mfma_f32_16x16x32_bf16 v[24:27], v[196:199], v[56:59], v[166:169]
	v_mfma_f32_16x16x32_bf16 v[80:83], v[200:203], v[64:67], v[24:27]
	v_mfma_f32_16x16x32_bf16 v[24:27], v[204:207], v[56:59], v[170:173]
	v_mfma_f32_16x16x32_bf16 v[84:87], v[224:227], v[64:67], v[24:27]
	v_mfma_f32_16x16x32_bf16 v[24:27], v[196:199], v[188:191], v[68:71]
	v_mfma_f32_16x16x32_bf16 v[64:67], v[200:203], v[208:211], v[24:27]
	v_mfma_f32_16x16x32_bf16 v[24:27], v[204:207], v[188:191], v[176:179]
	v_mfma_f32_16x16x32_bf16 v[68:71], v[224:227], v[208:211], v[24:27]
	s_barrier
	ds_read_b128 v[162:165], v139 offset:49152
	ds_read_b128 v[166:169], v139 offset:50176
	ds_read_b128 v[170:173], v140 offset:49152
	ds_read_b128 v[176:179], v140 offset:50176
	ds_read_b128 v[188:191], v141 offset:49152
	ds_read_b128 v[208:211], v141 offset:50176
	ds_read_b128 v[212:215], v142 offset:49152
	ds_read_b128 v[228:231], v142 offset:50176
	s_barrier
	s_waitcnt lgkmcnt(7)
	v_mfma_f32_16x16x32_bf16 v[24:27], v[0:3], v[162:165], v[60:63]
	s_waitcnt lgkmcnt(6)
	v_mfma_f32_16x16x32_bf16 v[56:59], v[8:11], v[166:169], v[24:27]
	v_mfma_f32_16x16x32_bf16 v[24:27], v[12:15], v[162:165], v[192:195]
	v_mfma_f32_16x16x32_bf16 v[60:63], v[184:187], v[166:169], v[24:27]
	s_waitcnt lgkmcnt(5)
	v_mfma_f32_16x16x32_bf16 v[24:27], v[0:3], v[170:173], v[52:55]
	s_waitcnt lgkmcnt(4)
	v_mfma_f32_16x16x32_bf16 v[40:43], v[8:11], v[176:179], v[24:27]
	v_mfma_f32_16x16x32_bf16 v[24:27], v[12:15], v[170:173], v[48:51]
	v_mfma_f32_16x16x32_bf16 v[44:47], v[184:187], v[176:179], v[24:27]
	s_waitcnt lgkmcnt(3)
	v_mfma_f32_16x16x32_bf16 v[24:27], v[0:3], v[188:191], v[216:219]
	s_waitcnt lgkmcnt(1)
	v_mfma_f32_16x16x32_bf16 v[0:3], v[0:3], v[212:215], v[36:39]
	v_mfma_f32_16x16x32_bf16 v[24:27], v[8:11], v[208:211], v[24:27]
	v_mfma_f32_16x16x32_bf16 v[28:31], v[12:15], v[188:191], v[220:223]
	s_waitcnt lgkmcnt(0)
	v_mfma_f32_16x16x32_bf16 v[8:11], v[8:11], v[228:231], v[0:3]
	v_mfma_f32_16x16x32_bf16 v[0:3], v[12:15], v[212:215], v[32:35]
	v_mfma_f32_16x16x32_bf16 v[28:31], v[184:187], v[208:211], v[28:31]
	v_mfma_f32_16x16x32_bf16 v[12:15], v[184:187], v[228:231], v[0:3]
	v_mfma_f32_16x16x32_bf16 v[0:3], v[196:199], v[162:165], v[130:133]
	v_mfma_f32_16x16x32_bf16 v[48:51], v[200:203], v[166:169], v[0:3]
	v_mfma_f32_16x16x32_bf16 v[0:3], v[204:207], v[162:165], v[146:149]
	v_mfma_f32_16x16x32_bf16 v[52:55], v[224:227], v[166:169], v[0:3]
	v_mfma_f32_16x16x32_bf16 v[0:3], v[196:199], v[170:173], v[20:23]
	v_mfma_f32_16x16x32_bf16 v[32:35], v[200:203], v[176:179], v[0:3]
	v_mfma_f32_16x16x32_bf16 v[0:3], v[204:207], v[170:173], v[16:19]
	v_mfma_f32_16x16x32_bf16 v[36:39], v[224:227], v[176:179], v[0:3]
	v_mfma_f32_16x16x32_bf16 v[0:3], v[196:199], v[188:191], v[150:153]
	v_mfma_f32_16x16x32_bf16 v[16:19], v[200:203], v[208:211], v[0:3]
	v_mfma_f32_16x16x32_bf16 v[0:3], v[204:207], v[188:191], v[154:157]
	v_mfma_f32_16x16x32_bf16 v[20:23], v[224:227], v[208:211], v[0:3]
	v_mfma_f32_16x16x32_bf16 v[0:3], v[196:199], v[212:215], v[4:7]
	v_mfma_f32_16x16x32_bf16 v[4:7], v[204:207], v[212:215], v[180:183]
	v_mfma_f32_16x16x32_bf16 v[0:3], v[200:203], v[228:231], v[0:3]
	v_mfma_f32_16x16x32_bf16 v[4:7], v[224:227], v[228:231], v[4:7]
	s_andn2_b64 vcc, exec, s[30:31]
	s_barrier
	s_cbranch_vccnz .LBB0_234
	s_barrier

; #define LDA(dst, b, h)                                                                                               \
;   _Pragma("unroll") for (int m = 0; m < 4; ++m) _Pragma("unroll") for (int k = 0; k < 2; ++k) dst[m][k] =            \
;       *reinterpret_cast<const bf16x8*>(SA(b, h) + lds_byte(wr * 64 + m * 16 + fr, k * 32 + fq * 8))
; #define LDB(dst, b, h)                                                                                               \
;   _Pragma("unroll") for (int n = 0; n < 2; ++n) _Pragma("unroll") for (int k = 0; k < 2; ++k) dst[n][k] =            \
;       *reinterpret_cast<const bf16x8*>(SB(b, h) + lds_byte(wc * 32 + n * 16 + fr, k * 32 + fq * 8))
; #define WAIT_V(n) asm volatile("s_waitcnt vmcnt(" #n ")" ::: "memory")
; #define WAIT_L(n) asm volatile("s_waitcnt lgkmcnt(" #n ")" ::: "memory")
; #define BAR __builtin_amdgcn_s_barrier()
; #define SCHED __builtin_amdgcn_sched_barrier(0)
; template <int EPI>
; __device__ __forceinline__ void gemm_phase(const u16* __restrict__ A, const u16* __restrict__ Bt, const int K,
;                                            const int nN, char* shm, const EpiArgs& ea) {
;     ...
;     for (int t = 0; t < nt - 2; t += 2) {
;       LDB(B0, 0, 0); SCHED; LDA(At, 0, 0); STAGE(SA(1, 1), rA, brow + HALF, t + 1);
;       WAIT_V(10); WAIT_L(8); BAR; WAIT_L(0); MMA(0, 0, At, B0); BAR; SCHED;
;       LDB(B1, 0, 1); STAGE(SB(0, 0), rB, bcol, t + 2);
;       WAIT_V(10); BAR; WAIT_L(0); MMA(0, 1, At, B1); BAR;
;       LDA(At, 0, 1); STAGE(SA(0, 0), rA, brow, t + 2);
;       BAR; WAIT_L(0); MMA(1, 0, At, B0); BAR; SCHED;
;       STAGE(SB(0, 1), rB, bcol + HALF, t + 2);
;       WAIT_V(10); BAR; MMA(1, 1, At, B1); BAR;
.LBB0_306:
	ds_read_b128 v[128:131], v168
	ds_read_b128 v[132:135], v168 offset:1024
	ds_read_b128 v[136:139], v168 offset:2048
	ds_read_b128 v[140:143], v168 offset:3072
	s_add_i32 s79, s72, s78
	s_mov_b32 m0, s52
	s_add_i32 s26, s79, 0x4000
	ds_read_b128 v[144:147], v169
	ds_read_b128 v[148:151], v169 offset:1024
	ds_read_b128 v[152:155], v170
	ds_read_b128 v[156:159], v170 offset:1024
	ds_read_b128 v[180:183], v171
	ds_read_b128 v[184:187], v171 offset:1024
	ds_read_b128 v[188:191], v172
	ds_read_b128 v[192:195], v172 offset:1024
	buffer_load_dwordx4 v161, s[0:3], s26 offen lds
	s_add_i32 s26, s79, 0x6000
	s_mov_b32 m0, s53
	s_nop 0
	buffer_load_dwordx4 v161, s[0:3], s26 offen lds
	s_waitcnt vmcnt(10)
	s_waitcnt lgkmcnt(8)
	s_barrier
	s_waitcnt lgkmcnt(7)
	v_mfma_f32_16x16x32_bf16 v[124:127], v[128:131], v[144:147], v[124:127]
	v_mfma_f32_16x16x32_bf16 v[120:123], v[136:139], v[144:147], v[120:123]
	s_waitcnt lgkmcnt(5)
	v_mfma_f32_16x16x32_bf16 v[116:119], v[128:131], v[152:155], v[116:119]
	v_mfma_f32_16x16x32_bf16 v[112:115], v[136:139], v[152:155], v[112:115]
	s_waitcnt lgkmcnt(3)
	v_mfma_f32_16x16x32_bf16 v[108:111], v[128:131], v[180:183], v[108:111]
	v_mfma_f32_16x16x32_bf16 v[104:107], v[136:139], v[180:183], v[104:107]
	s_waitcnt lgkmcnt(1)
	v_mfma_f32_16x16x32_bf16 v[100:103], v[128:131], v[188:191], v[100:103]
	v_mfma_f32_16x16x32_bf16 v[96:99], v[136:139], v[188:191], v[96:99]
	v_mfma_f32_16x16x32_bf16 v[124:127], v[132:135], v[148:151], v[124:127]
	v_mfma_f32_16x16x32_bf16 v[120:123], v[140:143], v[148:151], v[120:123]
	v_mfma_f32_16x16x32_bf16 v[116:119], v[132:135], v[156:159], v[116:119]
	v_mfma_f32_16x16x32_bf16 v[112:115], v[140:143], v[156:159], v[112:115]
	v_mfma_f32_16x16x32_bf16 v[108:111], v[132:135], v[184:187], v[108:111]
	v_mfma_f32_16x16x32_bf16 v[104:107], v[140:143], v[184:187], v[104:107]
	s_waitcnt lgkmcnt(0)
	v_mfma_f32_16x16x32_bf16 v[100:103], v[132:135], v[192:195], v[100:103]
	v_mfma_f32_16x16x32_bf16 v[96:99], v[140:143], v[192:195], v[96:99]
	s_barrier
	s_add_i32 s80, s74, s78
	s_mov_b32 m0, s54
	s_add_i32 s81, s80, 0x8000
	s_mov_b32 s26, s2
	s_mov_b32 s27, s3
	ds_read_b128 v[196:199], v173
	ds_read_b128 v[200:203], v173 offset:1024
	ds_read_b128 v[204:207], v173 offset:2048
	ds_read_b128 v[208:211], v173 offset:3072
	buffer_load_dwordx4 v161, s[24:27], s81 offen lds
	s_add_i32 s81, s80, 0xa000
	s_mov_b32 m0, s55
	s_nop 0
	buffer_load_dwordx4 v161, s[24:27], s81 offen lds
	s_waitcnt vmcnt(10)
	s_barrier
	s_waitcnt lgkmcnt(3)
	v_mfma_f32_16x16x32_bf16 v[92:95], v[196:199], v[144:147], v[92:95]
	s_waitcnt lgkmcnt(1)
	v_mfma_f32_16x16x32_bf16 v[88:91], v[204:207], v[144:147], v[88:91]
	v_mfma_f32_16x16x32_bf16 v[84:87], v[196:199], v[152:155], v[84:87]
	v_mfma_f32_16x16x32_bf16 v[80:83], v[204:207], v[152:155], v[80:83]
	v_mfma_f32_16x16x32_bf16 v[76:79], v[196:199], v[180:183], v[76:79]
	v_mfma_f32_16x16x32_bf16 v[72:75], v[204:207], v[180:183], v[72:75]
	v_mfma_f32_16x16x32_bf16 v[68:71], v[196:199], v[188:191], v[68:71]
	v_mfma_f32_16x16x32_bf16 v[64:67], v[204:207], v[188:191], v[64:67]
	v_mfma_f32_16x16x32_bf16 v[92:95], v[200:203], v[148:151], v[92:95]
	s_waitcnt lgkmcnt(0)
	v_mfma_f32_16x16x32_bf16 v[88:91], v[208:211], v[148:151], v[88:91]
	v_mfma_f32_16x16x32_bf16 v[84:87], v[200:203], v[156:159], v[84:87]
	v_mfma_f32_16x16x32_bf16 v[80:83], v[208:211], v[156:159], v[80:83]
	v_mfma_f32_16x16x32_bf16 v[76:79], v[200:203], v[184:187], v[76:79]
	v_mfma_f32_16x16x32_bf16 v[72:75], v[208:211], v[184:187], v[72:75]
	v_mfma_f32_16x16x32_bf16 v[68:71], v[200:203], v[192:195], v[68:71]
	v_mfma_f32_16x16x32_bf16 v[64:67], v[208:211], v[192:195], v[64:67]
	s_add_i32 s81, s73, s78
	s_mov_b32 m0, s49
	s_add_i32 s82, s81, 0x8000
	s_barrier
	ds_read_b128 v[144:147], v169 offset:16384
	ds_read_b128 v[148:151], v169 offset:17408
	ds_read_b128 v[152:155], v170 offset:16384
	ds_read_b128 v[156:159], v170 offset:17408
	ds_read_b128 v[180:183], v171 offset:16384
	ds_read_b128 v[184:187], v171 offset:17408
	ds_read_b128 v[188:191], v172 offset:16384
	ds_read_b128 v[192:195], v172 offset:17408
	buffer_load_dwordx4 v161, s[0:3], s82 offen lds
	s_add_i32 s82, s81, 0xa000
	s_mov_b32 m0, s56
	s_nop 0
	buffer_load_dwordx4 v161, s[0:3], s82 offen lds
	s_barrier
	s_waitcnt lgkmcnt(7)
	v_mfma_f32_16x16x32_bf16 v[60:63], v[128:131], v[144:147], v[60:63]
	v_mfma_f32_16x16x32_bf16 v[56:59], v[136:139], v[144:147], v[56:59]
	s_waitcnt lgkmcnt(5)
	v_mfma_f32_16x16x32_bf16 v[52:55], v[128:131], v[152:155], v[52:55]
	v_mfma_f32_16x16x32_bf16 v[48:51], v[136:139], v[152:155], v[48:51]
	s_waitcnt lgkmcnt(3)
	v_mfma_f32_16x16x32_bf16 v[44:47], v[128:131], v[180:183], v[44:47]
	v_mfma_f32_16x16x32_bf16 v[40:43], v[136:139], v[180:183], v[40:43]
	s_waitcnt lgkmcnt(1)
	v_mfma_f32_16x16x32_bf16 v[36:39], v[128:131], v[188:191], v[36:39]
	v_mfma_f32_16x16x32_bf16 v[32:35], v[136:139], v[188:191], v[32:35]
	v_mfma_f32_16x16x32_bf16 v[60:63], v[132:135], v[148:151], v[60:63]
	v_mfma_f32_16x16x32_bf16 v[56:59], v[140:143], v[148:151], v[56:59]
	v_mfma_f32_16x16x32_bf16 v[52:55], v[132:135], v[156:159], v[52:55]
	v_mfma_f32_16x16x32_bf16 v[48:51], v[140:143], v[156:159], v[48:51]
	v_mfma_f32_16x16x32_bf16 v[44:47], v[132:135], v[184:187], v[44:47]
	v_mfma_f32_16x16x32_bf16 v[40:43], v[140:143], v[184:187], v[40:43]
	s_waitcnt lgkmcnt(0)
	v_mfma_f32_16x16x32_bf16 v[36:39], v[132:135], v[192:195], v[36:39]
	v_mfma_f32_16x16x32_bf16 v[32:35], v[140:143], v[192:195], v[32:35]
	s_barrier
	s_add_i32 s82, s43, s78
	s_mov_b32 m0, s57
	s_add_i32 s83, s82, 0x8000
	buffer_load_dwordx4 v161, s[24:27], s83 offen lds
	s_add_i32 s83, s82, 0xa000
	s_mov_b32 m0, s58
	s_nop 0
	buffer_load_dwordx4 v161, s[24:27], s83 offen lds
	s_waitcnt vmcnt(10)
	s_barrier
; #define LDA(dst, b, h)                                                                                               \
;   _Pragma("unroll") for (int m = 0; m < 4; ++m) _Pragma("unroll") for (int k = 0; k < 2; ++k) dst[m][k] =            \
;       *reinterpret_cast<const bf16x8*>(SA(b, h) + lds_byte(wr * 64 + m * 16 + fr, k * 32 + fq * 8))
; #define LDB(dst, b, h)                                                                                               \
;   _Pragma("unroll") for (int n = 0; n < 2; ++n) _Pragma("unroll") for (int k = 0; k < 2; ++k) dst[n][k] =            \
;       *reinterpret_cast<const bf16x8*>(SB(b, h) + lds_byte(wc * 32 + n * 16 + fr, k * 32 + fq * 8))
; #define WAIT_V(n) asm volatile("s_waitcnt vmcnt(" #n ")" ::: "memory")
; #define WAIT_L(n) asm volatile("s_waitcnt lgkmcnt(" #n ")" ::: "memory")
; #define BAR __builtin_amdgcn_s_barrier()
; #define SCHED __builtin_amdgcn_sched_barrier(0)
; template <int EPI>
; __device__ __forceinline__ void gemm_phase(const u16* __restrict__ A, const u16* __restrict__ Bt, const int K,
;                                            const int nN, char* shm, const EpiArgs& ea) {
;     ...
;       WAIT_V(10); BAR; MMA(1, 1, At, B1); BAR;
;       LDB(B0, 1, 0); SCHED; LDA(At, 1, 0); STAGE(SA(0, 1), rA, brow + HALF, t + 2);
;       WAIT_V(10); WAIT_L(8); BAR; WAIT_L(0); MMA(0, 0, At, B0); BAR; SCHED;
;       LDB(B1, 1, 1); STAGE(SB(1, 0), rB, bcol, t + 3);
;       WAIT_V(10); BAR; WAIT_L(0); MMA(0, 1, At, B1); BAR;
	v_mfma_f32_16x16x32_bf16 v[28:31], v[196:199], v[144:147], v[28:31]
	v_mfma_f32_16x16x32_bf16 v[24:27], v[204:207], v[144:147], v[24:27]
	v_mfma_f32_16x16x32_bf16 v[20:23], v[196:199], v[152:155], v[20:23]
	v_mfma_f32_16x16x32_bf16 v[16:19], v[204:207], v[152:155], v[16:19]
	v_mfma_f32_16x16x32_bf16 v[12:15], v[196:199], v[180:183], v[12:15]
	v_mfma_f32_16x16x32_bf16 v[8:11], v[204:207], v[180:183], v[8:11]
	v_mfma_f32_16x16x32_bf16 v[4:7], v[196:199], v[188:191], v[4:7]
	v_mfma_f32_16x16x32_bf16 v[0:3], v[204:207], v[188:191], v[0:3]
	v_mfma_f32_16x16x32_bf16 v[28:31], v[200:203], v[148:151], v[28:31]
	v_mfma_f32_16x16x32_bf16 v[24:27], v[208:211], v[148:151], v[24:27]
	v_mfma_f32_16x16x32_bf16 v[20:23], v[200:203], v[156:159], v[20:23]
	v_mfma_f32_16x16x32_bf16 v[16:19], v[208:211], v[156:159], v[16:19]
	v_mfma_f32_16x16x32_bf16 v[12:15], v[200:203], v[184:187], v[12:15]
	v_mfma_f32_16x16x32_bf16 v[8:11], v[208:211], v[184:187], v[8:11]
	v_mfma_f32_16x16x32_bf16 v[4:7], v[200:203], v[192:195], v[4:7]
	v_mfma_f32_16x16x32_bf16 v[0:3], v[208:211], v[192:195], v[0:3]
	s_barrier
	ds_read_b128 v[128:131], v176
	ds_read_b128 v[132:135], v176 offset:1024
	ds_read_b128 v[136:139], v176 offset:2048
	ds_read_b128 v[140:143], v176 offset:3072
	s_mov_b32 m0, s59
	s_add_i32 s83, s79, 0x8000
	ds_read_b128 v[144:147], v169 offset:32768
	ds_read_b128 v[148:151], v169 offset:33792
	ds_read_b128 v[152:155], v170 offset:32768
	ds_read_b128 v[156:159], v170 offset:33792
	ds_read_b128 v[180:183], v171 offset:32768
	ds_read_b128 v[184:187], v171 offset:33792
	ds_read_b128 v[188:191], v172 offset:32768
	ds_read_b128 v[192:195], v172 offset:33792
	buffer_load_dwordx4 v161, s[0:3], s83 offen lds
	s_add_i32 s79, s79, 0xa000
	s_mov_b32 m0, s60
	s_nop 0
	buffer_load_dwordx4 v161, s[0:3], s79 offen lds
	s_waitcnt vmcnt(10)
	s_waitcnt lgkmcnt(8)
	s_barrier
	s_waitcnt lgkmcnt(7)
	v_mfma_f32_16x16x32_bf16 v[124:127], v[128:131], v[144:147], v[124:127]
	v_mfma_f32_16x16x32_bf16 v[120:123], v[136:139], v[144:147], v[120:123]
	s_waitcnt lgkmcnt(5)
	v_mfma_f32_16x16x32_bf16 v[116:119], v[128:131], v[152:155], v[116:119]
	v_mfma_f32_16x16x32_bf16 v[112:115], v[136:139], v[152:155], v[112:115]
	s_waitcnt lgkmcnt(3)
	v_mfma_f32_16x16x32_bf16 v[108:111], v[128:131], v[180:183], v[108:111]
	v_mfma_f32_16x16x32_bf16 v[104:107], v[136:139], v[180:183], v[104:107]
	s_waitcnt lgkmcnt(1)
	v_mfma_f32_16x16x32_bf16 v[100:103], v[128:131], v[188:191], v[100:103]
	v_mfma_f32_16x16x32_bf16 v[96:99], v[136:139], v[188:191], v[96:99]
	v_mfma_f32_16x16x32_bf16 v[124:127], v[132:135], v[148:151], v[124:127]
	v_mfma_f32_16x16x32_bf16 v[120:123], v[140:143], v[148:151], v[120:123]
	v_mfma_f32_16x16x32_bf16 v[116:119], v[132:135], v[156:159], v[116:119]
	v_mfma_f32_16x16x32_bf16 v[112:115], v[140:143], v[156:159], v[112:115]
	v_mfma_f32_16x16x32_bf16 v[108:111], v[132:135], v[184:187], v[108:111]
	v_mfma_f32_16x16x32_bf16 v[104:107], v[140:143], v[184:187], v[104:107]
	s_waitcnt lgkmcnt(0)
	v_mfma_f32_16x16x32_bf16 v[100:103], v[132:135], v[192:195], v[100:103]
	v_mfma_f32_16x16x32_bf16 v[96:99], v[140:143], v[192:195], v[96:99]
	s_barrier
	s_mov_b32 m0, s61
	s_add_i32 s79, s80, 0xc000
	ds_read_b128 v[196:199], v177
	ds_read_b128 v[200:203], v177 offset:1024
	ds_read_b128 v[204:207], v177 offset:2048
	ds_read_b128 v[208:211], v177 offset:3072
	buffer_load_dwordx4 v161, s[24:27], s79 offen lds
	s_add_i32 s80, s80, 0xe000
	s_mov_b32 m0, s62
	s_nop 0
	buffer_load_dwordx4 v161, s[24:27], s80 offen lds
	s_waitcnt vmcnt(10)
	s_barrier
	s_waitcnt lgkmcnt(3)
	v_mfma_f32_16x16x32_bf16 v[92:95], v[196:199], v[144:147], v[92:95]
	s_waitcnt lgkmcnt(1)
	v_mfma_f32_16x16x32_bf16 v[88:91], v[204:207], v[144:147], v[88:91]
	v_mfma_f32_16x16x32_bf16 v[84:87], v[196:199], v[152:155], v[84:87]
	v_mfma_f32_16x16x32_bf16 v[80:83], v[204:207], v[152:155], v[80:83]
	v_mfma_f32_16x16x32_bf16 v[76:79], v[196:199], v[180:183], v[76:79]
	v_mfma_f32_16x16x32_bf16 v[72:75], v[204:207], v[180:183], v[72:75]
	v_mfma_f32_16x16x32_bf16 v[68:71], v[196:199], v[188:191], v[68:71]
	v_mfma_f32_16x16x32_bf16 v[64:67], v[204:207], v[188:191], v[64:67]
	v_mfma_f32_16x16x32_bf16 v[92:95], v[200:203], v[148:151], v[92:95]
	s_waitcnt lgkmcnt(0)
	v_mfma_f32_16x16x32_bf16 v[88:91], v[208:211], v[148:151], v[88:91]
	v_mfma_f32_16x16x32_bf16 v[84:87], v[200:203], v[156:159], v[84:87]
	v_mfma_f32_16x16x32_bf16 v[80:83], v[208:211], v[156:159], v[80:83]
	v_mfma_f32_16x16x32_bf16 v[76:79], v[200:203], v[184:187], v[76:79]
	v_mfma_f32_16x16x32_bf16 v[72:75], v[208:211], v[184:187], v[72:75]
	v_mfma_f32_16x16x32_bf16 v[68:71], v[200:203], v[192:195], v[68:71]
	v_mfma_f32_16x16x32_bf16 v[64:67], v[208:211], v[192:195], v[64:67]
	s_mov_b32 m0, s63
	s_add_i32 s79, s81, 0xc000
	s_barrier
; #define LDA(dst, b, h)                                                                                               \
;   _Pragma("unroll") for (int m = 0; m < 4; ++m) _Pragma("unroll") for (int k = 0; k < 2; ++k) dst[m][k] =            \
;       *reinterpret_cast<const bf16x8*>(SA(b, h) + lds_byte(wr * 64 + m * 16 + fr, k * 32 + fq * 8))
; #define WAIT_V(n) asm volatile("s_waitcnt vmcnt(" #n ")" ::: "memory")
; #define WAIT_L(n) asm volatile("s_waitcnt lgkmcnt(" #n ")" ::: "memory")
; #define BAR __builtin_amdgcn_s_barrier()
; #define SCHED __builtin_amdgcn_sched_barrier(0)
; template <int EPI>
; __device__ __forceinline__ void gemm_phase(const u16* __restrict__ A, const u16* __restrict__ Bt, const int K,
;                                            const int nN, char* shm, const EpiArgs& ea) {
;     ...
;       LDA(At, 1, 1); STAGE(SA(1, 0), rA, brow, t + 3);
;       BAR; WAIT_L(0); MMA(1, 0, At, B0); BAR; SCHED;
;       STAGE(SB(1, 1), rB, bcol + HALF, t + 3);
;       WAIT_V(10); BAR; MMA(1, 1, At, B1); BAR;
;     }
;     float eC = 0.f, eB = 0.f;
;     float2 eS = make_float2(0.f, 0.f);
;     if (EPI == EPI_IN || EPI == EPI_SWIGLU_LN) {
;       if (wr == 0) {
;         eC = ea.c1[bcol + tid];
;         eS = *(const float2*)(ea.st_in + (size_t)(brow + tid) * 2);
;       } else {
;         eC = ea.c2[bcol + tid - 256];
;         if (EPI == EPI_IN) eB = ea.bias[bcol + tid - 256];
;       }
	ds_read_b128 v[144:147], v169 offset:49152
	ds_read_b128 v[148:151], v169 offset:50176
	ds_read_b128 v[152:155], v170 offset:49152
	ds_read_b128 v[156:159], v170 offset:50176
	ds_read_b128 v[180:183], v171 offset:49152
	ds_read_b128 v[184:187], v171 offset:50176
	ds_read_b128 v[188:191], v172 offset:49152
	ds_read_b128 v[192:195], v172 offset:50176
	buffer_load_dwordx4 v161, s[0:3], s79 offen lds
	s_add_i32 s81, s81, 0xe000
	s_mov_b32 m0, s64
	s_nop 0
	buffer_load_dwordx4 v161, s[0:3], s81 offen lds
	s_barrier
	s_waitcnt lgkmcnt(7)
	v_mfma_f32_16x16x32_bf16 v[60:63], v[128:131], v[144:147], v[60:63]
	v_mfma_f32_16x16x32_bf16 v[56:59], v[136:139], v[144:147], v[56:59]
	s_waitcnt lgkmcnt(5)
	v_mfma_f32_16x16x32_bf16 v[52:55], v[128:131], v[152:155], v[52:55]
	v_mfma_f32_16x16x32_bf16 v[48:51], v[136:139], v[152:155], v[48:51]
	s_waitcnt lgkmcnt(3)
	v_mfma_f32_16x16x32_bf16 v[44:47], v[128:131], v[180:183], v[44:47]
	v_mfma_f32_16x16x32_bf16 v[40:43], v[136:139], v[180:183], v[40:43]
	s_waitcnt lgkmcnt(1)
	v_mfma_f32_16x16x32_bf16 v[36:39], v[128:131], v[188:191], v[36:39]
	v_mfma_f32_16x16x32_bf16 v[32:35], v[136:139], v[188:191], v[32:35]
	v_mfma_f32_16x16x32_bf16 v[60:63], v[132:135], v[148:151], v[60:63]
	v_mfma_f32_16x16x32_bf16 v[56:59], v[140:143], v[148:151], v[56:59]
	v_mfma_f32_16x16x32_bf16 v[52:55], v[132:135], v[156:159], v[52:55]
	v_mfma_f32_16x16x32_bf16 v[48:51], v[140:143], v[156:159], v[48:51]
	v_mfma_f32_16x16x32_bf16 v[44:47], v[132:135], v[184:187], v[44:47]
	v_mfma_f32_16x16x32_bf16 v[40:43], v[140:143], v[184:187], v[40:43]
	s_waitcnt lgkmcnt(0)
	v_mfma_f32_16x16x32_bf16 v[36:39], v[132:135], v[192:195], v[36:39]
	v_mfma_f32_16x16x32_bf16 v[32:35], v[140:143], v[192:195], v[32:35]
	s_barrier
	s_mov_b32 m0, s65
	s_add_i32 s79, s82, 0xc000
	buffer_load_dwordx4 v161, s[24:27], s79 offen lds
	s_add_i32 s82, s82, 0xe000
	s_mov_b32 m0, s66
	s_nop 0
	buffer_load_dwordx4 v161, s[24:27], s82 offen lds
	s_waitcnt vmcnt(10)
	s_barrier
	v_mfma_f32_16x16x32_bf16 v[28:31], v[196:199], v[144:147], v[28:31]
	v_mfma_f32_16x16x32_bf16 v[24:27], v[204:207], v[144:147], v[24:27]
	v_mfma_f32_16x16x32_bf16 v[20:23], v[196:199], v[152:155], v[20:23]
	v_mfma_f32_16x16x32_bf16 v[16:19], v[204:207], v[152:155], v[16:19]
	v_mfma_f32_16x16x32_bf16 v[12:15], v[196:199], v[180:183], v[12:15]
	v_mfma_f32_16x16x32_bf16 v[8:11], v[204:207], v[180:183], v[8:11]
	v_mfma_f32_16x16x32_bf16 v[4:7], v[196:199], v[188:191], v[4:7]
	v_mfma_f32_16x16x32_bf16 v[0:3], v[204:207], v[188:191], v[0:3]
	v_mfma_f32_16x16x32_bf16 v[28:31], v[200:203], v[148:151], v[28:31]
	v_mfma_f32_16x16x32_bf16 v[24:27], v[208:211], v[148:151], v[24:27]
	v_mfma_f32_16x16x32_bf16 v[20:23], v[200:203], v[156:159], v[20:23]
	v_mfma_f32_16x16x32_bf16 v[16:19], v[208:211], v[156:159], v[16:19]
	v_mfma_f32_16x16x32_bf16 v[12:15], v[200:203], v[184:187], v[12:15]
	v_mfma_f32_16x16x32_bf16 v[8:11], v[208:211], v[184:187], v[8:11]
	v_mfma_f32_16x16x32_bf16 v[4:7], v[200:203], v[192:195], v[4:7]
	v_mfma_f32_16x16x32_bf16 v[0:3], v[208:211], v[192:195], v[0:3]
	s_add_i32 s75, s75, 2
	s_add_i32 s78, s78, 0x8000
	s_cmp_lt_u32 s75, 28
	s_barrier
	s_cbranch_scc1 .LBB0_306
	s_mov_b64 s[26:27], -1
	s_and_b64 vcc, exec, s[38:39]
	s_cbranch_vccz .LBB0_309
	s_ashr_i32 s43, s42, 31
	v_lshl_add_u64 v[128:129], v[174:175], 0, s[42:43]
	v_lshl_add_u64 v[128:129], v[128:129], 2, s[50:51]
	global_load_dword v150, v[128:129], off offset:-1024
	v_add_u32_e32 v128, s42, v163
	v_ashrrev_i32_e32 v129, 31, v128
	v_lshl_add_u64 v[128:129], v[128:129], 2, s[18:19]
	s_mov_b64 s[26:27], 0

; #define LDA(dst, b, h)                                                                                               \
;   _Pragma("unroll") for (int m = 0; m < 4; ++m) _Pragma("unroll") for (int k = 0; k < 2; ++k) dst[m][k] =            \
;       *reinterpret_cast<const bf16x8*>(SA(b, h) + lds_byte(wr * 64 + m * 16 + fr, k * 32 + fq * 8))
; #define LDB(dst, b, h)                                                                                               \
;   _Pragma("unroll") for (int n = 0; n < 2; ++n) _Pragma("unroll") for (int k = 0; k < 2; ++k) dst[n][k] =            \
;       *reinterpret_cast<const bf16x8*>(SB(b, h) + lds_byte(wc * 32 + n * 16 + fr, k * 32 + fq * 8))
; #define WAIT_V(n) asm volatile("s_waitcnt vmcnt(" #n ")" ::: "memory")
; #define WAIT_L(n) asm volatile("s_waitcnt lgkmcnt(" #n ")" ::: "memory")
; #define BAR __builtin_amdgcn_s_barrier()
; template <int EPI>
; __device__ __forceinline__ void gemm_phase(const u16* __restrict__ A, const u16* __restrict__ Bt, const int K,
;                                            const int nN, char* shm, const EpiArgs& ea) {
;     ...
;       LDB(B0, 0, 0); LDA(At, 0, 0); STAGE(SA(1, 1), rA, brow + HALF, nt - 1);
;       WAIT_V(10); BAR; WAIT_L(0); MMA(0, 0, At, B0); BAR;
;       LDB(B1, 0, 1); WAIT_V(8); BAR; WAIT_L(0); MMA(0, 1, At, B1); BAR;
;       LDA(At, 0, 1); WAIT_V(4); BAR; WAIT_L(0); MMA(1, 0, At, B0); MMA(1, 1, At, B1); BAR;
.LBB0_311:
	s_mov_b32 m0, s52
	s_add_i32 s26, s72, 0x7c000
	global_load_dword v151, v[128:129], off
	ds_read_b128 v[128:131], v168
	ds_read_b128 v[132:135], v168 offset:1024
	ds_read_b128 v[136:139], v168 offset:2048
	ds_read_b128 v[140:143], v168 offset:3072
	ds_read_b128 v[144:147], v169
	ds_read_b128 v[152:155], v169 offset:1024
	ds_read_b128 v[156:159], v170
	ds_read_b128 v[180:183], v170 offset:1024
	ds_read_b128 v[184:187], v171
	ds_read_b128 v[188:191], v171 offset:1024
	ds_read_b128 v[192:195], v172
	ds_read_b128 v[196:199], v172 offset:1024
	buffer_load_dwordx4 v161, s[0:3], s26 offen lds
	s_add_i32 s72, s72, 0x7e000
	s_mov_b32 m0, s53
	s_nop 0
	buffer_load_dwordx4 v161, s[0:3], s72 offen lds
	s_waitcnt vmcnt(10)
	s_barrier
	s_waitcnt lgkmcnt(7)
	v_mfma_f32_16x16x32_bf16 v[124:127], v[128:131], v[144:147], v[124:127]
	v_mfma_f32_16x16x32_bf16 v[120:123], v[136:139], v[144:147], v[120:123]
	s_waitcnt lgkmcnt(5)
	v_mfma_f32_16x16x32_bf16 v[116:119], v[128:131], v[156:159], v[116:119]
	v_mfma_f32_16x16x32_bf16 v[112:115], v[136:139], v[156:159], v[112:115]
	s_waitcnt lgkmcnt(3)
	v_mfma_f32_16x16x32_bf16 v[108:111], v[128:131], v[184:187], v[108:111]
	v_mfma_f32_16x16x32_bf16 v[104:107], v[136:139], v[184:187], v[104:107]
	s_waitcnt lgkmcnt(1)
	v_mfma_f32_16x16x32_bf16 v[100:103], v[128:131], v[192:195], v[100:103]
	v_mfma_f32_16x16x32_bf16 v[96:99], v[136:139], v[192:195], v[96:99]
	v_mfma_f32_16x16x32_bf16 v[124:127], v[132:135], v[152:155], v[124:127]
	v_mfma_f32_16x16x32_bf16 v[120:123], v[140:143], v[152:155], v[120:123]
	v_mfma_f32_16x16x32_bf16 v[116:119], v[132:135], v[180:183], v[116:119]
	v_mfma_f32_16x16x32_bf16 v[112:115], v[140:143], v[180:183], v[112:115]
	v_mfma_f32_16x16x32_bf16 v[108:111], v[132:135], v[188:191], v[108:111]
	v_mfma_f32_16x16x32_bf16 v[104:107], v[140:143], v[188:191], v[104:107]
	s_waitcnt lgkmcnt(0)
	v_mfma_f32_16x16x32_bf16 v[100:103], v[132:135], v[196:199], v[100:103]
	v_mfma_f32_16x16x32_bf16 v[96:99], v[140:143], v[196:199], v[96:99]
	s_barrier
	ds_read_b128 v[200:203], v173
	ds_read_b128 v[204:207], v173 offset:1024
	ds_read_b128 v[208:211], v173 offset:2048
	ds_read_b128 v[212:215], v173 offset:3072
	s_waitcnt vmcnt(8)
	s_barrier
	s_waitcnt lgkmcnt(3)
	v_mfma_f32_16x16x32_bf16 v[92:95], v[200:203], v[144:147], v[92:95]
	s_waitcnt lgkmcnt(1)
	v_mfma_f32_16x16x32_bf16 v[88:91], v[208:211], v[144:147], v[88:91]
	v_mfma_f32_16x16x32_bf16 v[84:87], v[200:203], v[156:159], v[84:87]
	v_mfma_f32_16x16x32_bf16 v[80:83], v[208:211], v[156:159], v[80:83]
	v_mfma_f32_16x16x32_bf16 v[76:79], v[200:203], v[184:187], v[76:79]
	v_mfma_f32_16x16x32_bf16 v[72:75], v[208:211], v[184:187], v[72:75]
	v_mfma_f32_16x16x32_bf16 v[68:71], v[200:203], v[192:195], v[68:71]
	v_mfma_f32_16x16x32_bf16 v[64:67], v[208:211], v[192:195], v[64:67]
	v_mfma_f32_16x16x32_bf16 v[92:95], v[204:207], v[152:155], v[92:95]
	s_waitcnt lgkmcnt(0)
	v_mfma_f32_16x16x32_bf16 v[88:91], v[212:215], v[152:155], v[88:91]
	v_mfma_f32_16x16x32_bf16 v[84:87], v[204:207], v[180:183], v[84:87]
	v_mfma_f32_16x16x32_bf16 v[80:83], v[212:215], v[180:183], v[80:83]
	v_mfma_f32_16x16x32_bf16 v[76:79], v[204:207], v[188:191], v[76:79]
	v_mfma_f32_16x16x32_bf16 v[72:75], v[212:215], v[188:191], v[72:75]
	v_mfma_f32_16x16x32_bf16 v[68:71], v[204:207], v[196:199], v[68:71]
	v_mfma_f32_16x16x32_bf16 v[64:67], v[212:215], v[196:199], v[64:67]
	s_barrier
	ds_read_b128 v[144:147], v169 offset:16384
	ds_read_b128 v[152:155], v169 offset:17408
	ds_read_b128 v[156:159], v170 offset:16384
	ds_read_b128 v[180:183], v170 offset:17408
	ds_read_b128 v[184:187], v171 offset:16384
	ds_read_b128 v[188:191], v171 offset:17408
	ds_read_b128 v[192:195], v172 offset:16384
	ds_read_b128 v[196:199], v172 offset:17408
	s_waitcnt vmcnt(4)
	s_barrier
	s_waitcnt lgkmcnt(7)
	v_mfma_f32_16x16x32_bf16 v[60:63], v[128:131], v[144:147], v[60:63]
	v_mfma_f32_16x16x32_bf16 v[56:59], v[136:139], v[144:147], v[56:59]
	s_waitcnt lgkmcnt(3)
	v_mfma_f32_16x16x32_bf16 v[40:43], v[136:139], v[184:187], v[40:43]
	v_mfma_f32_16x16x32_bf16 v[60:63], v[132:135], v[152:155], v[60:63]
	v_mfma_f32_16x16x32_bf16 v[56:59], v[140:143], v[152:155], v[56:59]
	v_mfma_f32_16x16x32_bf16 v[52:55], v[128:131], v[156:159], v[52:55]
	v_mfma_f32_16x16x32_bf16 v[48:51], v[136:139], v[156:159], v[48:51]
	v_mfma_f32_16x16x32_bf16 v[44:47], v[128:131], v[184:187], v[44:47]
	s_waitcnt lgkmcnt(2)
	v_mfma_f32_16x16x32_bf16 v[40:43], v[140:143], v[188:191], v[40:43]
	s_waitcnt lgkmcnt(1)
	v_mfma_f32_16x16x32_bf16 v[36:39], v[128:131], v[192:195], v[36:39]
	v_mfma_f32_16x16x32_bf16 v[32:35], v[136:139], v[192:195], v[32:35]
	v_mfma_f32_16x16x32_bf16 v[52:55], v[132:135], v[180:183], v[52:55]
	v_mfma_f32_16x16x32_bf16 v[216:219], v[140:143], v[180:183], v[48:51]
	v_mfma_f32_16x16x32_bf16 v[44:47], v[132:135], v[188:191], v[44:47]
	s_waitcnt lgkmcnt(0)
	v_mfma_f32_16x16x32_bf16 v[220:223], v[132:135], v[196:199], v[36:39]
	v_mfma_f32_16x16x32_bf16 v[32:35], v[140:143], v[196:199], v[32:35]
	v_mfma_f32_16x16x32_bf16 v[16:19], v[208:211], v[156:159], v[16:19]
	v_mfma_f32_16x16x32_bf16 v[4:7], v[200:203], v[192:195], v[4:7]
	v_mfma_f32_16x16x32_bf16 v[0:3], v[208:211], v[192:195], v[0:3]
	v_mfma_f32_16x16x32_bf16 v[28:31], v[200:203], v[144:147], v[28:31]
	v_mfma_f32_16x16x32_bf16 v[24:27], v[208:211], v[144:147], v[24:27]
	v_mfma_f32_16x16x32_bf16 v[20:23], v[200:203], v[156:159], v[20:23]
	v_mfma_f32_16x16x32_bf16 v[16:19], v[212:215], v[180:183], v[16:19]
	v_mfma_f32_16x16x32_bf16 v[12:15], v[200:203], v[184:187], v[12:15]
	v_mfma_f32_16x16x32_bf16 v[8:11], v[208:211], v[184:187], v[8:11]
	v_mfma_f32_16x16x32_bf16 v[4:7], v[204:207], v[196:199], v[4:7]
	v_mfma_f32_16x16x32_bf16 v[0:3], v[212:215], v[196:199], v[0:3]
	v_mfma_f32_16x16x32_bf16 v[224:227], v[204:207], v[152:155], v[28:31]
	v_mfma_f32_16x16x32_bf16 v[24:27], v[212:215], v[152:155], v[24:27]
	v_mfma_f32_16x16x32_bf16 v[20:23], v[204:207], v[180:183], v[20:23]
	v_mfma_f32_16x16x32_bf16 v[152:155], v[204:207], v[188:191], v[12:15]
	v_mfma_f32_16x16x32_bf16 v[156:159], v[212:215], v[188:191], v[8:11]
	s_barrier
; #define LDA(dst, b, h)                                                                                               \
;   _Pragma("unroll") for (int m = 0; m < 4; ++m) _Pragma("unroll") for (int k = 0; k < 2; ++k) dst[m][k] =            \
;       *reinterpret_cast<const bf16x8*>(SA(b, h) + lds_byte(wr * 64 + m * 16 + fr, k * 32 + fq * 8))
; #define LDB(dst, b, h)                                                                                               \
;   _Pragma("unroll") for (int n = 0; n < 2; ++n) _Pragma("unroll") for (int k = 0; k < 2; ++k) dst[n][k] =            \
;       *reinterpret_cast<const bf16x8*>(SB(b, h) + lds_byte(wc * 32 + n * 16 + fr, k * 32 + fq * 8))
; #define WAIT_V(n) asm volatile("s_waitcnt vmcnt(" #n ")" ::: "memory")
; #define WAIT_L(n) asm volatile("s_waitcnt lgkmcnt(" #n ")" ::: "memory")
; #define BAR __builtin_amdgcn_s_barrier()
; template <int EPI>
; __device__ __forceinline__ void gemm_phase(const u16* __restrict__ A, const u16* __restrict__ Bt, const int K,
;                                            const int nN, char* shm, const EpiArgs& ea) {
;     ...
;       LDB(B0, 1, 0); LDA(At, 1, 0); WAIT_V(2); BAR; WAIT_L(0); MMA(0, 0, At, B0); BAR;
;       LDB(B1, 1, 1); WAIT_V(0); BAR; WAIT_L(0); MMA(0, 1, At, B1); BAR;
;       LDA(At, 1, 1); BAR; WAIT_L(0); MMA(1, 0, At, B0); MMA(1, 1, At, B1); BAR;
;     }
;     if (wr == 0) BAR;
	s_nop 0
	ds_read_b128 v[8:11], v176
	ds_read_b128 v[12:15], v176 offset:1024
	ds_read_b128 v[180:183], v176 offset:2048
	ds_read_b128 v[184:187], v176 offset:3072
	ds_read_b128 v[128:131], v169 offset:32768
	ds_read_b128 v[132:135], v169 offset:33792
	ds_read_b128 v[188:191], v170 offset:32768
	ds_read_b128 v[192:195], v170 offset:33792
	ds_read_b128 v[196:199], v171 offset:32768
	ds_read_b128 v[200:203], v171 offset:33792
	ds_read_b128 v[204:207], v172 offset:32768
	ds_read_b128 v[208:211], v172 offset:33792
	s_waitcnt vmcnt(2)
	s_barrier
	s_waitcnt lgkmcnt(5)
	v_mfma_f32_16x16x32_bf16 v[48:51], v[8:11], v[188:191], v[116:119]
	s_waitcnt lgkmcnt(4)
	v_mfma_f32_16x16x32_bf16 v[140:143], v[12:15], v[192:195], v[48:51]
	v_mfma_f32_16x16x32_bf16 v[48:51], v[180:183], v[188:191], v[112:115]
	v_mfma_f32_16x16x32_bf16 v[136:139], v[184:187], v[192:195], v[48:51]
	s_waitcnt lgkmcnt(3)
	v_mfma_f32_16x16x32_bf16 v[48:51], v[8:11], v[196:199], v[108:111]
	v_mfma_f32_16x16x32_bf16 v[28:31], v[8:11], v[128:131], v[124:127]
	s_waitcnt lgkmcnt(2)
	v_mfma_f32_16x16x32_bf16 v[124:127], v[12:15], v[200:203], v[48:51]
	v_mfma_f32_16x16x32_bf16 v[48:51], v[180:183], v[196:199], v[104:107]
	v_mfma_f32_16x16x32_bf16 v[36:39], v[180:183], v[128:131], v[120:123]
	v_mfma_f32_16x16x32_bf16 v[120:123], v[184:187], v[200:203], v[48:51]
	s_waitcnt lgkmcnt(1)
	v_mfma_f32_16x16x32_bf16 v[48:51], v[8:11], v[204:207], v[100:103]
	s_waitcnt lgkmcnt(0)
	v_mfma_f32_16x16x32_bf16 v[108:111], v[12:15], v[208:211], v[48:51]
	v_mfma_f32_16x16x32_bf16 v[48:51], v[180:183], v[204:207], v[96:99]
	v_mfma_f32_16x16x32_bf16 v[28:31], v[12:15], v[132:135], v[28:31]
	v_mfma_f32_16x16x32_bf16 v[36:39], v[184:187], v[132:135], v[36:39]
	v_mfma_f32_16x16x32_bf16 v[104:107], v[184:187], v[208:211], v[48:51]
	s_barrier
	ds_read_b128 v[212:215], v177
	ds_read_b128 v[228:231], v177 offset:1024
	ds_read_b128 v[232:235], v177 offset:2048
	ds_read_b128 v[236:239], v177 offset:3072
	s_waitcnt vmcnt(0)
	s_barrier
	s_waitcnt lgkmcnt(3)
	v_mfma_f32_16x16x32_bf16 v[48:51], v[212:215], v[128:131], v[92:95]
	s_waitcnt lgkmcnt(1)
	v_mfma_f32_16x16x32_bf16 v[88:91], v[232:235], v[128:131], v[88:91]
	v_mfma_f32_16x16x32_bf16 v[84:87], v[212:215], v[188:191], v[84:87]
	v_mfma_f32_16x16x32_bf16 v[80:83], v[232:235], v[188:191], v[80:83]
	v_mfma_f32_16x16x32_bf16 v[76:79], v[212:215], v[196:199], v[76:79]
	v_mfma_f32_16x16x32_bf16 v[72:75], v[232:235], v[196:199], v[72:75]
	v_mfma_f32_16x16x32_bf16 v[68:71], v[212:215], v[204:207], v[68:71]
	v_mfma_f32_16x16x32_bf16 v[64:67], v[232:235], v[204:207], v[64:67]
	v_mfma_f32_16x16x32_bf16 v[48:51], v[228:231], v[132:135], v[48:51]
	s_waitcnt lgkmcnt(0)
	v_mfma_f32_16x16x32_bf16 v[144:147], v[236:239], v[132:135], v[88:91]
	v_mfma_f32_16x16x32_bf16 v[132:135], v[228:231], v[192:195], v[84:87]
	v_mfma_f32_16x16x32_bf16 v[128:131], v[236:239], v[192:195], v[80:83]
	v_mfma_f32_16x16x32_bf16 v[116:119], v[228:231], v[200:203], v[76:79]
	v_mfma_f32_16x16x32_bf16 v[112:115], v[236:239], v[200:203], v[72:75]
	v_mfma_f32_16x16x32_bf16 v[100:103], v[228:231], v[208:211], v[68:71]
	v_mfma_f32_16x16x32_bf16 v[96:99], v[236:239], v[208:211], v[64:67]
	s_barrier
	s_nop 0
	ds_read_b128 v[64:67], v169 offset:49152
	ds_read_b128 v[68:71], v169 offset:50176
	ds_read_b128 v[188:191], v170 offset:49152
	ds_read_b128 v[192:195], v170 offset:50176
	ds_read_b128 v[196:199], v171 offset:49152
	ds_read_b128 v[200:203], v171 offset:50176
	ds_read_b128 v[204:207], v172 offset:49152
	ds_read_b128 v[208:211], v172 offset:50176
	s_barrier
	s_waitcnt lgkmcnt(7)
	v_mfma_f32_16x16x32_bf16 v[60:63], v[8:11], v[64:67], v[60:63]
	s_waitcnt lgkmcnt(5)
	v_mfma_f32_16x16x32_bf16 v[52:55], v[8:11], v[188:191], v[52:55]
	s_waitcnt lgkmcnt(3)
	v_mfma_f32_16x16x32_bf16 v[44:47], v[8:11], v[196:199], v[44:47]
	s_waitcnt lgkmcnt(1)
	v_mfma_f32_16x16x32_bf16 v[8:11], v[8:11], v[204:207], v[220:223]
	v_mfma_f32_16x16x32_bf16 v[92:95], v[12:15], v[68:71], v[60:63]
	v_mfma_f32_16x16x32_bf16 v[56:59], v[180:183], v[64:67], v[56:59]
	v_mfma_f32_16x16x32_bf16 v[76:79], v[12:15], v[192:195], v[52:55]
	v_mfma_f32_16x16x32_bf16 v[52:55], v[180:183], v[188:191], v[216:219]
	v_mfma_f32_16x16x32_bf16 v[60:63], v[12:15], v[200:203], v[44:47]
	v_mfma_f32_16x16x32_bf16 v[40:43], v[180:183], v[196:199], v[40:43]
	s_waitcnt lgkmcnt(0)
	v_mfma_f32_16x16x32_bf16 v[12:15], v[12:15], v[208:211], v[8:11]
	v_mfma_f32_16x16x32_bf16 v[8:11], v[180:183], v[204:207], v[32:35]
	v_mfma_f32_16x16x32_bf16 v[88:91], v[184:187], v[68:71], v[56:59]
	v_mfma_f32_16x16x32_bf16 v[72:75], v[184:187], v[192:195], v[52:55]
	v_mfma_f32_16x16x32_bf16 v[56:59], v[184:187], v[200:203], v[40:43]
	v_mfma_f32_16x16x32_bf16 v[8:11], v[184:187], v[208:211], v[8:11]
	v_mfma_f32_16x16x32_bf16 v[16:19], v[232:235], v[188:191], v[16:19]
	v_mfma_f32_16x16x32_bf16 v[32:35], v[212:215], v[64:67], v[224:227]
	v_mfma_f32_16x16x32_bf16 v[24:27], v[232:235], v[64:67], v[24:27]
	v_mfma_f32_16x16x32_bf16 v[64:67], v[236:239], v[192:195], v[16:19]
	v_mfma_f32_16x16x32_bf16 v[16:19], v[212:215], v[196:199], v[152:155]
	v_mfma_f32_16x16x32_bf16 v[20:23], v[212:215], v[188:191], v[20:23]
	v_mfma_f32_16x16x32_bf16 v[40:43], v[228:231], v[200:203], v[16:19]
	v_mfma_f32_16x16x32_bf16 v[16:19], v[232:235], v[196:199], v[156:159]
	v_mfma_f32_16x16x32_bf16 v[4:7], v[212:215], v[204:207], v[4:7]
	v_mfma_f32_16x16x32_bf16 v[0:3], v[232:235], v[204:207], v[0:3]
	v_mfma_f32_16x16x32_bf16 v[84:87], v[228:231], v[68:71], v[32:35]
	v_mfma_f32_16x16x32_bf16 v[80:83], v[236:239], v[68:71], v[24:27]
	v_mfma_f32_16x16x32_bf16 v[68:71], v[228:231], v[192:195], v[20:23]
	v_mfma_f32_16x16x32_bf16 v[16:19], v[236:239], v[200:203], v[16:19]
	v_mfma_f32_16x16x32_bf16 v[4:7], v[228:231], v[208:211], v[4:7]
	v_mfma_f32_16x16x32_bf16 v[0:3], v[236:239], v[208:211], v[0:3]
	s_andn2_b64 vcc, exec, s[36:37]
	s_barrier
	s_cbranch_vccz .LBB0_380
	s_andn2_b64 vcc, exec, s[4:5]
	s_cbranch_vccz .LBB0_381

; #define LDA(dst, b, h)                                                                                               \
;   _Pragma("unroll") for (int m = 0; m < 4; ++m) _Pragma("unroll") for (int k = 0; k < 2; ++k) dst[m][k] =            \
;       *reinterpret_cast<const bf16x8*>(SA(b, h) + lds_byte(wr * 64 + m * 16 + fr, k * 32 + fq * 8))
; #define LDB(dst, b, h)                                                                                               \
;   _Pragma("unroll") for (int n = 0; n < 2; ++n) _Pragma("unroll") for (int k = 0; k < 2; ++k) dst[n][k] =            \
;       *reinterpret_cast<const bf16x8*>(SB(b, h) + lds_byte(wc * 32 + n * 16 + fr, k * 32 + fq * 8))
; #define WAIT_V(n) asm volatile("s_waitcnt vmcnt(" #n ")" ::: "memory")
; #define WAIT_L(n) asm volatile("s_waitcnt lgkmcnt(" #n ")" ::: "memory")
; #define BAR __builtin_amdgcn_s_barrier()
; #define SCHED __builtin_amdgcn_sched_barrier(0)
; template <int EPI>
; __device__ __forceinline__ void gemm_phase(const u16* __restrict__ A, const u16* __restrict__ Bt, const int K,
;                                            const int nN, char* shm, const EpiArgs& ea) {
;     ...
;     for (int t = 0; t < nt - 2; t += 2) {
;       LDB(B0, 0, 0); SCHED; LDA(At, 0, 0); STAGE(SA(1, 1), rA, brow + HALF, t + 1);
;       WAIT_V(10); WAIT_L(8); BAR; WAIT_L(0); MMA(0, 0, At, B0); BAR; SCHED;
;       LDB(B1, 0, 1); STAGE(SB(0, 0), rB, bcol, t + 2);
;       WAIT_V(10); BAR; WAIT_L(0); MMA(0, 1, At, B1); BAR;
;       LDA(At, 0, 1); STAGE(SA(0, 0), rA, brow, t + 2);
;       BAR; WAIT_L(0); MMA(1, 0, At, B0); BAR; SCHED;
;       STAGE(SB(0, 1), rB, bcol + HALF, t + 2);
;       WAIT_V(10); BAR; MMA(1, 1, At, B1); BAR;
.LBB0_492:
	ds_read_b128 v[130:133], v146
	ds_read_b128 v[134:137], v146 offset:1024
	ds_read_b128 v[138:141], v146 offset:2048
	ds_read_b128 v[154:157], v146 offset:3072
	s_add_i32 s65, s59, s64
	s_mov_b32 m0, s34
	s_add_i32 s10, s65, 0x4000
	ds_read_b128 v[158:161], v147
	ds_read_b128 v[162:165], v147 offset:1024
	ds_read_b128 v[166:169], v148
	ds_read_b128 v[170:173], v148 offset:1024
	ds_read_b128 v[176:179], v149
	ds_read_b128 v[180:183], v149 offset:1024
	ds_read_b128 v[184:187], v150
	ds_read_b128 v[188:191], v150 offset:1024
	buffer_load_dwordx4 v142, s[0:3], s10 offen lds
	s_add_i32 s10, s65, 0x6000
	s_mov_b32 m0, s35
	s_nop 0
	buffer_load_dwordx4 v142, s[0:3], s10 offen lds
	s_waitcnt vmcnt(10)
	s_waitcnt lgkmcnt(8)
	s_barrier
	s_waitcnt lgkmcnt(7)
	v_mfma_f32_16x16x32_bf16 v[124:127], v[130:133], v[158:161], v[124:127]
	v_mfma_f32_16x16x32_bf16 v[120:123], v[138:141], v[158:161], v[120:123]
	s_waitcnt lgkmcnt(5)
	v_mfma_f32_16x16x32_bf16 v[116:119], v[130:133], v[166:169], v[116:119]
	v_mfma_f32_16x16x32_bf16 v[112:115], v[138:141], v[166:169], v[112:115]
	s_waitcnt lgkmcnt(3)
	v_mfma_f32_16x16x32_bf16 v[108:111], v[130:133], v[176:179], v[108:111]
	v_mfma_f32_16x16x32_bf16 v[104:107], v[138:141], v[176:179], v[104:107]
	s_waitcnt lgkmcnt(1)
	v_mfma_f32_16x16x32_bf16 v[100:103], v[130:133], v[184:187], v[100:103]
	v_mfma_f32_16x16x32_bf16 v[96:99], v[138:141], v[184:187], v[96:99]
	v_mfma_f32_16x16x32_bf16 v[124:127], v[134:137], v[162:165], v[124:127]
	v_mfma_f32_16x16x32_bf16 v[120:123], v[154:157], v[162:165], v[120:123]
	v_mfma_f32_16x16x32_bf16 v[116:119], v[134:137], v[170:173], v[116:119]
	v_mfma_f32_16x16x32_bf16 v[112:115], v[154:157], v[170:173], v[112:115]
	v_mfma_f32_16x16x32_bf16 v[108:111], v[134:137], v[180:183], v[108:111]
	v_mfma_f32_16x16x32_bf16 v[104:107], v[154:157], v[180:183], v[104:107]
	s_waitcnt lgkmcnt(0)
	v_mfma_f32_16x16x32_bf16 v[100:103], v[134:137], v[188:191], v[100:103]
	v_mfma_f32_16x16x32_bf16 v[96:99], v[154:157], v[188:191], v[96:99]
	s_barrier
	s_add_i32 s66, s62, s64
	s_mov_b32 m0, s36
	s_add_i32 s67, s66, 0x8000
	s_mov_b32 s10, s2
	s_mov_b32 s11, s3
	ds_read_b128 v[192:195], v151
	ds_read_b128 v[196:199], v151 offset:1024
	ds_read_b128 v[200:203], v151 offset:2048
	ds_read_b128 v[204:207], v151 offset:3072
	buffer_load_dwordx4 v142, s[8:11], s67 offen lds
	s_add_i32 s67, s66, 0xa000
	s_mov_b32 m0, s37
	s_nop 0
	buffer_load_dwordx4 v142, s[8:11], s67 offen lds
	s_waitcnt vmcnt(10)
	s_barrier
	s_waitcnt lgkmcnt(3)
	v_mfma_f32_16x16x32_bf16 v[92:95], v[192:195], v[158:161], v[92:95]
	s_waitcnt lgkmcnt(1)
	v_mfma_f32_16x16x32_bf16 v[88:91], v[200:203], v[158:161], v[88:91]
	v_mfma_f32_16x16x32_bf16 v[84:87], v[192:195], v[166:169], v[84:87]
	v_mfma_f32_16x16x32_bf16 v[80:83], v[200:203], v[166:169], v[80:83]
	v_mfma_f32_16x16x32_bf16 v[76:79], v[192:195], v[176:179], v[76:79]
	v_mfma_f32_16x16x32_bf16 v[72:75], v[200:203], v[176:179], v[72:75]
	v_mfma_f32_16x16x32_bf16 v[68:71], v[192:195], v[184:187], v[68:71]
	v_mfma_f32_16x16x32_bf16 v[64:67], v[200:203], v[184:187], v[64:67]
	v_mfma_f32_16x16x32_bf16 v[92:95], v[196:199], v[162:165], v[92:95]
	s_waitcnt lgkmcnt(0)
	v_mfma_f32_16x16x32_bf16 v[88:91], v[204:207], v[162:165], v[88:91]
	v_mfma_f32_16x16x32_bf16 v[84:87], v[196:199], v[170:173], v[84:87]
	v_mfma_f32_16x16x32_bf16 v[80:83], v[204:207], v[170:173], v[80:83]
	v_mfma_f32_16x16x32_bf16 v[76:79], v[196:199], v[180:183], v[76:79]
	v_mfma_f32_16x16x32_bf16 v[72:75], v[204:207], v[180:183], v[72:75]
	v_mfma_f32_16x16x32_bf16 v[68:71], v[196:199], v[188:191], v[68:71]
	v_mfma_f32_16x16x32_bf16 v[64:67], v[204:207], v[188:191], v[64:67]
	s_add_i32 s67, s61, s64
	s_mov_b32 m0, s27
	s_add_i32 s68, s67, 0x8000
	s_barrier
	ds_read_b128 v[158:161], v147 offset:16384
	ds_read_b128 v[162:165], v147 offset:17408
	ds_read_b128 v[166:169], v148 offset:16384
	ds_read_b128 v[170:173], v148 offset:17408
	ds_read_b128 v[176:179], v149 offset:16384
	ds_read_b128 v[180:183], v149 offset:17408
	ds_read_b128 v[184:187], v150 offset:16384
	ds_read_b128 v[188:191], v150 offset:17408
	buffer_load_dwordx4 v142, s[0:3], s68 offen lds
	s_add_i32 s68, s67, 0xa000
	s_mov_b32 m0, s38
	s_nop 0
	buffer_load_dwordx4 v142, s[0:3], s68 offen lds
	s_barrier
	s_waitcnt lgkmcnt(7)
	v_mfma_f32_16x16x32_bf16 v[60:63], v[130:133], v[158:161], v[60:63]
	v_mfma_f32_16x16x32_bf16 v[56:59], v[138:141], v[158:161], v[56:59]
	s_waitcnt lgkmcnt(5)
	v_mfma_f32_16x16x32_bf16 v[52:55], v[130:133], v[166:169], v[52:55]
	v_mfma_f32_16x16x32_bf16 v[48:51], v[138:141], v[166:169], v[48:51]
	s_waitcnt lgkmcnt(3)
	v_mfma_f32_16x16x32_bf16 v[44:47], v[130:133], v[176:179], v[44:47]
	v_mfma_f32_16x16x32_bf16 v[40:43], v[138:141], v[176:179], v[40:43]
	s_waitcnt lgkmcnt(1)
	v_mfma_f32_16x16x32_bf16 v[36:39], v[130:133], v[184:187], v[36:39]
	v_mfma_f32_16x16x32_bf16 v[32:35], v[138:141], v[184:187], v[32:35]
	v_mfma_f32_16x16x32_bf16 v[60:63], v[134:137], v[162:165], v[60:63]
	v_mfma_f32_16x16x32_bf16 v[56:59], v[154:157], v[162:165], v[56:59]
	v_mfma_f32_16x16x32_bf16 v[52:55], v[134:137], v[170:173], v[52:55]
	v_mfma_f32_16x16x32_bf16 v[48:51], v[154:157], v[170:173], v[48:51]
	v_mfma_f32_16x16x32_bf16 v[44:47], v[134:137], v[180:183], v[44:47]
	v_mfma_f32_16x16x32_bf16 v[40:43], v[154:157], v[180:183], v[40:43]
	s_waitcnt lgkmcnt(0)
	v_mfma_f32_16x16x32_bf16 v[36:39], v[134:137], v[188:191], v[36:39]
	v_mfma_f32_16x16x32_bf16 v[32:35], v[154:157], v[188:191], v[32:35]
	s_barrier
	s_add_i32 s68, s60, s64
	s_mov_b32 m0, s39
	s_add_i32 s69, s68, 0x8000
	buffer_load_dwordx4 v142, s[8:11], s69 offen lds
	s_add_i32 s69, s68, 0xa000
	s_mov_b32 m0, s40
	s_nop 0
	buffer_load_dwordx4 v142, s[8:11], s69 offen lds
	s_waitcnt vmcnt(10)
	s_barrier
; #define LDA(dst, b, h)                                                                                               \
;   _Pragma("unroll") for (int m = 0; m < 4; ++m) _Pragma("unroll") for (int k = 0; k < 2; ++k) dst[m][k] =            \
;       *reinterpret_cast<const bf16x8*>(SA(b, h) + lds_byte(wr * 64 + m * 16 + fr, k * 32 + fq * 8))
; #define LDB(dst, b, h)                                                                                               \
;   _Pragma("unroll") for (int n = 0; n < 2; ++n) _Pragma("unroll") for (int k = 0; k < 2; ++k) dst[n][k] =            \
;       *reinterpret_cast<const bf16x8*>(SB(b, h) + lds_byte(wc * 32 + n * 16 + fr, k * 32 + fq * 8))
; #define WAIT_V(n) asm volatile("s_waitcnt vmcnt(" #n ")" ::: "memory")
; #define WAIT_L(n) asm volatile("s_waitcnt lgkmcnt(" #n ")" ::: "memory")
; #define BAR __builtin_amdgcn_s_barrier()
; #define SCHED __builtin_amdgcn_sched_barrier(0)
; template <int EPI>
; __device__ __forceinline__ void gemm_phase(const u16* __restrict__ A, const u16* __restrict__ Bt, const int K,
;                                            const int nN, char* shm, const EpiArgs& ea) {
;     ...
;       WAIT_V(10); BAR; MMA(1, 1, At, B1); BAR;
;       LDB(B0, 1, 0); SCHED; LDA(At, 1, 0); STAGE(SA(0, 1), rA, brow + HALF, t + 2);
;       WAIT_V(10); WAIT_L(8); BAR; WAIT_L(0); MMA(0, 0, At, B0); BAR; SCHED;
;       LDB(B1, 1, 1); STAGE(SB(1, 0), rB, bcol, t + 3);
;       WAIT_V(10); BAR; WAIT_L(0); MMA(0, 1, At, B1); BAR;
	v_mfma_f32_16x16x32_bf16 v[28:31], v[192:195], v[158:161], v[28:31]
	v_mfma_f32_16x16x32_bf16 v[24:27], v[200:203], v[158:161], v[24:27]
	v_mfma_f32_16x16x32_bf16 v[20:23], v[192:195], v[166:169], v[20:23]
	v_mfma_f32_16x16x32_bf16 v[16:19], v[200:203], v[166:169], v[16:19]
	v_mfma_f32_16x16x32_bf16 v[12:15], v[192:195], v[176:179], v[12:15]
	v_mfma_f32_16x16x32_bf16 v[8:11], v[200:203], v[176:179], v[8:11]
	v_mfma_f32_16x16x32_bf16 v[4:7], v[192:195], v[184:187], v[4:7]
	v_mfma_f32_16x16x32_bf16 v[0:3], v[200:203], v[184:187], v[0:3]
	v_mfma_f32_16x16x32_bf16 v[28:31], v[196:199], v[162:165], v[28:31]
	v_mfma_f32_16x16x32_bf16 v[24:27], v[204:207], v[162:165], v[24:27]
	v_mfma_f32_16x16x32_bf16 v[20:23], v[196:199], v[170:173], v[20:23]
	v_mfma_f32_16x16x32_bf16 v[16:19], v[204:207], v[170:173], v[16:19]
	v_mfma_f32_16x16x32_bf16 v[12:15], v[196:199], v[180:183], v[12:15]
	v_mfma_f32_16x16x32_bf16 v[8:11], v[204:207], v[180:183], v[8:11]
	v_mfma_f32_16x16x32_bf16 v[4:7], v[196:199], v[188:191], v[4:7]
	v_mfma_f32_16x16x32_bf16 v[0:3], v[204:207], v[188:191], v[0:3]
	s_barrier
	ds_read_b128 v[130:133], v152
	ds_read_b128 v[134:137], v152 offset:1024
	ds_read_b128 v[138:141], v152 offset:2048
	ds_read_b128 v[154:157], v152 offset:3072
	s_mov_b32 m0, s41
	s_add_i32 s69, s65, 0x8000
	ds_read_b128 v[158:161], v147 offset:32768
	ds_read_b128 v[162:165], v147 offset:33792
	ds_read_b128 v[166:169], v148 offset:32768
	ds_read_b128 v[170:173], v148 offset:33792
	ds_read_b128 v[176:179], v149 offset:32768
	ds_read_b128 v[180:183], v149 offset:33792
	ds_read_b128 v[184:187], v150 offset:32768
	ds_read_b128 v[188:191], v150 offset:33792
	buffer_load_dwordx4 v142, s[0:3], s69 offen lds
	s_add_i32 s65, s65, 0xa000
	s_mov_b32 m0, s42
	s_nop 0
	buffer_load_dwordx4 v142, s[0:3], s65 offen lds
	s_waitcnt vmcnt(10)
	s_waitcnt lgkmcnt(8)
	s_barrier
	s_waitcnt lgkmcnt(7)
	v_mfma_f32_16x16x32_bf16 v[124:127], v[130:133], v[158:161], v[124:127]
	v_mfma_f32_16x16x32_bf16 v[120:123], v[138:141], v[158:161], v[120:123]
	s_waitcnt lgkmcnt(5)
	v_mfma_f32_16x16x32_bf16 v[116:119], v[130:133], v[166:169], v[116:119]
	v_mfma_f32_16x16x32_bf16 v[112:115], v[138:141], v[166:169], v[112:115]
	s_waitcnt lgkmcnt(3)
	v_mfma_f32_16x16x32_bf16 v[108:111], v[130:133], v[176:179], v[108:111]
	v_mfma_f32_16x16x32_bf16 v[104:107], v[138:141], v[176:179], v[104:107]
	s_waitcnt lgkmcnt(1)
	v_mfma_f32_16x16x32_bf16 v[100:103], v[130:133], v[184:187], v[100:103]
	v_mfma_f32_16x16x32_bf16 v[96:99], v[138:141], v[184:187], v[96:99]
	v_mfma_f32_16x16x32_bf16 v[124:127], v[134:137], v[162:165], v[124:127]
	v_mfma_f32_16x16x32_bf16 v[120:123], v[154:157], v[162:165], v[120:123]
	v_mfma_f32_16x16x32_bf16 v[116:119], v[134:137], v[170:173], v[116:119]
	v_mfma_f32_16x16x32_bf16 v[112:115], v[154:157], v[170:173], v[112:115]
	v_mfma_f32_16x16x32_bf16 v[108:111], v[134:137], v[180:183], v[108:111]
	v_mfma_f32_16x16x32_bf16 v[104:107], v[154:157], v[180:183], v[104:107]
	s_waitcnt lgkmcnt(0)
	v_mfma_f32_16x16x32_bf16 v[100:103], v[134:137], v[188:191], v[100:103]
	v_mfma_f32_16x16x32_bf16 v[96:99], v[154:157], v[188:191], v[96:99]
	s_barrier
	s_mov_b32 m0, s43
	s_add_i32 s65, s66, 0xc000
	ds_read_b128 v[192:195], v153
	ds_read_b128 v[196:199], v153 offset:1024
	ds_read_b128 v[200:203], v153 offset:2048
	ds_read_b128 v[204:207], v153 offset:3072
	buffer_load_dwordx4 v142, s[8:11], s65 offen lds
	s_add_i32 s66, s66, 0xe000
	s_mov_b32 m0, s48
	s_nop 0
	buffer_load_dwordx4 v142, s[8:11], s66 offen lds
	s_waitcnt vmcnt(10)
	s_barrier
	s_waitcnt lgkmcnt(3)
	v_mfma_f32_16x16x32_bf16 v[92:95], v[192:195], v[158:161], v[92:95]
	s_waitcnt lgkmcnt(1)
	v_mfma_f32_16x16x32_bf16 v[88:91], v[200:203], v[158:161], v[88:91]
	v_mfma_f32_16x16x32_bf16 v[84:87], v[192:195], v[166:169], v[84:87]
	v_mfma_f32_16x16x32_bf16 v[80:83], v[200:203], v[166:169], v[80:83]
	v_mfma_f32_16x16x32_bf16 v[76:79], v[192:195], v[176:179], v[76:79]
	v_mfma_f32_16x16x32_bf16 v[72:75], v[200:203], v[176:179], v[72:75]
	v_mfma_f32_16x16x32_bf16 v[68:71], v[192:195], v[184:187], v[68:71]
	v_mfma_f32_16x16x32_bf16 v[64:67], v[200:203], v[184:187], v[64:67]
	v_mfma_f32_16x16x32_bf16 v[92:95], v[196:199], v[162:165], v[92:95]
	s_waitcnt lgkmcnt(0)
	v_mfma_f32_16x16x32_bf16 v[88:91], v[204:207], v[162:165], v[88:91]
	v_mfma_f32_16x16x32_bf16 v[84:87], v[196:199], v[170:173], v[84:87]
	v_mfma_f32_16x16x32_bf16 v[80:83], v[204:207], v[170:173], v[80:83]
	v_mfma_f32_16x16x32_bf16 v[76:79], v[196:199], v[180:183], v[76:79]
	v_mfma_f32_16x16x32_bf16 v[72:75], v[204:207], v[180:183], v[72:75]
	v_mfma_f32_16x16x32_bf16 v[68:71], v[196:199], v[188:191], v[68:71]
	v_mfma_f32_16x16x32_bf16 v[64:67], v[204:207], v[188:191], v[64:67]
	s_mov_b32 m0, s49
	s_add_i32 s65, s67, 0xc000
	s_barrier
	ds_read_b128 v[158:161], v147 offset:49152
	ds_read_b128 v[162:165], v147 offset:50176
	ds_read_b128 v[166:169], v148 offset:49152
	ds_read_b128 v[170:173], v148 offset:50176
	ds_read_b128 v[176:179], v149 offset:49152
	ds_read_b128 v[180:183], v149 offset:50176
	ds_read_b128 v[184:187], v150 offset:49152
	ds_read_b128 v[188:191], v150 offset:50176
	buffer_load_dwordx4 v142, s[0:3], s65 offen lds
	s_add_i32 s67, s67, 0xe000
	s_mov_b32 m0, s50
	s_nop 0
	buffer_load_dwordx4 v142, s[0:3], s67 offen lds
	s_barrier
; #define LDA(dst, b, h)                                                                                               \
;   _Pragma("unroll") for (int m = 0; m < 4; ++m) _Pragma("unroll") for (int k = 0; k < 2; ++k) dst[m][k] =            \
;       *reinterpret_cast<const bf16x8*>(SA(b, h) + lds_byte(wr * 64 + m * 16 + fr, k * 32 + fq * 8))
; #define LDB(dst, b, h)                                                                                               \
;   _Pragma("unroll") for (int n = 0; n < 2; ++n) _Pragma("unroll") for (int k = 0; k < 2; ++k) dst[n][k] =            \
;       *reinterpret_cast<const bf16x8*>(SB(b, h) + lds_byte(wc * 32 + n * 16 + fr, k * 32 + fq * 8))
; #define WAIT_V(n) asm volatile("s_waitcnt vmcnt(" #n ")" ::: "memory")
; #define WAIT_L(n) asm volatile("s_waitcnt lgkmcnt(" #n ")" ::: "memory")
; #define BAR __builtin_amdgcn_s_barrier()
; #define SCHED __builtin_amdgcn_sched_barrier(0)
; template <int EPI>
; __device__ __forceinline__ void gemm_phase(const u16* __restrict__ A, const u16* __restrict__ Bt, const int K,
;                                            const int nN, char* shm, const EpiArgs& ea) {
;     ...
;       LDA(At, 1, 1); STAGE(SA(1, 0), rA, brow, t + 3);
;       BAR; WAIT_L(0); MMA(1, 0, At, B0); BAR; SCHED;
;       STAGE(SB(1, 1), rB, bcol + HALF, t + 3);
;       WAIT_V(10); BAR; MMA(1, 1, At, B1); BAR;
;     }
;     float eC = 0.f, eB = 0.f;
;     float2 eS = make_float2(0.f, 0.f);
;     if (EPI == EPI_IN || EPI == EPI_SWIGLU_LN) {
;       if (wr == 0) {
;         eC = ea.c1[bcol + tid];
;         eS = *(const float2*)(ea.st_in + (size_t)(brow + tid) * 2);
;       } else {
;         eC = ea.c2[bcol + tid - 256];
;         if (EPI == EPI_IN) eB = ea.bias[bcol + tid - 256];
;       }
;     }
;     {
;       LDB(B0, 0, 0); LDA(At, 0, 0); STAGE(SA(1, 1), rA, brow + HALF, nt - 1);
;       WAIT_V(10); BAR; WAIT_L(0); MMA(0, 0, At, B0); BAR;
;       LDB(B1, 0, 1); WAIT_V(8); BAR; WAIT_L(0); MMA(0, 1, At, B1); BAR;
	s_waitcnt lgkmcnt(7)
	v_mfma_f32_16x16x32_bf16 v[60:63], v[130:133], v[158:161], v[60:63]
	v_mfma_f32_16x16x32_bf16 v[56:59], v[138:141], v[158:161], v[56:59]
	s_waitcnt lgkmcnt(5)
	v_mfma_f32_16x16x32_bf16 v[52:55], v[130:133], v[166:169], v[52:55]
	v_mfma_f32_16x16x32_bf16 v[48:51], v[138:141], v[166:169], v[48:51]
	s_waitcnt lgkmcnt(3)
	v_mfma_f32_16x16x32_bf16 v[44:47], v[130:133], v[176:179], v[44:47]
	v_mfma_f32_16x16x32_bf16 v[40:43], v[138:141], v[176:179], v[40:43]
	s_waitcnt lgkmcnt(1)
	v_mfma_f32_16x16x32_bf16 v[36:39], v[130:133], v[184:187], v[36:39]
	v_mfma_f32_16x16x32_bf16 v[32:35], v[138:141], v[184:187], v[32:35]
	v_mfma_f32_16x16x32_bf16 v[60:63], v[134:137], v[162:165], v[60:63]
	v_mfma_f32_16x16x32_bf16 v[56:59], v[154:157], v[162:165], v[56:59]
	v_mfma_f32_16x16x32_bf16 v[52:55], v[134:137], v[170:173], v[52:55]
	v_mfma_f32_16x16x32_bf16 v[48:51], v[154:157], v[170:173], v[48:51]
	v_mfma_f32_16x16x32_bf16 v[44:47], v[134:137], v[180:183], v[44:47]
	v_mfma_f32_16x16x32_bf16 v[40:43], v[154:157], v[180:183], v[40:43]
	s_waitcnt lgkmcnt(0)
	v_mfma_f32_16x16x32_bf16 v[36:39], v[134:137], v[188:191], v[36:39]
	v_mfma_f32_16x16x32_bf16 v[32:35], v[154:157], v[188:191], v[32:35]
	s_barrier
	s_mov_b32 m0, s51
	s_add_i32 s65, s68, 0xc000
	buffer_load_dwordx4 v142, s[8:11], s65 offen lds
	s_add_i32 s68, s68, 0xe000
	s_mov_b32 m0, s52
	s_nop 0
	buffer_load_dwordx4 v142, s[8:11], s68 offen lds
	s_waitcnt vmcnt(10)
	s_barrier
	v_mfma_f32_16x16x32_bf16 v[28:31], v[192:195], v[158:161], v[28:31]
	v_mfma_f32_16x16x32_bf16 v[24:27], v[200:203], v[158:161], v[24:27]
	v_mfma_f32_16x16x32_bf16 v[20:23], v[192:195], v[166:169], v[20:23]
	v_mfma_f32_16x16x32_bf16 v[16:19], v[200:203], v[166:169], v[16:19]
	v_mfma_f32_16x16x32_bf16 v[12:15], v[192:195], v[176:179], v[12:15]
	v_mfma_f32_16x16x32_bf16 v[8:11], v[200:203], v[176:179], v[8:11]
	v_mfma_f32_16x16x32_bf16 v[4:7], v[192:195], v[184:187], v[4:7]
	v_mfma_f32_16x16x32_bf16 v[0:3], v[200:203], v[184:187], v[0:3]
	v_mfma_f32_16x16x32_bf16 v[28:31], v[196:199], v[162:165], v[28:31]
	v_mfma_f32_16x16x32_bf16 v[24:27], v[204:207], v[162:165], v[24:27]
	v_mfma_f32_16x16x32_bf16 v[20:23], v[196:199], v[170:173], v[20:23]
	v_mfma_f32_16x16x32_bf16 v[16:19], v[204:207], v[170:173], v[16:19]
	v_mfma_f32_16x16x32_bf16 v[12:15], v[196:199], v[180:183], v[12:15]
	v_mfma_f32_16x16x32_bf16 v[8:11], v[204:207], v[180:183], v[8:11]
	v_mfma_f32_16x16x32_bf16 v[4:7], v[196:199], v[188:191], v[4:7]
	v_mfma_f32_16x16x32_bf16 v[0:3], v[204:207], v[188:191], v[0:3]
	s_add_i32 s63, s63, 2
	s_add_i32 s64, s64, 0x8000
	s_cmp_lt_u32 s63, 28
	s_barrier
	s_cbranch_scc1 .LBB0_492
	s_mov_b32 m0, s34
	s_add_i32 s10, s59, 0x7c000
	ds_read_b128 v[130:133], v146
	ds_read_b128 v[134:137], v146 offset:1024
	ds_read_b128 v[138:141], v146 offset:2048
	ds_read_b128 v[154:157], v146 offset:3072
	ds_read_b128 v[158:161], v147
	ds_read_b128 v[162:165], v147 offset:1024
	ds_read_b128 v[166:169], v148
	ds_read_b128 v[170:173], v148 offset:1024
	ds_read_b128 v[176:179], v149
	ds_read_b128 v[180:183], v149 offset:1024
	ds_read_b128 v[184:187], v150
	ds_read_b128 v[188:191], v150 offset:1024
	buffer_load_dwordx4 v142, s[0:3], s10 offen lds
	s_add_i32 s59, s59, 0x7e000
	s_mov_b32 m0, s35
	s_nop 0
	buffer_load_dwordx4 v142, s[0:3], s59 offen lds
	s_waitcnt vmcnt(10)
	s_barrier
	s_waitcnt lgkmcnt(7)
	v_mfma_f32_16x16x32_bf16 v[124:127], v[130:133], v[158:161], v[124:127]
	v_mfma_f32_16x16x32_bf16 v[120:123], v[138:141], v[158:161], v[120:123]
	s_waitcnt lgkmcnt(5)
	v_mfma_f32_16x16x32_bf16 v[116:119], v[130:133], v[166:169], v[116:119]
	v_mfma_f32_16x16x32_bf16 v[112:115], v[138:141], v[166:169], v[112:115]
	s_waitcnt lgkmcnt(1)
	v_mfma_f32_16x16x32_bf16 v[100:103], v[130:133], v[184:187], v[100:103]
	v_mfma_f32_16x16x32_bf16 v[96:99], v[138:141], v[184:187], v[96:99]
	v_mfma_f32_16x16x32_bf16 v[124:127], v[134:137], v[162:165], v[124:127]
	v_mfma_f32_16x16x32_bf16 v[120:123], v[154:157], v[162:165], v[120:123]
	v_mfma_f32_16x16x32_bf16 v[116:119], v[134:137], v[170:173], v[116:119]
	v_mfma_f32_16x16x32_bf16 v[112:115], v[154:157], v[170:173], v[112:115]
	v_mfma_f32_16x16x32_bf16 v[108:111], v[130:133], v[176:179], v[108:111]
	v_mfma_f32_16x16x32_bf16 v[104:107], v[138:141], v[176:179], v[104:107]
	s_waitcnt lgkmcnt(0)
	v_mfma_f32_16x16x32_bf16 v[100:103], v[134:137], v[188:191], v[100:103]
	v_mfma_f32_16x16x32_bf16 v[96:99], v[154:157], v[188:191], v[96:99]
	v_mfma_f32_16x16x32_bf16 v[192:195], v[134:137], v[180:183], v[108:111]
	v_mfma_f32_16x16x32_bf16 v[196:199], v[154:157], v[180:183], v[104:107]
	s_barrier
	s_nop 0
	ds_read_b128 v[104:107], v151
	ds_read_b128 v[108:111], v151 offset:1024
	ds_read_b128 v[200:203], v151 offset:2048
	ds_read_b128 v[204:207], v151 offset:3072
	s_waitcnt vmcnt(8)
	s_barrier
	s_waitcnt lgkmcnt(3)
	v_mfma_f32_16x16x32_bf16 v[84:87], v[104:107], v[166:169], v[84:87]
	s_waitcnt lgkmcnt(1)
	v_mfma_f32_16x16x32_bf16 v[80:83], v[200:203], v[166:169], v[80:83]
	v_mfma_f32_16x16x32_bf16 v[68:71], v[104:107], v[184:187], v[68:71]
	v_mfma_f32_16x16x32_bf16 v[64:67], v[200:203], v[184:187], v[64:67]
	v_mfma_f32_16x16x32_bf16 v[92:95], v[104:107], v[158:161], v[92:95]
	v_mfma_f32_16x16x32_bf16 v[88:91], v[200:203], v[158:161], v[88:91]
	v_mfma_f32_16x16x32_bf16 v[84:87], v[108:111], v[170:173], v[84:87]
	s_waitcnt lgkmcnt(0)
	v_mfma_f32_16x16x32_bf16 v[80:83], v[204:207], v[170:173], v[80:83]
	v_mfma_f32_16x16x32_bf16 v[76:79], v[104:107], v[176:179], v[76:79]
	v_mfma_f32_16x16x32_bf16 v[72:75], v[200:203], v[176:179], v[72:75]
	v_mfma_f32_16x16x32_bf16 v[68:71], v[108:111], v[188:191], v[68:71]
	v_mfma_f32_16x16x32_bf16 v[64:67], v[204:207], v[188:191], v[64:67]
	v_mfma_f32_16x16x32_bf16 v[208:211], v[108:111], v[162:165], v[92:95]
	v_mfma_f32_16x16x32_bf16 v[158:161], v[204:207], v[162:165], v[88:91]
	v_mfma_f32_16x16x32_bf16 v[162:165], v[108:111], v[180:183], v[76:79]
	v_mfma_f32_16x16x32_bf16 v[166:169], v[204:207], v[180:183], v[72:75]
	s_barrier
; #define LDA(dst, b, h)                                                                                               \
;   _Pragma("unroll") for (int m = 0; m < 4; ++m) _Pragma("unroll") for (int k = 0; k < 2; ++k) dst[m][k] =            \
;       *reinterpret_cast<const bf16x8*>(SA(b, h) + lds_byte(wr * 64 + m * 16 + fr, k * 32 + fq * 8))
; #define LDB(dst, b, h)                                                                                               \
;   _Pragma("unroll") for (int n = 0; n < 2; ++n) _Pragma("unroll") for (int k = 0; k < 2; ++k) dst[n][k] =            \
;       *reinterpret_cast<const bf16x8*>(SB(b, h) + lds_byte(wc * 32 + n * 16 + fr, k * 32 + fq * 8))
; #define WAIT_V(n) asm volatile("s_waitcnt vmcnt(" #n ")" ::: "memory")
; #define WAIT_L(n) asm volatile("s_waitcnt lgkmcnt(" #n ")" ::: "memory")
; #define BAR __builtin_amdgcn_s_barrier()
; template <int EPI>
; __device__ __forceinline__ void gemm_phase(const u16* __restrict__ A, const u16* __restrict__ Bt, const int K,
;                                            const int nN, char* shm, const EpiArgs& ea) {
;     ...
;       LDA(At, 0, 1); WAIT_V(4); BAR; WAIT_L(0); MMA(1, 0, At, B0); MMA(1, 1, At, B1); BAR;
;     }
;     {
;       LDB(B0, 1, 0); LDA(At, 1, 0); WAIT_V(2); BAR; WAIT_L(0); MMA(0, 0, At, B0); BAR;
	s_nop 0
	ds_read_b128 v[72:75], v147 offset:16384
	ds_read_b128 v[76:79], v147 offset:17408
	ds_read_b128 v[88:91], v148 offset:16384
	ds_read_b128 v[92:95], v148 offset:17408
	ds_read_b128 v[170:173], v149 offset:16384
	ds_read_b128 v[176:179], v149 offset:17408
	ds_read_b128 v[180:183], v150 offset:16384
	ds_read_b128 v[184:187], v150 offset:17408
	s_waitcnt vmcnt(4)
	s_barrier
	s_waitcnt lgkmcnt(7)
	v_mfma_f32_16x16x32_bf16 v[60:63], v[130:133], v[72:75], v[60:63]
	s_waitcnt lgkmcnt(5)
	v_mfma_f32_16x16x32_bf16 v[52:55], v[130:133], v[88:91], v[52:55]
	v_mfma_f32_16x16x32_bf16 v[48:51], v[138:141], v[88:91], v[48:51]
	s_waitcnt lgkmcnt(1)
	v_mfma_f32_16x16x32_bf16 v[36:39], v[130:133], v[180:183], v[36:39]
	v_mfma_f32_16x16x32_bf16 v[32:35], v[138:141], v[180:183], v[32:35]
	v_mfma_f32_16x16x32_bf16 v[60:63], v[134:137], v[76:79], v[60:63]
	v_mfma_f32_16x16x32_bf16 v[56:59], v[138:141], v[72:75], v[56:59]
	v_mfma_f32_16x16x32_bf16 v[52:55], v[134:137], v[92:95], v[52:55]
	v_mfma_f32_16x16x32_bf16 v[48:51], v[154:157], v[92:95], v[48:51]
	v_mfma_f32_16x16x32_bf16 v[44:47], v[130:133], v[170:173], v[44:47]
	v_mfma_f32_16x16x32_bf16 v[40:43], v[138:141], v[170:173], v[40:43]
	s_waitcnt lgkmcnt(0)
	v_mfma_f32_16x16x32_bf16 v[36:39], v[134:137], v[184:187], v[36:39]
	v_mfma_f32_16x16x32_bf16 v[32:35], v[154:157], v[184:187], v[32:35]
	v_mfma_f32_16x16x32_bf16 v[188:191], v[154:157], v[76:79], v[56:59]
	v_mfma_f32_16x16x32_bf16 v[212:215], v[134:137], v[176:179], v[44:47]
	v_mfma_f32_16x16x32_bf16 v[216:219], v[154:157], v[176:179], v[40:43]
	v_mfma_f32_16x16x32_bf16 v[20:23], v[104:107], v[88:91], v[20:23]
	v_mfma_f32_16x16x32_bf16 v[16:19], v[200:203], v[88:91], v[16:19]
	v_mfma_f32_16x16x32_bf16 v[4:7], v[104:107], v[180:183], v[4:7]
	v_mfma_f32_16x16x32_bf16 v[0:3], v[200:203], v[180:183], v[0:3]
	v_mfma_f32_16x16x32_bf16 v[28:31], v[104:107], v[72:75], v[28:31]
	v_mfma_f32_16x16x32_bf16 v[24:27], v[200:203], v[72:75], v[24:27]
	v_mfma_f32_16x16x32_bf16 v[20:23], v[108:111], v[92:95], v[20:23]
	v_mfma_f32_16x16x32_bf16 v[16:19], v[204:207], v[92:95], v[16:19]
	v_mfma_f32_16x16x32_bf16 v[12:15], v[104:107], v[170:173], v[12:15]
	v_mfma_f32_16x16x32_bf16 v[8:11], v[200:203], v[170:173], v[8:11]
	v_mfma_f32_16x16x32_bf16 v[4:7], v[108:111], v[184:187], v[4:7]
	v_mfma_f32_16x16x32_bf16 v[0:3], v[204:207], v[184:187], v[0:3]
	v_mfma_f32_16x16x32_bf16 v[130:133], v[108:111], v[76:79], v[28:31]
	v_mfma_f32_16x16x32_bf16 v[134:137], v[204:207], v[76:79], v[24:27]
	v_mfma_f32_16x16x32_bf16 v[138:141], v[108:111], v[176:179], v[12:15]
	v_mfma_f32_16x16x32_bf16 v[154:157], v[204:207], v[176:179], v[8:11]
	s_barrier
	s_nop 0
	ds_read_b128 v[8:11], v152
	ds_read_b128 v[12:15], v152 offset:1024
	ds_read_b128 v[170:173], v152 offset:2048
	ds_read_b128 v[176:179], v152 offset:3072
	ds_read_b128 v[24:27], v147 offset:32768
	ds_read_b128 v[28:31], v147 offset:33792
	ds_read_b128 v[40:43], v148 offset:32768
	ds_read_b128 v[44:47], v148 offset:33792
	ds_read_b128 v[56:59], v149 offset:32768
	ds_read_b128 v[180:183], v149 offset:33792
	ds_read_b128 v[184:187], v150 offset:32768
	ds_read_b128 v[200:203], v150 offset:33792
	s_waitcnt vmcnt(2)
	s_barrier
	s_waitcnt lgkmcnt(7)
	v_mfma_f32_16x16x32_bf16 v[72:75], v[8:11], v[24:27], v[124:127]
	s_waitcnt lgkmcnt(6)
	v_mfma_f32_16x16x32_bf16 v[124:127], v[12:15], v[28:31], v[72:75]
	v_mfma_f32_16x16x32_bf16 v[72:75], v[170:173], v[24:27], v[120:123]
	v_mfma_f32_16x16x32_bf16 v[120:123], v[176:179], v[28:31], v[72:75]
	s_waitcnt lgkmcnt(5)
	v_mfma_f32_16x16x32_bf16 v[72:75], v[8:11], v[40:43], v[116:119]
	s_waitcnt lgkmcnt(4)
	v_mfma_f32_16x16x32_bf16 v[104:107], v[12:15], v[44:47], v[72:75]
	v_mfma_f32_16x16x32_bf16 v[72:75], v[170:173], v[40:43], v[112:115]
	v_mfma_f32_16x16x32_bf16 v[108:111], v[176:179], v[44:47], v[72:75]
	s_waitcnt lgkmcnt(3)
	v_mfma_f32_16x16x32_bf16 v[72:75], v[8:11], v[56:59], v[192:195]
	s_waitcnt lgkmcnt(2)
	v_mfma_f32_16x16x32_bf16 v[88:91], v[12:15], v[180:183], v[72:75]
	v_mfma_f32_16x16x32_bf16 v[72:75], v[170:173], v[56:59], v[196:199]
	v_mfma_f32_16x16x32_bf16 v[92:95], v[176:179], v[180:183], v[72:75]
	s_waitcnt lgkmcnt(1)
	v_mfma_f32_16x16x32_bf16 v[72:75], v[8:11], v[184:187], v[100:103]
	v_mfma_f32_16x16x32_bf16 v[76:79], v[170:173], v[184:187], v[96:99]
	s_waitcnt lgkmcnt(0)
	v_mfma_f32_16x16x32_bf16 v[72:75], v[12:15], v[200:203], v[72:75]
	v_mfma_f32_16x16x32_bf16 v[76:79], v[176:179], v[200:203], v[76:79]
	s_barrier
; #define LDA(dst, b, h)                                                                                               \
;   _Pragma("unroll") for (int m = 0; m < 4; ++m) _Pragma("unroll") for (int k = 0; k < 2; ++k) dst[m][k] =            \
;       *reinterpret_cast<const bf16x8*>(SA(b, h) + lds_byte(wr * 64 + m * 16 + fr, k * 32 + fq * 8))
; #define LDB(dst, b, h)                                                                                               \
;   _Pragma("unroll") for (int n = 0; n < 2; ++n) _Pragma("unroll") for (int k = 0; k < 2; ++k) dst[n][k] =            \
;       *reinterpret_cast<const bf16x8*>(SB(b, h) + lds_byte(wc * 32 + n * 16 + fr, k * 32 + fq * 8))
; #define WAIT_V(n) asm volatile("s_waitcnt vmcnt(" #n ")" ::: "memory")
; #define WAIT_L(n) asm volatile("s_waitcnt lgkmcnt(" #n ")" ::: "memory")
; #define BAR __builtin_amdgcn_s_barrier()
; template <int EPI>
; __device__ __forceinline__ void gemm_phase(const u16* __restrict__ A, const u16* __restrict__ Bt, const int K,
;                                            const int nN, char* shm, const EpiArgs& ea) {
;     ...
;       LDB(B1, 1, 1); WAIT_V(0); BAR; WAIT_L(0); MMA(0, 1, At, B1); BAR;
;       LDA(At, 1, 1); BAR; WAIT_L(0); MMA(1, 0, At, B0); MMA(1, 1, At, B1); BAR;
;     }
;     if (wr == 0) BAR;
	ds_read_b128 v[192:195], v153
	ds_read_b128 v[196:199], v153 offset:1024
	ds_read_b128 v[204:207], v153 offset:2048
	ds_read_b128 v[220:223], v153 offset:3072
	s_waitcnt vmcnt(0)
	s_barrier
	s_waitcnt lgkmcnt(3)
	v_mfma_f32_16x16x32_bf16 v[96:99], v[192:195], v[24:27], v[208:211]
	s_waitcnt lgkmcnt(1)
	v_mfma_f32_16x16x32_bf16 v[24:27], v[204:207], v[24:27], v[158:161]
	s_waitcnt lgkmcnt(0)
	v_mfma_f32_16x16x32_bf16 v[112:115], v[220:223], v[28:31], v[24:27]
	v_mfma_f32_16x16x32_bf16 v[24:27], v[192:195], v[40:43], v[84:87]
	v_mfma_f32_16x16x32_bf16 v[100:103], v[196:199], v[44:47], v[24:27]
	v_mfma_f32_16x16x32_bf16 v[24:27], v[204:207], v[40:43], v[80:83]
	v_mfma_f32_16x16x32_bf16 v[116:119], v[196:199], v[28:31], v[96:99]
	v_mfma_f32_16x16x32_bf16 v[96:99], v[220:223], v[44:47], v[24:27]
	v_mfma_f32_16x16x32_bf16 v[24:27], v[192:195], v[56:59], v[162:165]
	v_mfma_f32_16x16x32_bf16 v[84:87], v[196:199], v[180:183], v[24:27]
	v_mfma_f32_16x16x32_bf16 v[24:27], v[204:207], v[56:59], v[166:169]
	v_mfma_f32_16x16x32_bf16 v[80:83], v[220:223], v[180:183], v[24:27]
	v_mfma_f32_16x16x32_bf16 v[24:27], v[192:195], v[184:187], v[68:71]
	v_mfma_f32_16x16x32_bf16 v[68:71], v[196:199], v[200:203], v[24:27]
	v_mfma_f32_16x16x32_bf16 v[24:27], v[204:207], v[184:187], v[64:67]
	v_mfma_f32_16x16x32_bf16 v[64:67], v[220:223], v[200:203], v[24:27]
	s_barrier
	ds_read_b128 v[158:161], v147 offset:49152
	ds_read_b128 v[162:165], v147 offset:50176
	ds_read_b128 v[166:169], v148 offset:49152
	ds_read_b128 v[180:183], v148 offset:50176
	ds_read_b128 v[184:187], v149 offset:49152
	ds_read_b128 v[200:203], v149 offset:50176
	ds_read_b128 v[208:211], v150 offset:49152
	ds_read_b128 v[224:227], v150 offset:50176
	s_barrier
	s_waitcnt lgkmcnt(7)
	v_mfma_f32_16x16x32_bf16 v[24:27], v[8:11], v[158:161], v[60:63]
	s_waitcnt lgkmcnt(6)
	v_mfma_f32_16x16x32_bf16 v[56:59], v[12:15], v[162:165], v[24:27]
	v_mfma_f32_16x16x32_bf16 v[24:27], v[170:173], v[158:161], v[188:191]
	v_mfma_f32_16x16x32_bf16 v[60:63], v[176:179], v[162:165], v[24:27]
	s_waitcnt lgkmcnt(5)
	v_mfma_f32_16x16x32_bf16 v[24:27], v[8:11], v[166:169], v[52:55]
	s_waitcnt lgkmcnt(4)
	v_mfma_f32_16x16x32_bf16 v[40:43], v[12:15], v[180:183], v[24:27]
	v_mfma_f32_16x16x32_bf16 v[24:27], v[170:173], v[166:169], v[48:51]
	v_mfma_f32_16x16x32_bf16 v[44:47], v[176:179], v[180:183], v[24:27]
	s_waitcnt lgkmcnt(3)
	v_mfma_f32_16x16x32_bf16 v[24:27], v[8:11], v[184:187], v[212:215]
	s_waitcnt lgkmcnt(1)
	v_mfma_f32_16x16x32_bf16 v[8:11], v[8:11], v[208:211], v[36:39]
	v_mfma_f32_16x16x32_bf16 v[24:27], v[12:15], v[200:203], v[24:27]
	v_mfma_f32_16x16x32_bf16 v[28:31], v[170:173], v[184:187], v[216:219]
	s_waitcnt lgkmcnt(0)
	v_mfma_f32_16x16x32_bf16 v[8:11], v[12:15], v[224:227], v[8:11]
	v_mfma_f32_16x16x32_bf16 v[12:15], v[170:173], v[208:211], v[32:35]
	v_mfma_f32_16x16x32_bf16 v[28:31], v[176:179], v[200:203], v[28:31]
	v_mfma_f32_16x16x32_bf16 v[12:15], v[176:179], v[224:227], v[12:15]
	v_mfma_f32_16x16x32_bf16 v[32:35], v[192:195], v[158:161], v[130:133]
	v_mfma_f32_16x16x32_bf16 v[52:55], v[196:199], v[162:165], v[32:35]
	v_mfma_f32_16x16x32_bf16 v[32:35], v[204:207], v[158:161], v[134:137]
	v_mfma_f32_16x16x32_bf16 v[16:19], v[204:207], v[166:169], v[16:19]
	v_mfma_f32_16x16x32_bf16 v[48:51], v[220:223], v[162:165], v[32:35]
	v_mfma_f32_16x16x32_bf16 v[20:23], v[192:195], v[166:169], v[20:23]
	v_mfma_f32_16x16x32_bf16 v[32:35], v[220:223], v[180:183], v[16:19]
	v_mfma_f32_16x16x32_bf16 v[16:19], v[192:195], v[184:187], v[138:141]
	v_mfma_f32_16x16x32_bf16 v[36:39], v[196:199], v[180:183], v[20:23]
	v_mfma_f32_16x16x32_bf16 v[20:23], v[196:199], v[200:203], v[16:19]
	v_mfma_f32_16x16x32_bf16 v[16:19], v[204:207], v[184:187], v[154:157]
	v_mfma_f32_16x16x32_bf16 v[4:7], v[192:195], v[208:211], v[4:7]
	v_mfma_f32_16x16x32_bf16 v[0:3], v[204:207], v[208:211], v[0:3]
	v_mfma_f32_16x16x32_bf16 v[16:19], v[220:223], v[200:203], v[16:19]
	v_mfma_f32_16x16x32_bf16 v[4:7], v[196:199], v[224:227], v[4:7]
	v_mfma_f32_16x16x32_bf16 v[0:3], v[220:223], v[224:227], v[0:3]
	s_andn2_b64 vcc, exec, s[18:19]
	s_barrier
	s_cbranch_vccnz .LBB0_495
	s_barrier

; #define LDA(dst, b, h)                                                                                               \
;   _Pragma("unroll") for (int m = 0; m < 4; ++m) _Pragma("unroll") for (int k = 0; k < 2; ++k) dst[m][k] =            \
;       *reinterpret_cast<const bf16x8*>(SA(b, h) + lds_byte(wr * 64 + m * 16 + fr, k * 32 + fq * 8))
; #define LDB(dst, b, h)                                                                                               \
;   _Pragma("unroll") for (int n = 0; n < 2; ++n) _Pragma("unroll") for (int k = 0; k < 2; ++k) dst[n][k] =            \
;       *reinterpret_cast<const bf16x8*>(SB(b, h) + lds_byte(wc * 32 + n * 16 + fr, k * 32 + fq * 8))
; #define WAIT_V(n) asm volatile("s_waitcnt vmcnt(" #n ")" ::: "memory")
; #define WAIT_L(n) asm volatile("s_waitcnt lgkmcnt(" #n ")" ::: "memory")
; #define BAR __builtin_amdgcn_s_barrier()
; #define SCHED __builtin_amdgcn_sched_barrier(0)
; template <int EPI>
; __device__ __forceinline__ void gemm_phase(const u16* __restrict__ A, const u16* __restrict__ Bt, const int K,
;                                            const int nN, char* shm, const EpiArgs& ea) {
;     ...
;     for (int t = 0; t < nt - 2; t += 2) {
;       LDB(B0, 0, 0); SCHED; LDA(At, 0, 0); STAGE(SA(1, 1), rA, brow + HALF, t + 1);
;       WAIT_V(10); WAIT_L(8); BAR; WAIT_L(0); MMA(0, 0, At, B0); BAR; SCHED;
;       LDB(B1, 0, 1); STAGE(SB(0, 0), rB, bcol, t + 2);
;       WAIT_V(10); BAR; WAIT_L(0); MMA(0, 1, At, B1); BAR;
;       LDA(At, 0, 1); STAGE(SA(0, 0), rA, brow, t + 2);
;       BAR; WAIT_L(0); MMA(1, 0, At, B0); BAR; SCHED;
;       STAGE(SB(0, 1), rB, bcol + HALF, t + 2);
;       WAIT_V(10); BAR; MMA(1, 1, At, B1); BAR;
.LBB0_565:
	ds_read_b128 v[128:131], v183
	ds_read_b128 v[132:135], v183 offset:1024
	ds_read_b128 v[136:139], v183 offset:2048
	ds_read_b128 v[140:143], v183 offset:3072
	s_add_i32 s64, s58, s63
	s_mov_b32 m0, s46
	s_add_i32 s6, s64, 0x4000
	ds_read_b128 v[144:147], v184
	ds_read_b128 v[148:151], v184 offset:1024
	ds_read_b128 v[152:155], v185
	ds_read_b128 v[156:159], v185 offset:1024
	ds_read_b128 v[160:163], v186
	ds_read_b128 v[164:167], v186 offset:1024
	ds_read_b128 v[168:171], v187
	ds_read_b128 v[192:195], v187 offset:1024
	buffer_load_dwordx4 v175, s[0:3], s6 offen lds
	s_add_i32 s6, s64, 0x6000
	s_mov_b32 m0, s47
	s_nop 0
	buffer_load_dwordx4 v175, s[0:3], s6 offen lds
	s_waitcnt vmcnt(10)
	s_waitcnt lgkmcnt(8)
	s_barrier
	s_waitcnt lgkmcnt(7)
	v_mfma_f32_16x16x32_bf16 v[124:127], v[128:131], v[144:147], v[124:127]
	v_mfma_f32_16x16x32_bf16 v[120:123], v[136:139], v[144:147], v[120:123]
	s_waitcnt lgkmcnt(5)
	v_mfma_f32_16x16x32_bf16 v[116:119], v[128:131], v[152:155], v[116:119]
	v_mfma_f32_16x16x32_bf16 v[112:115], v[136:139], v[152:155], v[112:115]
	s_waitcnt lgkmcnt(3)
	v_mfma_f32_16x16x32_bf16 v[108:111], v[128:131], v[160:163], v[108:111]
	v_mfma_f32_16x16x32_bf16 v[104:107], v[136:139], v[160:163], v[104:107]
	s_waitcnt lgkmcnt(1)
	v_mfma_f32_16x16x32_bf16 v[100:103], v[128:131], v[168:171], v[100:103]
	v_mfma_f32_16x16x32_bf16 v[96:99], v[136:139], v[168:171], v[96:99]
	v_mfma_f32_16x16x32_bf16 v[124:127], v[132:135], v[148:151], v[124:127]
	v_mfma_f32_16x16x32_bf16 v[120:123], v[140:143], v[148:151], v[120:123]
	v_mfma_f32_16x16x32_bf16 v[116:119], v[132:135], v[156:159], v[116:119]
	v_mfma_f32_16x16x32_bf16 v[112:115], v[140:143], v[156:159], v[112:115]
	v_mfma_f32_16x16x32_bf16 v[108:111], v[132:135], v[164:167], v[108:111]
	v_mfma_f32_16x16x32_bf16 v[104:107], v[140:143], v[164:167], v[104:107]
	s_waitcnt lgkmcnt(0)
	v_mfma_f32_16x16x32_bf16 v[100:103], v[132:135], v[192:195], v[100:103]
	v_mfma_f32_16x16x32_bf16 v[96:99], v[140:143], v[192:195], v[96:99]
	s_barrier
	s_add_i32 s65, s61, s63
	s_mov_b32 m0, s30
	s_add_i32 s66, s65, 0x8000
	s_mov_b32 s6, s2
	s_mov_b32 s7, s3
	ds_read_b128 v[196:199], v188
	ds_read_b128 v[200:203], v188 offset:1024
	ds_read_b128 v[204:207], v188 offset:2048
	ds_read_b128 v[208:211], v188 offset:3072
	buffer_load_dwordx4 v175, s[4:7], s66 offen lds
	s_add_i32 s66, s65, 0xa000
	s_mov_b32 m0, s31
	s_nop 0
	buffer_load_dwordx4 v175, s[4:7], s66 offen lds
	s_waitcnt vmcnt(10)
	s_barrier
	s_waitcnt lgkmcnt(3)
	v_mfma_f32_16x16x32_bf16 v[92:95], v[196:199], v[144:147], v[92:95]
	s_waitcnt lgkmcnt(1)
	v_mfma_f32_16x16x32_bf16 v[88:91], v[204:207], v[144:147], v[88:91]
	v_mfma_f32_16x16x32_bf16 v[84:87], v[196:199], v[152:155], v[84:87]
	v_mfma_f32_16x16x32_bf16 v[80:83], v[204:207], v[152:155], v[80:83]
	v_mfma_f32_16x16x32_bf16 v[76:79], v[196:199], v[160:163], v[76:79]
	v_mfma_f32_16x16x32_bf16 v[72:75], v[204:207], v[160:163], v[72:75]
	v_mfma_f32_16x16x32_bf16 v[68:71], v[196:199], v[168:171], v[68:71]
	v_mfma_f32_16x16x32_bf16 v[64:67], v[204:207], v[168:171], v[64:67]
	v_mfma_f32_16x16x32_bf16 v[92:95], v[200:203], v[148:151], v[92:95]
	s_waitcnt lgkmcnt(0)
	v_mfma_f32_16x16x32_bf16 v[88:91], v[208:211], v[148:151], v[88:91]
	v_mfma_f32_16x16x32_bf16 v[84:87], v[200:203], v[156:159], v[84:87]
	v_mfma_f32_16x16x32_bf16 v[80:83], v[208:211], v[156:159], v[80:83]
	v_mfma_f32_16x16x32_bf16 v[76:79], v[200:203], v[164:167], v[76:79]
	v_mfma_f32_16x16x32_bf16 v[72:75], v[208:211], v[164:167], v[72:75]
	v_mfma_f32_16x16x32_bf16 v[68:71], v[200:203], v[192:195], v[68:71]
	v_mfma_f32_16x16x32_bf16 v[64:67], v[208:211], v[192:195], v[64:67]
	s_add_i32 s66, s60, s63
	s_mov_b32 m0, s33
	s_add_i32 s67, s66, 0x8000
	s_barrier
	ds_read_b128 v[144:147], v184 offset:16384
	ds_read_b128 v[148:151], v184 offset:17408
	ds_read_b128 v[152:155], v185 offset:16384
	ds_read_b128 v[156:159], v185 offset:17408
	ds_read_b128 v[160:163], v186 offset:16384
	ds_read_b128 v[164:167], v186 offset:17408
	ds_read_b128 v[168:171], v187 offset:16384
	ds_read_b128 v[192:195], v187 offset:17408
	buffer_load_dwordx4 v175, s[0:3], s67 offen lds
	s_add_i32 s67, s66, 0xa000
	s_mov_b32 m0, s34
	s_nop 0
	buffer_load_dwordx4 v175, s[0:3], s67 offen lds
	s_barrier
	s_waitcnt lgkmcnt(7)
	v_mfma_f32_16x16x32_bf16 v[60:63], v[128:131], v[144:147], v[60:63]
	v_mfma_f32_16x16x32_bf16 v[56:59], v[136:139], v[144:147], v[56:59]
	s_waitcnt lgkmcnt(5)
	v_mfma_f32_16x16x32_bf16 v[52:55], v[128:131], v[152:155], v[52:55]
	v_mfma_f32_16x16x32_bf16 v[48:51], v[136:139], v[152:155], v[48:51]
	s_waitcnt lgkmcnt(3)
	v_mfma_f32_16x16x32_bf16 v[44:47], v[128:131], v[160:163], v[44:47]
	v_mfma_f32_16x16x32_bf16 v[40:43], v[136:139], v[160:163], v[40:43]
	s_waitcnt lgkmcnt(1)
	v_mfma_f32_16x16x32_bf16 v[36:39], v[128:131], v[168:171], v[36:39]
	v_mfma_f32_16x16x32_bf16 v[32:35], v[136:139], v[168:171], v[32:35]
	v_mfma_f32_16x16x32_bf16 v[60:63], v[132:135], v[148:151], v[60:63]
	v_mfma_f32_16x16x32_bf16 v[56:59], v[140:143], v[148:151], v[56:59]
	v_mfma_f32_16x16x32_bf16 v[52:55], v[132:135], v[156:159], v[52:55]
	v_mfma_f32_16x16x32_bf16 v[48:51], v[140:143], v[156:159], v[48:51]
	v_mfma_f32_16x16x32_bf16 v[44:47], v[132:135], v[164:167], v[44:47]
	v_mfma_f32_16x16x32_bf16 v[40:43], v[140:143], v[164:167], v[40:43]
	s_waitcnt lgkmcnt(0)
	v_mfma_f32_16x16x32_bf16 v[36:39], v[132:135], v[192:195], v[36:39]
	v_mfma_f32_16x16x32_bf16 v[32:35], v[140:143], v[192:195], v[32:35]
	s_barrier
	s_add_i32 s67, s59, s63
	s_mov_b32 m0, s35
	s_add_i32 s68, s67, 0x8000
	buffer_load_dwordx4 v175, s[4:7], s68 offen lds
	s_add_i32 s68, s67, 0xa000
	s_mov_b32 m0, s36
	s_nop 0
	buffer_load_dwordx4 v175, s[4:7], s68 offen lds
	s_waitcnt vmcnt(10)
	s_barrier
; #define LDA(dst, b, h)                                                                                               \
;   _Pragma("unroll") for (int m = 0; m < 4; ++m) _Pragma("unroll") for (int k = 0; k < 2; ++k) dst[m][k] =            \
;       *reinterpret_cast<const bf16x8*>(SA(b, h) + lds_byte(wr * 64 + m * 16 + fr, k * 32 + fq * 8))
; #define LDB(dst, b, h)                                                                                               \
;   _Pragma("unroll") for (int n = 0; n < 2; ++n) _Pragma("unroll") for (int k = 0; k < 2; ++k) dst[n][k] =            \
;       *reinterpret_cast<const bf16x8*>(SB(b, h) + lds_byte(wc * 32 + n * 16 + fr, k * 32 + fq * 8))
; #define WAIT_V(n) asm volatile("s_waitcnt vmcnt(" #n ")" ::: "memory")
; #define WAIT_L(n) asm volatile("s_waitcnt lgkmcnt(" #n ")" ::: "memory")
; #define BAR __builtin_amdgcn_s_barrier()
; #define SCHED __builtin_amdgcn_sched_barrier(0)
; template <int EPI>
; __device__ __forceinline__ void gemm_phase(const u16* __restrict__ A, const u16* __restrict__ Bt, const int K,
;                                            const int nN, char* shm, const EpiArgs& ea) {
;     ...
;       WAIT_V(10); BAR; MMA(1, 1, At, B1); BAR;
;       LDB(B0, 1, 0); SCHED; LDA(At, 1, 0); STAGE(SA(0, 1), rA, brow + HALF, t + 2);
;       WAIT_V(10); WAIT_L(8); BAR; WAIT_L(0); MMA(0, 0, At, B0); BAR; SCHED;
;       LDB(B1, 1, 1); STAGE(SB(1, 0), rB, bcol, t + 3);
	v_mfma_f32_16x16x32_bf16 v[28:31], v[196:199], v[144:147], v[28:31]
	v_mfma_f32_16x16x32_bf16 v[24:27], v[204:207], v[144:147], v[24:27]
	v_mfma_f32_16x16x32_bf16 v[20:23], v[196:199], v[152:155], v[20:23]
	v_mfma_f32_16x16x32_bf16 v[16:19], v[204:207], v[152:155], v[16:19]
	v_mfma_f32_16x16x32_bf16 v[12:15], v[196:199], v[160:163], v[12:15]
	v_mfma_f32_16x16x32_bf16 v[8:11], v[204:207], v[160:163], v[8:11]
	v_mfma_f32_16x16x32_bf16 v[4:7], v[196:199], v[168:171], v[4:7]
	v_mfma_f32_16x16x32_bf16 v[0:3], v[204:207], v[168:171], v[0:3]
	v_mfma_f32_16x16x32_bf16 v[28:31], v[200:203], v[148:151], v[28:31]
	v_mfma_f32_16x16x32_bf16 v[24:27], v[208:211], v[148:151], v[24:27]
	v_mfma_f32_16x16x32_bf16 v[20:23], v[200:203], v[156:159], v[20:23]
	v_mfma_f32_16x16x32_bf16 v[16:19], v[208:211], v[156:159], v[16:19]
	v_mfma_f32_16x16x32_bf16 v[12:15], v[200:203], v[164:167], v[12:15]
	v_mfma_f32_16x16x32_bf16 v[8:11], v[208:211], v[164:167], v[8:11]
	v_mfma_f32_16x16x32_bf16 v[4:7], v[200:203], v[192:195], v[4:7]
	v_mfma_f32_16x16x32_bf16 v[0:3], v[208:211], v[192:195], v[0:3]
	s_barrier
	ds_read_b128 v[128:131], v189
	ds_read_b128 v[132:135], v189 offset:1024
	ds_read_b128 v[136:139], v189 offset:2048
	ds_read_b128 v[140:143], v189 offset:3072
	s_mov_b32 m0, s37
	s_add_i32 s68, s64, 0x8000
	ds_read_b128 v[144:147], v184 offset:32768
	ds_read_b128 v[148:151], v184 offset:33792
	ds_read_b128 v[152:155], v185 offset:32768
	ds_read_b128 v[156:159], v185 offset:33792
	ds_read_b128 v[160:163], v186 offset:32768
	ds_read_b128 v[164:167], v186 offset:33792
	ds_read_b128 v[168:171], v187 offset:32768
	ds_read_b128 v[192:195], v187 offset:33792
	buffer_load_dwordx4 v175, s[0:3], s68 offen lds
	s_add_i32 s64, s64, 0xa000
	s_mov_b32 m0, s38
	s_nop 0
	buffer_load_dwordx4 v175, s[0:3], s64 offen lds
	s_waitcnt vmcnt(10)
	s_waitcnt lgkmcnt(8)
	s_barrier
	s_waitcnt lgkmcnt(7)
	v_mfma_f32_16x16x32_bf16 v[124:127], v[128:131], v[144:147], v[124:127]
	v_mfma_f32_16x16x32_bf16 v[120:123], v[136:139], v[144:147], v[120:123]
	s_waitcnt lgkmcnt(5)
	v_mfma_f32_16x16x32_bf16 v[116:119], v[128:131], v[152:155], v[116:119]
	v_mfma_f32_16x16x32_bf16 v[112:115], v[136:139], v[152:155], v[112:115]
	s_waitcnt lgkmcnt(3)
	v_mfma_f32_16x16x32_bf16 v[108:111], v[128:131], v[160:163], v[108:111]
	v_mfma_f32_16x16x32_bf16 v[104:107], v[136:139], v[160:163], v[104:107]
	s_waitcnt lgkmcnt(1)
	v_mfma_f32_16x16x32_bf16 v[100:103], v[128:131], v[168:171], v[100:103]
	v_mfma_f32_16x16x32_bf16 v[96:99], v[136:139], v[168:171], v[96:99]
	v_mfma_f32_16x16x32_bf16 v[124:127], v[132:135], v[148:151], v[124:127]
	v_mfma_f32_16x16x32_bf16 v[120:123], v[140:143], v[148:151], v[120:123]
	v_mfma_f32_16x16x32_bf16 v[116:119], v[132:135], v[156:159], v[116:119]
	v_mfma_f32_16x16x32_bf16 v[112:115], v[140:143], v[156:159], v[112:115]
	v_mfma_f32_16x16x32_bf16 v[108:111], v[132:135], v[164:167], v[108:111]
	v_mfma_f32_16x16x32_bf16 v[104:107], v[140:143], v[164:167], v[104:107]
	s_waitcnt lgkmcnt(0)
	v_mfma_f32_16x16x32_bf16 v[100:103], v[132:135], v[192:195], v[100:103]
	v_mfma_f32_16x16x32_bf16 v[96:99], v[140:143], v[192:195], v[96:99]
	s_barrier
	s_mov_b32 m0, s39
	s_add_i32 s64, s65, 0xc000
	ds_read_b128 v[196:199], v190
	ds_read_b128 v[200:203], v190 offset:1024
	ds_read_b128 v[204:207], v190 offset:2048
	ds_read_b128 v[208:211], v190 offset:3072
	buffer_load_dwordx4 v175, s[4:7], s64 offen lds
	s_add_i32 s65, s65, 0xe000
	s_mov_b32 m0, s40
	s_nop 0
	buffer_load_dwordx4 v175, s[4:7], s65 offen lds
	s_waitcnt vmcnt(10)
	s_barrier
; #define LDA(dst, b, h)                                                                                               \
;   _Pragma("unroll") for (int m = 0; m < 4; ++m) _Pragma("unroll") for (int k = 0; k < 2; ++k) dst[m][k] =            \
;       *reinterpret_cast<const bf16x8*>(SA(b, h) + lds_byte(wr * 64 + m * 16 + fr, k * 32 + fq * 8))
; #define WAIT_V(n) asm volatile("s_waitcnt vmcnt(" #n ")" ::: "memory")
; #define WAIT_L(n) asm volatile("s_waitcnt lgkmcnt(" #n ")" ::: "memory")
; #define BAR __builtin_amdgcn_s_barrier()
; #define SCHED __builtin_amdgcn_sched_barrier(0)
; template <int EPI>
; __device__ __forceinline__ void gemm_phase(const u16* __restrict__ A, const u16* __restrict__ Bt, const int K,
;                                            const int nN, char* shm, const EpiArgs& ea) {
;     ...
;       WAIT_V(10); BAR; WAIT_L(0); MMA(0, 1, At, B1); BAR;
;       LDA(At, 1, 1); STAGE(SA(1, 0), rA, brow, t + 3);
;       BAR; WAIT_L(0); MMA(1, 0, At, B0); BAR; SCHED;
;       STAGE(SB(1, 1), rB, bcol + HALF, t + 3);
;       WAIT_V(10); BAR; MMA(1, 1, At, B1); BAR;
;     }
;     float eC = 0.f, eB = 0.f;
;     float2 eS = make_float2(0.f, 0.f);
;     if (EPI == EPI_IN || EPI == EPI_SWIGLU_LN) {
;       if (wr == 0) {
;         eC = ea.c1[bcol + tid];
;         eS = *(const float2*)(ea.st_in + (size_t)(brow + tid) * 2);
;       } else {
;         eC = ea.c2[bcol + tid - 256];
;         if (EPI == EPI_IN) eB = ea.bias[bcol + tid - 256];
;       }
	s_waitcnt lgkmcnt(3)
	v_mfma_f32_16x16x32_bf16 v[92:95], v[196:199], v[144:147], v[92:95]
	s_waitcnt lgkmcnt(1)
	v_mfma_f32_16x16x32_bf16 v[88:91], v[204:207], v[144:147], v[88:91]
	v_mfma_f32_16x16x32_bf16 v[84:87], v[196:199], v[152:155], v[84:87]
	v_mfma_f32_16x16x32_bf16 v[80:83], v[204:207], v[152:155], v[80:83]
	v_mfma_f32_16x16x32_bf16 v[76:79], v[196:199], v[160:163], v[76:79]
	v_mfma_f32_16x16x32_bf16 v[72:75], v[204:207], v[160:163], v[72:75]
	v_mfma_f32_16x16x32_bf16 v[68:71], v[196:199], v[168:171], v[68:71]
	v_mfma_f32_16x16x32_bf16 v[64:67], v[204:207], v[168:171], v[64:67]
	v_mfma_f32_16x16x32_bf16 v[92:95], v[200:203], v[148:151], v[92:95]
	s_waitcnt lgkmcnt(0)
	v_mfma_f32_16x16x32_bf16 v[88:91], v[208:211], v[148:151], v[88:91]
	v_mfma_f32_16x16x32_bf16 v[84:87], v[200:203], v[156:159], v[84:87]
	v_mfma_f32_16x16x32_bf16 v[80:83], v[208:211], v[156:159], v[80:83]
	v_mfma_f32_16x16x32_bf16 v[76:79], v[200:203], v[164:167], v[76:79]
	v_mfma_f32_16x16x32_bf16 v[72:75], v[208:211], v[164:167], v[72:75]
	v_mfma_f32_16x16x32_bf16 v[68:71], v[200:203], v[192:195], v[68:71]
	v_mfma_f32_16x16x32_bf16 v[64:67], v[208:211], v[192:195], v[64:67]
	s_mov_b32 m0, s41
	s_add_i32 s64, s66, 0xc000
	s_barrier
	ds_read_b128 v[144:147], v184 offset:49152
	ds_read_b128 v[148:151], v184 offset:50176
	ds_read_b128 v[152:155], v185 offset:49152
	ds_read_b128 v[156:159], v185 offset:50176
	ds_read_b128 v[160:163], v186 offset:49152
	ds_read_b128 v[164:167], v186 offset:50176
	ds_read_b128 v[168:171], v187 offset:49152
	ds_read_b128 v[192:195], v187 offset:50176
	buffer_load_dwordx4 v175, s[0:3], s64 offen lds
	s_add_i32 s66, s66, 0xe000
	s_mov_b32 m0, s42
	s_nop 0
	buffer_load_dwordx4 v175, s[0:3], s66 offen lds
	s_barrier
	s_waitcnt lgkmcnt(7)
	v_mfma_f32_16x16x32_bf16 v[60:63], v[128:131], v[144:147], v[60:63]
	v_mfma_f32_16x16x32_bf16 v[56:59], v[136:139], v[144:147], v[56:59]
	s_waitcnt lgkmcnt(5)
	v_mfma_f32_16x16x32_bf16 v[52:55], v[128:131], v[152:155], v[52:55]
	v_mfma_f32_16x16x32_bf16 v[48:51], v[136:139], v[152:155], v[48:51]
	s_waitcnt lgkmcnt(3)
	v_mfma_f32_16x16x32_bf16 v[44:47], v[128:131], v[160:163], v[44:47]
	v_mfma_f32_16x16x32_bf16 v[40:43], v[136:139], v[160:163], v[40:43]
	s_waitcnt lgkmcnt(1)
	v_mfma_f32_16x16x32_bf16 v[36:39], v[128:131], v[168:171], v[36:39]
	v_mfma_f32_16x16x32_bf16 v[32:35], v[136:139], v[168:171], v[32:35]
	v_mfma_f32_16x16x32_bf16 v[60:63], v[132:135], v[148:151], v[60:63]
	v_mfma_f32_16x16x32_bf16 v[56:59], v[140:143], v[148:151], v[56:59]
	v_mfma_f32_16x16x32_bf16 v[52:55], v[132:135], v[156:159], v[52:55]
	v_mfma_f32_16x16x32_bf16 v[48:51], v[140:143], v[156:159], v[48:51]
	v_mfma_f32_16x16x32_bf16 v[44:47], v[132:135], v[164:167], v[44:47]
	v_mfma_f32_16x16x32_bf16 v[40:43], v[140:143], v[164:167], v[40:43]
	s_waitcnt lgkmcnt(0)
	v_mfma_f32_16x16x32_bf16 v[36:39], v[132:135], v[192:195], v[36:39]
	v_mfma_f32_16x16x32_bf16 v[32:35], v[140:143], v[192:195], v[32:35]
	s_barrier
	s_mov_b32 m0, s43
	s_add_i32 s64, s67, 0xc000
	buffer_load_dwordx4 v175, s[4:7], s64 offen lds
	s_add_i32 s67, s67, 0xe000
	s_mov_b32 m0, s44
	s_nop 0
	buffer_load_dwordx4 v175, s[4:7], s67 offen lds
	s_waitcnt vmcnt(10)
	s_barrier
	v_mfma_f32_16x16x32_bf16 v[28:31], v[196:199], v[144:147], v[28:31]
	v_mfma_f32_16x16x32_bf16 v[24:27], v[204:207], v[144:147], v[24:27]
	v_mfma_f32_16x16x32_bf16 v[20:23], v[196:199], v[152:155], v[20:23]
	v_mfma_f32_16x16x32_bf16 v[16:19], v[204:207], v[152:155], v[16:19]
	v_mfma_f32_16x16x32_bf16 v[12:15], v[196:199], v[160:163], v[12:15]
	v_mfma_f32_16x16x32_bf16 v[8:11], v[204:207], v[160:163], v[8:11]
	v_mfma_f32_16x16x32_bf16 v[4:7], v[196:199], v[168:171], v[4:7]
	v_mfma_f32_16x16x32_bf16 v[0:3], v[204:207], v[168:171], v[0:3]
	v_mfma_f32_16x16x32_bf16 v[28:31], v[200:203], v[148:151], v[28:31]
	v_mfma_f32_16x16x32_bf16 v[24:27], v[208:211], v[148:151], v[24:27]
	v_mfma_f32_16x16x32_bf16 v[20:23], v[200:203], v[156:159], v[20:23]
	v_mfma_f32_16x16x32_bf16 v[16:19], v[208:211], v[156:159], v[16:19]
	v_mfma_f32_16x16x32_bf16 v[12:15], v[200:203], v[164:167], v[12:15]
	v_mfma_f32_16x16x32_bf16 v[8:11], v[208:211], v[164:167], v[8:11]
	v_mfma_f32_16x16x32_bf16 v[4:7], v[200:203], v[192:195], v[4:7]
	v_mfma_f32_16x16x32_bf16 v[0:3], v[208:211], v[192:195], v[0:3]
	s_add_i32 s62, s62, 2
	s_add_i32 s63, s63, 0x8000
	s_cmp_lt_u32 s62, 28
	s_barrier
	s_cbranch_scc1 .LBB0_565
	v_add_u32_e32 v128, s57, v174
	v_ashrrev_i32_e32 v129, 31, v128
	s_mov_b64 s[6:7], -1
	s_and_b64 vcc, exec, s[18:19]
	s_cbranch_vccz .LBB0_568
	v_lshl_add_u64 v[130:131], v[128:129], 2, s[90:91]
	v_lshl_add_u64 v[130:131], v[130:131], 0, s[20:21]
	s_mov_b64 s[6:7], 0

; #define LDA(dst, b, h)                                                                                               \
;   _Pragma("unroll") for (int m = 0; m < 4; ++m) _Pragma("unroll") for (int k = 0; k < 2; ++k) dst[m][k] =            \
;       *reinterpret_cast<const bf16x8*>(SA(b, h) + lds_byte(wr * 64 + m * 16 + fr, k * 32 + fq * 8))
; #define LDB(dst, b, h)                                                                                               \
;   _Pragma("unroll") for (int n = 0; n < 2; ++n) _Pragma("unroll") for (int k = 0; k < 2; ++k) dst[n][k] =            \
;       *reinterpret_cast<const bf16x8*>(SB(b, h) + lds_byte(wc * 32 + n * 16 + fr, k * 32 + fq * 8))
; #define WAIT_V(n) asm volatile("s_waitcnt vmcnt(" #n ")" ::: "memory")
; #define WAIT_L(n) asm volatile("s_waitcnt lgkmcnt(" #n ")" ::: "memory")
; #define BAR __builtin_amdgcn_s_barrier()
; template <int EPI>
; __device__ __forceinline__ void gemm_phase(const u16* __restrict__ A, const u16* __restrict__ Bt, const int K,
;                                            const int nN, char* shm, const EpiArgs& ea) {
;     ...
;       LDB(B0, 0, 0); LDA(At, 0, 0); STAGE(SA(1, 1), rA, brow + HALF, nt - 1);
;       WAIT_V(10); BAR; WAIT_L(0); MMA(0, 0, At, B0); BAR;
;       LDB(B1, 0, 1); WAIT_V(8); BAR; WAIT_L(0); MMA(0, 1, At, B1); BAR;
;       LDA(At, 0, 1); WAIT_V(4); BAR; WAIT_L(0); MMA(1, 0, At, B0); MMA(1, 1, At, B1); BAR;
.LBB0_570:
	s_mov_b32 m0, s46
	s_add_i32 s6, s58, 0x7c000
	global_load_dword v154, v[130:131], off
	ds_read_b128 v[128:131], v183
	ds_read_b128 v[132:135], v183 offset:1024
	ds_read_b128 v[136:139], v183 offset:2048
	ds_read_b128 v[140:143], v183 offset:3072
	ds_read_b128 v[144:147], v184
	ds_read_b128 v[148:151], v184 offset:1024
	ds_read_b128 v[156:159], v185
	ds_read_b128 v[160:163], v185 offset:1024
	ds_read_b128 v[164:167], v186
	ds_read_b128 v[168:171], v186 offset:1024
	ds_read_b128 v[192:195], v187
	ds_read_b128 v[196:199], v187 offset:1024
	buffer_load_dwordx4 v175, s[0:3], s6 offen lds
	s_add_i32 s58, s58, 0x7e000
	s_mov_b32 m0, s47
	s_nop 0
	buffer_load_dwordx4 v175, s[0:3], s58 offen lds
	s_waitcnt vmcnt(10)
	s_barrier
	s_waitcnt lgkmcnt(7)
	v_mfma_f32_16x16x32_bf16 v[124:127], v[128:131], v[144:147], v[124:127]
	v_mfma_f32_16x16x32_bf16 v[120:123], v[136:139], v[144:147], v[120:123]
	s_waitcnt lgkmcnt(5)
	v_mfma_f32_16x16x32_bf16 v[116:119], v[128:131], v[156:159], v[116:119]
	v_mfma_f32_16x16x32_bf16 v[112:115], v[136:139], v[156:159], v[112:115]
	s_waitcnt lgkmcnt(3)
	v_mfma_f32_16x16x32_bf16 v[108:111], v[128:131], v[164:167], v[108:111]
	v_mfma_f32_16x16x32_bf16 v[104:107], v[136:139], v[164:167], v[104:107]
	s_waitcnt lgkmcnt(1)
	v_mfma_f32_16x16x32_bf16 v[100:103], v[128:131], v[192:195], v[100:103]
	v_mfma_f32_16x16x32_bf16 v[96:99], v[136:139], v[192:195], v[96:99]
	v_mfma_f32_16x16x32_bf16 v[124:127], v[132:135], v[148:151], v[124:127]
	v_mfma_f32_16x16x32_bf16 v[120:123], v[140:143], v[148:151], v[120:123]
	v_mfma_f32_16x16x32_bf16 v[116:119], v[132:135], v[160:163], v[116:119]
	v_mfma_f32_16x16x32_bf16 v[112:115], v[140:143], v[160:163], v[112:115]
	v_mfma_f32_16x16x32_bf16 v[108:111], v[132:135], v[168:171], v[108:111]
	v_mfma_f32_16x16x32_bf16 v[104:107], v[140:143], v[168:171], v[104:107]
	s_waitcnt lgkmcnt(0)
	v_mfma_f32_16x16x32_bf16 v[100:103], v[132:135], v[196:199], v[100:103]
	v_mfma_f32_16x16x32_bf16 v[96:99], v[140:143], v[196:199], v[96:99]
	s_barrier
	ds_read_b128 v[200:203], v188
	ds_read_b128 v[204:207], v188 offset:1024
	ds_read_b128 v[208:211], v188 offset:2048
	ds_read_b128 v[212:215], v188 offset:3072
	s_waitcnt vmcnt(8)
	s_barrier
	s_waitcnt lgkmcnt(3)
	v_mfma_f32_16x16x32_bf16 v[92:95], v[200:203], v[144:147], v[92:95]
	s_waitcnt lgkmcnt(1)
	v_mfma_f32_16x16x32_bf16 v[88:91], v[208:211], v[144:147], v[88:91]
	v_mfma_f32_16x16x32_bf16 v[84:87], v[200:203], v[156:159], v[84:87]
	v_mfma_f32_16x16x32_bf16 v[80:83], v[208:211], v[156:159], v[80:83]
	v_mfma_f32_16x16x32_bf16 v[76:79], v[200:203], v[164:167], v[76:79]
	v_mfma_f32_16x16x32_bf16 v[72:75], v[208:211], v[164:167], v[72:75]
	v_mfma_f32_16x16x32_bf16 v[68:71], v[200:203], v[192:195], v[68:71]
	v_mfma_f32_16x16x32_bf16 v[92:95], v[204:207], v[148:151], v[92:95]
	s_waitcnt lgkmcnt(0)
	v_mfma_f32_16x16x32_bf16 v[88:91], v[212:215], v[148:151], v[88:91]
	v_mfma_f32_16x16x32_bf16 v[84:87], v[204:207], v[160:163], v[84:87]
	v_mfma_f32_16x16x32_bf16 v[80:83], v[212:215], v[160:163], v[80:83]
	v_mfma_f32_16x16x32_bf16 v[76:79], v[204:207], v[168:171], v[76:79]
	v_mfma_f32_16x16x32_bf16 v[72:75], v[212:215], v[168:171], v[72:75]
	v_mfma_f32_16x16x32_bf16 v[68:71], v[204:207], v[196:199], v[68:71]
	v_mfma_f32_16x16x32_bf16 v[64:67], v[208:211], v[192:195], v[64:67]
	v_mfma_f32_16x16x32_bf16 v[64:67], v[212:215], v[196:199], v[64:67]
	s_barrier
	ds_read_b128 v[144:147], v184 offset:16384
	ds_read_b128 v[148:151], v184 offset:17408
	ds_read_b128 v[156:159], v185 offset:16384
	ds_read_b128 v[160:163], v185 offset:17408
	ds_read_b128 v[164:167], v186 offset:16384
	ds_read_b128 v[168:171], v186 offset:17408
	ds_read_b128 v[192:195], v187 offset:16384
	ds_read_b128 v[196:199], v187 offset:17408
	s_waitcnt vmcnt(4)
	s_barrier
	s_waitcnt lgkmcnt(3)
	v_mfma_f32_16x16x32_bf16 v[40:43], v[136:139], v[164:167], v[40:43]
	s_waitcnt lgkmcnt(1)
	v_mfma_f32_16x16x32_bf16 v[36:39], v[128:131], v[192:195], v[36:39]
	v_mfma_f32_16x16x32_bf16 v[60:63], v[128:131], v[144:147], v[60:63]
	v_mfma_f32_16x16x32_bf16 v[56:59], v[136:139], v[144:147], v[56:59]
	v_mfma_f32_16x16x32_bf16 v[52:55], v[128:131], v[156:159], v[52:55]
	v_mfma_f32_16x16x32_bf16 v[48:51], v[136:139], v[156:159], v[48:51]
	v_mfma_f32_16x16x32_bf16 v[44:47], v[128:131], v[164:167], v[44:47]
	v_mfma_f32_16x16x32_bf16 v[40:43], v[140:143], v[168:171], v[40:43]
	s_waitcnt lgkmcnt(0)
	v_mfma_f32_16x16x32_bf16 v[36:39], v[132:135], v[196:199], v[36:39]
	v_mfma_f32_16x16x32_bf16 v[32:35], v[136:139], v[192:195], v[32:35]
	v_mfma_f32_16x16x32_bf16 v[60:63], v[132:135], v[148:151], v[60:63]
	v_mfma_f32_16x16x32_bf16 v[56:59], v[140:143], v[148:151], v[56:59]
	v_mfma_f32_16x16x32_bf16 v[52:55], v[132:135], v[160:163], v[52:55]
	v_mfma_f32_16x16x32_bf16 v[48:51], v[140:143], v[160:163], v[48:51]
	v_mfma_f32_16x16x32_bf16 v[44:47], v[132:135], v[168:171], v[44:47]
	v_mfma_f32_16x16x32_bf16 v[32:35], v[140:143], v[196:199], v[32:35]
	v_mfma_f32_16x16x32_bf16 v[12:15], v[200:203], v[164:167], v[12:15]
	v_mfma_f32_16x16x32_bf16 v[8:11], v[208:211], v[164:167], v[8:11]
	v_mfma_f32_16x16x32_bf16 v[4:7], v[200:203], v[192:195], v[4:7]
	v_mfma_f32_16x16x32_bf16 v[0:3], v[208:211], v[192:195], v[0:3]
	v_mfma_f32_16x16x32_bf16 v[28:31], v[200:203], v[144:147], v[28:31]
	v_mfma_f32_16x16x32_bf16 v[24:27], v[208:211], v[144:147], v[24:27]
	v_mfma_f32_16x16x32_bf16 v[20:23], v[200:203], v[156:159], v[20:23]
	v_mfma_f32_16x16x32_bf16 v[16:19], v[208:211], v[156:159], v[16:19]
	v_mfma_f32_16x16x32_bf16 v[12:15], v[204:207], v[168:171], v[12:15]
	v_mfma_f32_16x16x32_bf16 v[8:11], v[212:215], v[168:171], v[8:11]
	v_mfma_f32_16x16x32_bf16 v[4:7], v[204:207], v[196:199], v[4:7]
	v_mfma_f32_16x16x32_bf16 v[0:3], v[212:215], v[196:199], v[0:3]
	v_mfma_f32_16x16x32_bf16 v[216:219], v[204:207], v[148:151], v[28:31]
	v_mfma_f32_16x16x32_bf16 v[220:223], v[212:215], v[148:151], v[24:27]
	v_mfma_f32_16x16x32_bf16 v[224:227], v[204:207], v[160:163], v[20:23]
	v_mfma_f32_16x16x32_bf16 v[160:163], v[212:215], v[160:163], v[16:19]
	s_barrier
; #define LDA(dst, b, h)                                                                                               \
;   _Pragma("unroll") for (int m = 0; m < 4; ++m) _Pragma("unroll") for (int k = 0; k < 2; ++k) dst[m][k] =            \
;       *reinterpret_cast<const bf16x8*>(SA(b, h) + lds_byte(wr * 64 + m * 16 + fr, k * 32 + fq * 8))
; #define LDB(dst, b, h)                                                                                               \
;   _Pragma("unroll") for (int n = 0; n < 2; ++n) _Pragma("unroll") for (int k = 0; k < 2; ++k) dst[n][k] =            \
;       *reinterpret_cast<const bf16x8*>(SB(b, h) + lds_byte(wc * 32 + n * 16 + fr, k * 32 + fq * 8))
; #define WAIT_V(n) asm volatile("s_waitcnt vmcnt(" #n ")" ::: "memory")
; #define WAIT_L(n) asm volatile("s_waitcnt lgkmcnt(" #n ")" ::: "memory")
; #define BAR __builtin_amdgcn_s_barrier()
; template <int EPI>
; __device__ __forceinline__ void gemm_phase(const u16* __restrict__ A, const u16* __restrict__ Bt, const int K,
;                                            const int nN, char* shm, const EpiArgs& ea) {
;     ...
;       LDB(B0, 1, 0); LDA(At, 1, 0); WAIT_V(2); BAR; WAIT_L(0); MMA(0, 0, At, B0); BAR;
;       LDB(B1, 1, 1); WAIT_V(0); BAR; WAIT_L(0); MMA(0, 1, At, B1); BAR;
;       LDA(At, 1, 1); BAR; WAIT_L(0); MMA(1, 0, At, B0); MMA(1, 1, At, B1); BAR;
;     }
;     if (wr == 0) BAR;
	s_nop 0
	ds_read_b128 v[16:19], v189
	ds_read_b128 v[20:23], v189 offset:1024
	ds_read_b128 v[164:167], v189 offset:2048
	ds_read_b128 v[168:171], v189 offset:3072
	ds_read_b128 v[24:27], v184 offset:32768
	ds_read_b128 v[28:31], v184 offset:33792
	ds_read_b128 v[192:195], v185 offset:32768
	ds_read_b128 v[196:199], v185 offset:33792
	ds_read_b128 v[200:203], v186 offset:32768
	ds_read_b128 v[204:207], v186 offset:33792
	ds_read_b128 v[208:211], v187 offset:32768
	ds_read_b128 v[212:215], v187 offset:33792
	s_waitcnt vmcnt(2)
	s_barrier
	s_waitcnt lgkmcnt(7)
	v_mfma_f32_16x16x32_bf16 v[124:127], v[16:19], v[24:27], v[124:127]
	v_mfma_f32_16x16x32_bf16 v[120:123], v[164:167], v[24:27], v[120:123]
	s_waitcnt lgkmcnt(5)
	v_mfma_f32_16x16x32_bf16 v[116:119], v[16:19], v[192:195], v[116:119]
	v_mfma_f32_16x16x32_bf16 v[112:115], v[164:167], v[192:195], v[112:115]
	s_waitcnt lgkmcnt(3)
	v_mfma_f32_16x16x32_bf16 v[108:111], v[16:19], v[200:203], v[108:111]
	v_mfma_f32_16x16x32_bf16 v[104:107], v[164:167], v[200:203], v[104:107]
	s_waitcnt lgkmcnt(1)
	v_mfma_f32_16x16x32_bf16 v[100:103], v[16:19], v[208:211], v[100:103]
	v_mfma_f32_16x16x32_bf16 v[96:99], v[164:167], v[208:211], v[96:99]
	v_mfma_f32_16x16x32_bf16 v[156:159], v[20:23], v[28:31], v[124:127]
	v_mfma_f32_16x16x32_bf16 v[148:151], v[168:171], v[28:31], v[120:123]
	v_mfma_f32_16x16x32_bf16 v[144:147], v[20:23], v[196:199], v[116:119]
	v_mfma_f32_16x16x32_bf16 v[140:143], v[168:171], v[196:199], v[112:115]
	v_mfma_f32_16x16x32_bf16 v[120:123], v[20:23], v[204:207], v[108:111]
	v_mfma_f32_16x16x32_bf16 v[116:119], v[168:171], v[204:207], v[104:107]
	s_waitcnt lgkmcnt(0)
	v_mfma_f32_16x16x32_bf16 v[112:115], v[20:23], v[212:215], v[100:103]
	v_mfma_f32_16x16x32_bf16 v[108:111], v[168:171], v[212:215], v[96:99]
	s_barrier
	ds_read_b128 v[228:231], v190
	ds_read_b128 v[232:235], v190 offset:1024
	ds_read_b128 v[236:239], v190 offset:2048
	ds_read_b128 v[240:243], v190 offset:3072
	s_waitcnt vmcnt(0)
	s_barrier
	s_waitcnt lgkmcnt(3)
	v_mfma_f32_16x16x32_bf16 v[92:95], v[228:231], v[24:27], v[92:95]
	s_waitcnt lgkmcnt(1)
	v_mfma_f32_16x16x32_bf16 v[24:27], v[236:239], v[24:27], v[88:91]
	s_waitcnt lgkmcnt(0)
	v_mfma_f32_16x16x32_bf16 v[132:135], v[240:243], v[28:31], v[24:27]
	v_mfma_f32_16x16x32_bf16 v[24:27], v[228:231], v[192:195], v[84:87]
	v_mfma_f32_16x16x32_bf16 v[128:131], v[232:235], v[196:199], v[24:27]
	v_mfma_f32_16x16x32_bf16 v[24:27], v[236:239], v[192:195], v[80:83]
	v_mfma_f32_16x16x32_bf16 v[124:127], v[240:243], v[196:199], v[24:27]
	v_mfma_f32_16x16x32_bf16 v[24:27], v[228:231], v[200:203], v[76:79]
	v_mfma_f32_16x16x32_bf16 v[104:107], v[232:235], v[204:207], v[24:27]
	v_mfma_f32_16x16x32_bf16 v[24:27], v[236:239], v[200:203], v[72:75]
	v_mfma_f32_16x16x32_bf16 v[100:103], v[240:243], v[204:207], v[24:27]
	v_mfma_f32_16x16x32_bf16 v[24:27], v[228:231], v[208:211], v[68:71]
	v_mfma_f32_16x16x32_bf16 v[96:99], v[232:235], v[212:215], v[24:27]
	v_mfma_f32_16x16x32_bf16 v[24:27], v[236:239], v[208:211], v[64:67]
	v_mfma_f32_16x16x32_bf16 v[136:139], v[232:235], v[28:31], v[92:95]
	v_mfma_f32_16x16x32_bf16 v[92:95], v[240:243], v[212:215], v[24:27]
	s_barrier
	ds_read_b128 v[64:67], v184 offset:49152
	ds_read_b128 v[68:71], v184 offset:50176
	ds_read_b128 v[192:195], v185 offset:49152
	ds_read_b128 v[196:199], v185 offset:50176
	ds_read_b128 v[200:203], v186 offset:49152
	ds_read_b128 v[204:207], v186 offset:50176
	ds_read_b128 v[208:211], v187 offset:49152
	ds_read_b128 v[212:215], v187 offset:50176
	s_barrier
	s_waitcnt lgkmcnt(7)
	v_mfma_f32_16x16x32_bf16 v[24:27], v[16:19], v[64:67], v[60:63]
	s_waitcnt lgkmcnt(6)
	v_mfma_f32_16x16x32_bf16 v[88:91], v[20:23], v[68:71], v[24:27]
	v_mfma_f32_16x16x32_bf16 v[24:27], v[164:167], v[64:67], v[56:59]
	v_mfma_f32_16x16x32_bf16 v[84:87], v[168:171], v[68:71], v[24:27]
	s_waitcnt lgkmcnt(5)
	v_mfma_f32_16x16x32_bf16 v[24:27], v[16:19], v[192:195], v[52:55]
	s_waitcnt lgkmcnt(4)
	v_mfma_f32_16x16x32_bf16 v[80:83], v[20:23], v[196:199], v[24:27]
	v_mfma_f32_16x16x32_bf16 v[24:27], v[164:167], v[192:195], v[48:51]
	v_mfma_f32_16x16x32_bf16 v[76:79], v[168:171], v[196:199], v[24:27]
	s_waitcnt lgkmcnt(3)
	v_mfma_f32_16x16x32_bf16 v[24:27], v[16:19], v[200:203], v[44:47]
	s_waitcnt lgkmcnt(1)
	v_mfma_f32_16x16x32_bf16 v[16:19], v[16:19], v[208:211], v[36:39]
	v_mfma_f32_16x16x32_bf16 v[28:31], v[20:23], v[204:207], v[24:27]
	v_mfma_f32_16x16x32_bf16 v[24:27], v[164:167], v[200:203], v[40:43]
	s_waitcnt lgkmcnt(0)
	v_mfma_f32_16x16x32_bf16 v[20:23], v[20:23], v[212:215], v[16:19]
	v_mfma_f32_16x16x32_bf16 v[16:19], v[164:167], v[208:211], v[32:35]
	v_mfma_f32_16x16x32_bf16 v[24:27], v[168:171], v[204:207], v[24:27]
	v_mfma_f32_16x16x32_bf16 v[16:19], v[168:171], v[212:215], v[16:19]
	v_mfma_f32_16x16x32_bf16 v[32:35], v[228:231], v[64:67], v[216:219]
	v_mfma_f32_16x16x32_bf16 v[72:75], v[232:235], v[68:71], v[32:35]
	v_mfma_f32_16x16x32_bf16 v[32:35], v[236:239], v[64:67], v[220:223]
	v_mfma_f32_16x16x32_bf16 v[68:71], v[240:243], v[68:71], v[32:35]
	v_mfma_f32_16x16x32_bf16 v[32:35], v[228:231], v[192:195], v[224:227]
	v_mfma_f32_16x16x32_bf16 v[40:43], v[232:235], v[196:199], v[32:35]
	v_mfma_f32_16x16x32_bf16 v[32:35], v[236:239], v[192:195], v[160:163]
	v_mfma_f32_16x16x32_bf16 v[12:15], v[228:231], v[200:203], v[12:15]
	v_mfma_f32_16x16x32_bf16 v[8:11], v[236:239], v[200:203], v[8:11]
	v_mfma_f32_16x16x32_bf16 v[4:7], v[228:231], v[208:211], v[4:7]
	v_mfma_f32_16x16x32_bf16 v[0:3], v[236:239], v[208:211], v[0:3]
	v_mfma_f32_16x16x32_bf16 v[36:39], v[240:243], v[196:199], v[32:35]
	v_mfma_f32_16x16x32_bf16 v[12:15], v[232:235], v[204:207], v[12:15]
	v_mfma_f32_16x16x32_bf16 v[8:11], v[240:243], v[204:207], v[8:11]
	v_mfma_f32_16x16x32_bf16 v[4:7], v[232:235], v[212:215], v[4:7]
	v_mfma_f32_16x16x32_bf16 v[0:3], v[240:243], v[212:215], v[0:3]
	s_andn2_b64 vcc, exec, s[16:17]
	s_barrier
	s_cbranch_vccz .LBB0_574
	s_andn2_b64 vcc, exec, s[28:29]
	s_cbranch_vccz .LBB0_575

; #define LDA(dst, b, h)                                                                                               \
;   _Pragma("unroll") for (int m = 0; m < 4; ++m) _Pragma("unroll") for (int k = 0; k < 2; ++k) dst[m][k] =            \
;       *reinterpret_cast<const bf16x8*>(SA(b, h) + lds_byte(wr * 64 + m * 16 + fr, k * 32 + fq * 8))
; #define LDB(dst, b, h)                                                                                               \
;   _Pragma("unroll") for (int n = 0; n < 2; ++n) _Pragma("unroll") for (int k = 0; k < 2; ++k) dst[n][k] =            \
;       *reinterpret_cast<const bf16x8*>(SB(b, h) + lds_byte(wc * 32 + n * 16 + fr, k * 32 + fq * 8))
; #define WAIT_V(n) asm volatile("s_waitcnt vmcnt(" #n ")" ::: "memory")
; #define WAIT_L(n) asm volatile("s_waitcnt lgkmcnt(" #n ")" ::: "memory")
; #define BAR __builtin_amdgcn_s_barrier()
; #define SCHED __builtin_amdgcn_sched_barrier(0)
; template <int EPI>
; __device__ __forceinline__ void gemm_phase(const u16* __restrict__ A, const u16* __restrict__ Bt, const int K,
;                                            const int nN, char* shm, const EpiArgs& ea) {
;     ...
;     for (int t = 0; t < nt - 2; t += 2) {
;       LDB(B0, 0, 0); SCHED; LDA(At, 0, 0); STAGE(SA(1, 1), rA, brow + HALF, t + 1);
;       WAIT_V(10); WAIT_L(8); BAR; WAIT_L(0); MMA(0, 0, At, B0); BAR; SCHED;
;       LDB(B1, 0, 1); STAGE(SB(0, 0), rB, bcol, t + 2);
;       WAIT_V(10); BAR; WAIT_L(0); MMA(0, 1, At, B1); BAR;
;       LDA(At, 0, 1); STAGE(SA(0, 0), rA, brow, t + 2);
;       BAR; WAIT_L(0); MMA(1, 0, At, B0); BAR; SCHED;
;       STAGE(SB(0, 1), rB, bcol + HALF, t + 2);
;       WAIT_V(10); BAR; MMA(1, 1, At, B1); BAR;
.LBB0_631:
	ds_read_b128 v[130:133], v141
	ds_read_b128 v[134:137], v141 offset:1024
	ds_read_b128 v[150:153], v141 offset:2048
	ds_read_b128 v[154:157], v141 offset:3072
	s_add_i32 s54, s48, s53
	s_mov_b32 m0, s41
	s_add_i32 s6, s54, 0x4000
	ds_read_b128 v[158:161], v142
	ds_read_b128 v[162:165], v142 offset:1024
	ds_read_b128 v[166:169], v143
	ds_read_b128 v[170:173], v143 offset:1024
	ds_read_b128 v[176:179], v144
	ds_read_b128 v[180:183], v144 offset:1024
	ds_read_b128 v[184:187], v145
	ds_read_b128 v[188:191], v145 offset:1024
	buffer_load_dwordx4 v138, s[0:3], s6 offen lds
	s_add_i32 s6, s54, 0x6000
	s_mov_b32 m0, s42
	s_nop 0
	buffer_load_dwordx4 v138, s[0:3], s6 offen lds
	s_waitcnt vmcnt(10)
	s_waitcnt lgkmcnt(8)
	s_barrier
	s_waitcnt lgkmcnt(7)
	v_mfma_f32_16x16x32_bf16 v[124:127], v[130:133], v[158:161], v[124:127]
	v_mfma_f32_16x16x32_bf16 v[120:123], v[150:153], v[158:161], v[120:123]
	s_waitcnt lgkmcnt(5)
	v_mfma_f32_16x16x32_bf16 v[116:119], v[130:133], v[166:169], v[116:119]
	v_mfma_f32_16x16x32_bf16 v[112:115], v[150:153], v[166:169], v[112:115]
	s_waitcnt lgkmcnt(3)
	v_mfma_f32_16x16x32_bf16 v[108:111], v[130:133], v[176:179], v[108:111]
	v_mfma_f32_16x16x32_bf16 v[104:107], v[150:153], v[176:179], v[104:107]
	s_waitcnt lgkmcnt(1)
	v_mfma_f32_16x16x32_bf16 v[100:103], v[130:133], v[184:187], v[100:103]
	v_mfma_f32_16x16x32_bf16 v[96:99], v[150:153], v[184:187], v[96:99]
	v_mfma_f32_16x16x32_bf16 v[124:127], v[134:137], v[162:165], v[124:127]
	v_mfma_f32_16x16x32_bf16 v[120:123], v[154:157], v[162:165], v[120:123]
	v_mfma_f32_16x16x32_bf16 v[116:119], v[134:137], v[170:173], v[116:119]
	v_mfma_f32_16x16x32_bf16 v[112:115], v[154:157], v[170:173], v[112:115]
	v_mfma_f32_16x16x32_bf16 v[108:111], v[134:137], v[180:183], v[108:111]
	v_mfma_f32_16x16x32_bf16 v[104:107], v[154:157], v[180:183], v[104:107]
	s_waitcnt lgkmcnt(0)
	v_mfma_f32_16x16x32_bf16 v[100:103], v[134:137], v[188:191], v[100:103]
	v_mfma_f32_16x16x32_bf16 v[96:99], v[154:157], v[188:191], v[96:99]
	s_barrier
	s_add_i32 s55, s51, s53
	s_mov_b32 m0, s19
	s_add_i32 s56, s55, 0x8000
	s_mov_b32 s6, s2
	s_mov_b32 s7, s3
	ds_read_b128 v[192:195], v146
	ds_read_b128 v[196:199], v146 offset:1024
	ds_read_b128 v[200:203], v146 offset:2048
	ds_read_b128 v[204:207], v146 offset:3072
	buffer_load_dwordx4 v138, s[4:7], s56 offen lds
	s_add_i32 s56, s55, 0xa000
	s_mov_b32 m0, s26
	s_nop 0
	buffer_load_dwordx4 v138, s[4:7], s56 offen lds
	s_waitcnt vmcnt(10)
	s_barrier
	s_waitcnt lgkmcnt(3)
	v_mfma_f32_16x16x32_bf16 v[92:95], v[192:195], v[158:161], v[92:95]
	s_waitcnt lgkmcnt(1)
	v_mfma_f32_16x16x32_bf16 v[88:91], v[200:203], v[158:161], v[88:91]
	v_mfma_f32_16x16x32_bf16 v[84:87], v[192:195], v[166:169], v[84:87]
	v_mfma_f32_16x16x32_bf16 v[80:83], v[200:203], v[166:169], v[80:83]
	v_mfma_f32_16x16x32_bf16 v[76:79], v[192:195], v[176:179], v[76:79]
	v_mfma_f32_16x16x32_bf16 v[72:75], v[200:203], v[176:179], v[72:75]
	v_mfma_f32_16x16x32_bf16 v[68:71], v[192:195], v[184:187], v[68:71]
	v_mfma_f32_16x16x32_bf16 v[64:67], v[200:203], v[184:187], v[64:67]
	v_mfma_f32_16x16x32_bf16 v[92:95], v[196:199], v[162:165], v[92:95]
	s_waitcnt lgkmcnt(0)
	v_mfma_f32_16x16x32_bf16 v[88:91], v[204:207], v[162:165], v[88:91]
	v_mfma_f32_16x16x32_bf16 v[84:87], v[196:199], v[170:173], v[84:87]
	v_mfma_f32_16x16x32_bf16 v[80:83], v[204:207], v[170:173], v[80:83]
	v_mfma_f32_16x16x32_bf16 v[76:79], v[196:199], v[180:183], v[76:79]
	v_mfma_f32_16x16x32_bf16 v[72:75], v[204:207], v[180:183], v[72:75]
	v_mfma_f32_16x16x32_bf16 v[68:71], v[196:199], v[188:191], v[68:71]
	v_mfma_f32_16x16x32_bf16 v[64:67], v[204:207], v[188:191], v[64:67]
	s_add_i32 s56, s50, s53
	s_mov_b32 m0, s27
	s_add_i32 s57, s56, 0x8000
	s_barrier
	ds_read_b128 v[158:161], v142 offset:16384
	ds_read_b128 v[162:165], v142 offset:17408
	ds_read_b128 v[166:169], v143 offset:16384
	ds_read_b128 v[170:173], v143 offset:17408
	ds_read_b128 v[176:179], v144 offset:16384
	ds_read_b128 v[180:183], v144 offset:17408
	ds_read_b128 v[184:187], v145 offset:16384
	ds_read_b128 v[188:191], v145 offset:17408
	buffer_load_dwordx4 v138, s[0:3], s57 offen lds
	s_add_i32 s57, s56, 0xa000
	s_mov_b32 m0, s28
	s_nop 0
	buffer_load_dwordx4 v138, s[0:3], s57 offen lds
	s_barrier
	s_waitcnt lgkmcnt(7)
	v_mfma_f32_16x16x32_bf16 v[60:63], v[130:133], v[158:161], v[60:63]
	v_mfma_f32_16x16x32_bf16 v[56:59], v[150:153], v[158:161], v[56:59]
	s_waitcnt lgkmcnt(5)
	v_mfma_f32_16x16x32_bf16 v[52:55], v[130:133], v[166:169], v[52:55]
	v_mfma_f32_16x16x32_bf16 v[48:51], v[150:153], v[166:169], v[48:51]
	s_waitcnt lgkmcnt(3)
	v_mfma_f32_16x16x32_bf16 v[44:47], v[130:133], v[176:179], v[44:47]
	v_mfma_f32_16x16x32_bf16 v[40:43], v[150:153], v[176:179], v[40:43]
	s_waitcnt lgkmcnt(1)
	v_mfma_f32_16x16x32_bf16 v[36:39], v[130:133], v[184:187], v[36:39]
	v_mfma_f32_16x16x32_bf16 v[32:35], v[150:153], v[184:187], v[32:35]
	v_mfma_f32_16x16x32_bf16 v[60:63], v[134:137], v[162:165], v[60:63]
	v_mfma_f32_16x16x32_bf16 v[56:59], v[154:157], v[162:165], v[56:59]
	v_mfma_f32_16x16x32_bf16 v[52:55], v[134:137], v[170:173], v[52:55]
	v_mfma_f32_16x16x32_bf16 v[48:51], v[154:157], v[170:173], v[48:51]
	v_mfma_f32_16x16x32_bf16 v[44:47], v[134:137], v[180:183], v[44:47]
	v_mfma_f32_16x16x32_bf16 v[40:43], v[154:157], v[180:183], v[40:43]
	s_waitcnt lgkmcnt(0)
	v_mfma_f32_16x16x32_bf16 v[36:39], v[134:137], v[188:191], v[36:39]
	v_mfma_f32_16x16x32_bf16 v[32:35], v[154:157], v[188:191], v[32:35]
	s_barrier
	s_add_i32 s57, s49, s53
	s_mov_b32 m0, s29
	s_add_i32 s58, s57, 0x8000
	buffer_load_dwordx4 v138, s[4:7], s58 offen lds
	s_add_i32 s58, s57, 0xa000
	s_mov_b32 m0, s30
	s_nop 0
	buffer_load_dwordx4 v138, s[4:7], s58 offen lds
	s_waitcnt vmcnt(10)
	s_barrier
; #define LDA(dst, b, h)                                                                                               \
;   _Pragma("unroll") for (int m = 0; m < 4; ++m) _Pragma("unroll") for (int k = 0; k < 2; ++k) dst[m][k] =            \
;       *reinterpret_cast<const bf16x8*>(SA(b, h) + lds_byte(wr * 64 + m * 16 + fr, k * 32 + fq * 8))
; #define LDB(dst, b, h)                                                                                               \
;   _Pragma("unroll") for (int n = 0; n < 2; ++n) _Pragma("unroll") for (int k = 0; k < 2; ++k) dst[n][k] =            \
;       *reinterpret_cast<const bf16x8*>(SB(b, h) + lds_byte(wc * 32 + n * 16 + fr, k * 32 + fq * 8))
; #define WAIT_V(n) asm volatile("s_waitcnt vmcnt(" #n ")" ::: "memory")
; #define WAIT_L(n) asm volatile("s_waitcnt lgkmcnt(" #n ")" ::: "memory")
; #define BAR __builtin_amdgcn_s_barrier()
; #define SCHED __builtin_amdgcn_sched_barrier(0)
; template <int EPI>
; __device__ __forceinline__ void gemm_phase(const u16* __restrict__ A, const u16* __restrict__ Bt, const int K,
;                                            const int nN, char* shm, const EpiArgs& ea) {
;     ...
;       WAIT_V(10); BAR; MMA(1, 1, At, B1); BAR;
;       LDB(B0, 1, 0); SCHED; LDA(At, 1, 0); STAGE(SA(0, 1), rA, brow + HALF, t + 2);
;       WAIT_V(10); WAIT_L(8); BAR; WAIT_L(0); MMA(0, 0, At, B0); BAR; SCHED;
;       LDB(B1, 1, 1); STAGE(SB(1, 0), rB, bcol, t + 3);
;       WAIT_V(10); BAR; WAIT_L(0); MMA(0, 1, At, B1); BAR;
	v_mfma_f32_16x16x32_bf16 v[28:31], v[192:195], v[158:161], v[28:31]
	v_mfma_f32_16x16x32_bf16 v[24:27], v[200:203], v[158:161], v[24:27]
	v_mfma_f32_16x16x32_bf16 v[20:23], v[192:195], v[166:169], v[20:23]
	v_mfma_f32_16x16x32_bf16 v[16:19], v[200:203], v[166:169], v[16:19]
	v_mfma_f32_16x16x32_bf16 v[12:15], v[192:195], v[176:179], v[12:15]
	v_mfma_f32_16x16x32_bf16 v[8:11], v[200:203], v[176:179], v[8:11]
	v_mfma_f32_16x16x32_bf16 v[4:7], v[192:195], v[184:187], v[4:7]
	v_mfma_f32_16x16x32_bf16 v[0:3], v[200:203], v[184:187], v[0:3]
	v_mfma_f32_16x16x32_bf16 v[28:31], v[196:199], v[162:165], v[28:31]
	v_mfma_f32_16x16x32_bf16 v[24:27], v[204:207], v[162:165], v[24:27]
	v_mfma_f32_16x16x32_bf16 v[20:23], v[196:199], v[170:173], v[20:23]
	v_mfma_f32_16x16x32_bf16 v[16:19], v[204:207], v[170:173], v[16:19]
	v_mfma_f32_16x16x32_bf16 v[12:15], v[196:199], v[180:183], v[12:15]
	v_mfma_f32_16x16x32_bf16 v[8:11], v[204:207], v[180:183], v[8:11]
	v_mfma_f32_16x16x32_bf16 v[4:7], v[196:199], v[188:191], v[4:7]
	v_mfma_f32_16x16x32_bf16 v[0:3], v[204:207], v[188:191], v[0:3]
	s_barrier
	ds_read_b128 v[130:133], v147
	ds_read_b128 v[134:137], v147 offset:1024
	ds_read_b128 v[150:153], v147 offset:2048
	ds_read_b128 v[154:157], v147 offset:3072
	s_mov_b32 m0, s31
	s_add_i32 s58, s54, 0x8000
	ds_read_b128 v[158:161], v142 offset:32768
	ds_read_b128 v[162:165], v142 offset:33792
	ds_read_b128 v[166:169], v143 offset:32768
	ds_read_b128 v[170:173], v143 offset:33792
	ds_read_b128 v[176:179], v144 offset:32768
	ds_read_b128 v[180:183], v144 offset:33792
	ds_read_b128 v[184:187], v145 offset:32768
	ds_read_b128 v[188:191], v145 offset:33792
	buffer_load_dwordx4 v138, s[0:3], s58 offen lds
	s_add_i32 s54, s54, 0xa000
	s_mov_b32 m0, s34
	s_nop 0
	buffer_load_dwordx4 v138, s[0:3], s54 offen lds
	s_waitcnt vmcnt(10)
	s_waitcnt lgkmcnt(8)
	s_barrier
	s_waitcnt lgkmcnt(7)
	v_mfma_f32_16x16x32_bf16 v[124:127], v[130:133], v[158:161], v[124:127]
	v_mfma_f32_16x16x32_bf16 v[120:123], v[150:153], v[158:161], v[120:123]
	s_waitcnt lgkmcnt(5)
	v_mfma_f32_16x16x32_bf16 v[116:119], v[130:133], v[166:169], v[116:119]
	v_mfma_f32_16x16x32_bf16 v[112:115], v[150:153], v[166:169], v[112:115]
	s_waitcnt lgkmcnt(3)
	v_mfma_f32_16x16x32_bf16 v[108:111], v[130:133], v[176:179], v[108:111]
	v_mfma_f32_16x16x32_bf16 v[104:107], v[150:153], v[176:179], v[104:107]
	s_waitcnt lgkmcnt(1)
	v_mfma_f32_16x16x32_bf16 v[100:103], v[130:133], v[184:187], v[100:103]
	v_mfma_f32_16x16x32_bf16 v[96:99], v[150:153], v[184:187], v[96:99]
	v_mfma_f32_16x16x32_bf16 v[124:127], v[134:137], v[162:165], v[124:127]
	v_mfma_f32_16x16x32_bf16 v[120:123], v[154:157], v[162:165], v[120:123]
	v_mfma_f32_16x16x32_bf16 v[116:119], v[134:137], v[170:173], v[116:119]
	v_mfma_f32_16x16x32_bf16 v[112:115], v[154:157], v[170:173], v[112:115]
	v_mfma_f32_16x16x32_bf16 v[108:111], v[134:137], v[180:183], v[108:111]
	v_mfma_f32_16x16x32_bf16 v[104:107], v[154:157], v[180:183], v[104:107]
	s_waitcnt lgkmcnt(0)
	v_mfma_f32_16x16x32_bf16 v[100:103], v[134:137], v[188:191], v[100:103]
	v_mfma_f32_16x16x32_bf16 v[96:99], v[154:157], v[188:191], v[96:99]
	s_barrier
	s_mov_b32 m0, s35
	s_add_i32 s54, s55, 0xc000
	ds_read_b128 v[192:195], v148
	ds_read_b128 v[196:199], v148 offset:1024
	ds_read_b128 v[200:203], v148 offset:2048
	ds_read_b128 v[204:207], v148 offset:3072
	buffer_load_dwordx4 v138, s[4:7], s54 offen lds
	s_add_i32 s55, s55, 0xe000
	s_mov_b32 m0, s36
	s_nop 0
	buffer_load_dwordx4 v138, s[4:7], s55 offen lds
	s_waitcnt vmcnt(10)
	s_barrier
	s_waitcnt lgkmcnt(3)
	v_mfma_f32_16x16x32_bf16 v[92:95], v[192:195], v[158:161], v[92:95]
	s_waitcnt lgkmcnt(1)
	v_mfma_f32_16x16x32_bf16 v[88:91], v[200:203], v[158:161], v[88:91]
	v_mfma_f32_16x16x32_bf16 v[84:87], v[192:195], v[166:169], v[84:87]
	v_mfma_f32_16x16x32_bf16 v[80:83], v[200:203], v[166:169], v[80:83]
	v_mfma_f32_16x16x32_bf16 v[76:79], v[192:195], v[176:179], v[76:79]
	v_mfma_f32_16x16x32_bf16 v[72:75], v[200:203], v[176:179], v[72:75]
	v_mfma_f32_16x16x32_bf16 v[68:71], v[192:195], v[184:187], v[68:71]
	v_mfma_f32_16x16x32_bf16 v[64:67], v[200:203], v[184:187], v[64:67]
	v_mfma_f32_16x16x32_bf16 v[92:95], v[196:199], v[162:165], v[92:95]
	s_waitcnt lgkmcnt(0)
	v_mfma_f32_16x16x32_bf16 v[88:91], v[204:207], v[162:165], v[88:91]
	v_mfma_f32_16x16x32_bf16 v[84:87], v[196:199], v[170:173], v[84:87]
	v_mfma_f32_16x16x32_bf16 v[80:83], v[204:207], v[170:173], v[80:83]
	v_mfma_f32_16x16x32_bf16 v[76:79], v[196:199], v[180:183], v[76:79]
	v_mfma_f32_16x16x32_bf16 v[72:75], v[204:207], v[180:183], v[72:75]
	v_mfma_f32_16x16x32_bf16 v[68:71], v[196:199], v[188:191], v[68:71]
	v_mfma_f32_16x16x32_bf16 v[64:67], v[204:207], v[188:191], v[64:67]
	s_mov_b32 m0, s37
	s_add_i32 s54, s56, 0xc000
	s_barrier
	ds_read_b128 v[158:161], v142 offset:49152
	ds_read_b128 v[162:165], v142 offset:50176
	ds_read_b128 v[166:169], v143 offset:49152
	ds_read_b128 v[170:173], v143 offset:50176
	ds_read_b128 v[176:179], v144 offset:49152
	ds_read_b128 v[180:183], v144 offset:50176
	ds_read_b128 v[184:187], v145 offset:49152
	ds_read_b128 v[188:191], v145 offset:50176
	buffer_load_dwordx4 v138, s[0:3], s54 offen lds
	s_add_i32 s56, s56, 0xe000
	s_mov_b32 m0, s38
	s_nop 0
	buffer_load_dwordx4 v138, s[0:3], s56 offen lds
	s_barrier
; #define LDA(dst, b, h)                                                                                               \
;   _Pragma("unroll") for (int m = 0; m < 4; ++m) _Pragma("unroll") for (int k = 0; k < 2; ++k) dst[m][k] =            \
;       *reinterpret_cast<const bf16x8*>(SA(b, h) + lds_byte(wr * 64 + m * 16 + fr, k * 32 + fq * 8))
; #define LDB(dst, b, h)                                                                                               \
;   _Pragma("unroll") for (int n = 0; n < 2; ++n) _Pragma("unroll") for (int k = 0; k < 2; ++k) dst[n][k] =            \
;       *reinterpret_cast<const bf16x8*>(SB(b, h) + lds_byte(wc * 32 + n * 16 + fr, k * 32 + fq * 8))
; #define WAIT_V(n) asm volatile("s_waitcnt vmcnt(" #n ")" ::: "memory")
; #define WAIT_L(n) asm volatile("s_waitcnt lgkmcnt(" #n ")" ::: "memory")
; #define BAR __builtin_amdgcn_s_barrier()
; #define SCHED __builtin_amdgcn_sched_barrier(0)
; template <int EPI>
; __device__ __forceinline__ void gemm_phase(const u16* __restrict__ A, const u16* __restrict__ Bt, const int K,
;                                            const int nN, char* shm, const EpiArgs& ea) {
;     ...
;       LDA(At, 1, 1); STAGE(SA(1, 0), rA, brow, t + 3);
;       BAR; WAIT_L(0); MMA(1, 0, At, B0); BAR; SCHED;
;       STAGE(SB(1, 1), rB, bcol + HALF, t + 3);
;       WAIT_V(10); BAR; MMA(1, 1, At, B1); BAR;
;     }
;     float eC = 0.f, eB = 0.f;
;     float2 eS = make_float2(0.f, 0.f);
;     if (EPI == EPI_IN || EPI == EPI_SWIGLU_LN) {
;       if (wr == 0) {
;         eC = ea.c1[bcol + tid];
;         eS = *(const float2*)(ea.st_in + (size_t)(brow + tid) * 2);
;       } else {
;         eC = ea.c2[bcol + tid - 256];
;         if (EPI == EPI_IN) eB = ea.bias[bcol + tid - 256];
;       }
;     }
;     {
;       LDB(B0, 0, 0); LDA(At, 0, 0); STAGE(SA(1, 1), rA, brow + HALF, nt - 1);
;       WAIT_V(10); BAR; WAIT_L(0); MMA(0, 0, At, B0); BAR;
;       LDB(B1, 0, 1); WAIT_V(8); BAR; WAIT_L(0); MMA(0, 1, At, B1); BAR;
	s_waitcnt lgkmcnt(7)
	v_mfma_f32_16x16x32_bf16 v[60:63], v[130:133], v[158:161], v[60:63]
	v_mfma_f32_16x16x32_bf16 v[56:59], v[150:153], v[158:161], v[56:59]
	s_waitcnt lgkmcnt(5)
	v_mfma_f32_16x16x32_bf16 v[52:55], v[130:133], v[166:169], v[52:55]
	v_mfma_f32_16x16x32_bf16 v[48:51], v[150:153], v[166:169], v[48:51]
	s_waitcnt lgkmcnt(3)
	v_mfma_f32_16x16x32_bf16 v[44:47], v[130:133], v[176:179], v[44:47]
	v_mfma_f32_16x16x32_bf16 v[40:43], v[150:153], v[176:179], v[40:43]
	s_waitcnt lgkmcnt(1)
	v_mfma_f32_16x16x32_bf16 v[36:39], v[130:133], v[184:187], v[36:39]
	v_mfma_f32_16x16x32_bf16 v[32:35], v[150:153], v[184:187], v[32:35]
	v_mfma_f32_16x16x32_bf16 v[60:63], v[134:137], v[162:165], v[60:63]
	v_mfma_f32_16x16x32_bf16 v[56:59], v[154:157], v[162:165], v[56:59]
	v_mfma_f32_16x16x32_bf16 v[52:55], v[134:137], v[170:173], v[52:55]
	v_mfma_f32_16x16x32_bf16 v[48:51], v[154:157], v[170:173], v[48:51]
	v_mfma_f32_16x16x32_bf16 v[44:47], v[134:137], v[180:183], v[44:47]
	v_mfma_f32_16x16x32_bf16 v[40:43], v[154:157], v[180:183], v[40:43]
	s_waitcnt lgkmcnt(0)
	v_mfma_f32_16x16x32_bf16 v[36:39], v[134:137], v[188:191], v[36:39]
	v_mfma_f32_16x16x32_bf16 v[32:35], v[154:157], v[188:191], v[32:35]
	s_barrier
	s_mov_b32 m0, s39
	s_add_i32 s54, s57, 0xc000
	buffer_load_dwordx4 v138, s[4:7], s54 offen lds
	s_add_i32 s57, s57, 0xe000
	s_mov_b32 m0, s40
	s_nop 0
	buffer_load_dwordx4 v138, s[4:7], s57 offen lds
	s_waitcnt vmcnt(10)
	s_barrier
	v_mfma_f32_16x16x32_bf16 v[28:31], v[192:195], v[158:161], v[28:31]
	v_mfma_f32_16x16x32_bf16 v[24:27], v[200:203], v[158:161], v[24:27]
	v_mfma_f32_16x16x32_bf16 v[20:23], v[192:195], v[166:169], v[20:23]
	v_mfma_f32_16x16x32_bf16 v[16:19], v[200:203], v[166:169], v[16:19]
	v_mfma_f32_16x16x32_bf16 v[12:15], v[192:195], v[176:179], v[12:15]
	v_mfma_f32_16x16x32_bf16 v[8:11], v[200:203], v[176:179], v[8:11]
	v_mfma_f32_16x16x32_bf16 v[4:7], v[192:195], v[184:187], v[4:7]
	v_mfma_f32_16x16x32_bf16 v[0:3], v[200:203], v[184:187], v[0:3]
	v_mfma_f32_16x16x32_bf16 v[28:31], v[196:199], v[162:165], v[28:31]
	v_mfma_f32_16x16x32_bf16 v[24:27], v[204:207], v[162:165], v[24:27]
	v_mfma_f32_16x16x32_bf16 v[20:23], v[196:199], v[170:173], v[20:23]
	v_mfma_f32_16x16x32_bf16 v[16:19], v[204:207], v[170:173], v[16:19]
	v_mfma_f32_16x16x32_bf16 v[12:15], v[196:199], v[180:183], v[12:15]
	v_mfma_f32_16x16x32_bf16 v[8:11], v[204:207], v[180:183], v[8:11]
	v_mfma_f32_16x16x32_bf16 v[4:7], v[196:199], v[188:191], v[4:7]
	v_mfma_f32_16x16x32_bf16 v[0:3], v[204:207], v[188:191], v[0:3]
	s_add_i32 s52, s52, 2
	s_add_i32 s53, s53, 0x8000
	s_cmpk_lt_u32 s52, 0x54
	s_barrier
	s_cbranch_scc1 .LBB0_631
	s_mov_b32 m0, s41
	s_add_i32 s6, s48, 0x15c000
	ds_read_b128 v[130:133], v141
	ds_read_b128 v[134:137], v141 offset:1024
	ds_read_b128 v[150:153], v141 offset:2048
	ds_read_b128 v[154:157], v141 offset:3072
	ds_read_b128 v[158:161], v142
	ds_read_b128 v[162:165], v142 offset:1024
	ds_read_b128 v[166:169], v143
	ds_read_b128 v[170:173], v143 offset:1024
	ds_read_b128 v[176:179], v144
	ds_read_b128 v[180:183], v144 offset:1024
	ds_read_b128 v[184:187], v145
	ds_read_b128 v[188:191], v145 offset:1024
	buffer_load_dwordx4 v138, s[0:3], s6 offen lds
	s_add_i32 s48, s48, 0x15e000
	s_mov_b32 m0, s42
	s_nop 0
	buffer_load_dwordx4 v138, s[0:3], s48 offen lds
	s_waitcnt vmcnt(10)
	s_barrier
	s_waitcnt lgkmcnt(7)
	v_mfma_f32_16x16x32_bf16 v[124:127], v[130:133], v[158:161], v[124:127]
	v_mfma_f32_16x16x32_bf16 v[120:123], v[150:153], v[158:161], v[120:123]
	s_waitcnt lgkmcnt(5)
	v_mfma_f32_16x16x32_bf16 v[116:119], v[130:133], v[166:169], v[116:119]
	v_mfma_f32_16x16x32_bf16 v[112:115], v[150:153], v[166:169], v[112:115]
	s_waitcnt lgkmcnt(1)
	v_mfma_f32_16x16x32_bf16 v[100:103], v[130:133], v[184:187], v[100:103]
	v_mfma_f32_16x16x32_bf16 v[96:99], v[150:153], v[184:187], v[96:99]
	v_mfma_f32_16x16x32_bf16 v[124:127], v[134:137], v[162:165], v[124:127]
	v_mfma_f32_16x16x32_bf16 v[120:123], v[154:157], v[162:165], v[120:123]
	v_mfma_f32_16x16x32_bf16 v[116:119], v[134:137], v[170:173], v[116:119]
	v_mfma_f32_16x16x32_bf16 v[112:115], v[154:157], v[170:173], v[112:115]
	v_mfma_f32_16x16x32_bf16 v[108:111], v[130:133], v[176:179], v[108:111]
	v_mfma_f32_16x16x32_bf16 v[104:107], v[150:153], v[176:179], v[104:107]
	s_waitcnt lgkmcnt(0)
	v_mfma_f32_16x16x32_bf16 v[100:103], v[134:137], v[188:191], v[100:103]
	v_mfma_f32_16x16x32_bf16 v[96:99], v[154:157], v[188:191], v[96:99]
	v_mfma_f32_16x16x32_bf16 v[192:195], v[134:137], v[180:183], v[108:111]
	v_mfma_f32_16x16x32_bf16 v[196:199], v[154:157], v[180:183], v[104:107]
	s_barrier
	s_nop 0
	ds_read_b128 v[104:107], v146
	ds_read_b128 v[108:111], v146 offset:1024
	ds_read_b128 v[200:203], v146 offset:2048
	ds_read_b128 v[204:207], v146 offset:3072
	s_waitcnt vmcnt(8)
	s_barrier
	s_waitcnt lgkmcnt(3)
	v_mfma_f32_16x16x32_bf16 v[84:87], v[104:107], v[166:169], v[84:87]
	s_waitcnt lgkmcnt(1)
	v_mfma_f32_16x16x32_bf16 v[80:83], v[200:203], v[166:169], v[80:83]
	v_mfma_f32_16x16x32_bf16 v[68:71], v[104:107], v[184:187], v[68:71]
	v_mfma_f32_16x16x32_bf16 v[64:67], v[200:203], v[184:187], v[64:67]
	v_mfma_f32_16x16x32_bf16 v[92:95], v[104:107], v[158:161], v[92:95]
	v_mfma_f32_16x16x32_bf16 v[88:91], v[200:203], v[158:161], v[88:91]
	v_mfma_f32_16x16x32_bf16 v[84:87], v[108:111], v[170:173], v[84:87]
	s_waitcnt lgkmcnt(0)
	v_mfma_f32_16x16x32_bf16 v[80:83], v[204:207], v[170:173], v[80:83]
	v_mfma_f32_16x16x32_bf16 v[76:79], v[104:107], v[176:179], v[76:79]
	v_mfma_f32_16x16x32_bf16 v[72:75], v[200:203], v[176:179], v[72:75]
	v_mfma_f32_16x16x32_bf16 v[68:71], v[108:111], v[188:191], v[68:71]
	v_mfma_f32_16x16x32_bf16 v[64:67], v[204:207], v[188:191], v[64:67]
	v_mfma_f32_16x16x32_bf16 v[208:211], v[108:111], v[162:165], v[92:95]
	v_mfma_f32_16x16x32_bf16 v[158:161], v[204:207], v[162:165], v[88:91]
	v_mfma_f32_16x16x32_bf16 v[162:165], v[108:111], v[180:183], v[76:79]
	v_mfma_f32_16x16x32_bf16 v[166:169], v[204:207], v[180:183], v[72:75]
	s_barrier
; #define LDA(dst, b, h)                                                                                               \
;   _Pragma("unroll") for (int m = 0; m < 4; ++m) _Pragma("unroll") for (int k = 0; k < 2; ++k) dst[m][k] =            \
;       *reinterpret_cast<const bf16x8*>(SA(b, h) + lds_byte(wr * 64 + m * 16 + fr, k * 32 + fq * 8))
; #define LDB(dst, b, h)                                                                                               \
;   _Pragma("unroll") for (int n = 0; n < 2; ++n) _Pragma("unroll") for (int k = 0; k < 2; ++k) dst[n][k] =            \
;       *reinterpret_cast<const bf16x8*>(SB(b, h) + lds_byte(wc * 32 + n * 16 + fr, k * 32 + fq * 8))
; #define WAIT_V(n) asm volatile("s_waitcnt vmcnt(" #n ")" ::: "memory")
; #define WAIT_L(n) asm volatile("s_waitcnt lgkmcnt(" #n ")" ::: "memory")
; #define BAR __builtin_amdgcn_s_barrier()
; template <int EPI>
; __device__ __forceinline__ void gemm_phase(const u16* __restrict__ A, const u16* __restrict__ Bt, const int K,
;                                            const int nN, char* shm, const EpiArgs& ea) {
;     ...
;       LDA(At, 0, 1); WAIT_V(4); BAR; WAIT_L(0); MMA(1, 0, At, B0); MMA(1, 1, At, B1); BAR;
;     }
;     {
;       LDB(B0, 1, 0); LDA(At, 1, 0); WAIT_V(2); BAR; WAIT_L(0); MMA(0, 0, At, B0); BAR;
	s_nop 0
	ds_read_b128 v[72:75], v142 offset:16384
	ds_read_b128 v[76:79], v142 offset:17408
	ds_read_b128 v[88:91], v143 offset:16384
	ds_read_b128 v[92:95], v143 offset:17408
	ds_read_b128 v[170:173], v144 offset:16384
	ds_read_b128 v[176:179], v144 offset:17408
	ds_read_b128 v[180:183], v145 offset:16384
	ds_read_b128 v[184:187], v145 offset:17408
	s_waitcnt vmcnt(4)
	s_barrier
	s_waitcnt lgkmcnt(7)
	v_mfma_f32_16x16x32_bf16 v[60:63], v[130:133], v[72:75], v[60:63]
	v_mfma_f32_16x16x32_bf16 v[56:59], v[150:153], v[72:75], v[56:59]
	s_waitcnt lgkmcnt(5)
	v_mfma_f32_16x16x32_bf16 v[52:55], v[130:133], v[88:91], v[52:55]
	v_mfma_f32_16x16x32_bf16 v[48:51], v[150:153], v[88:91], v[48:51]
	s_waitcnt lgkmcnt(1)
	v_mfma_f32_16x16x32_bf16 v[36:39], v[130:133], v[180:183], v[36:39]
	v_mfma_f32_16x16x32_bf16 v[32:35], v[150:153], v[180:183], v[32:35]
	v_mfma_f32_16x16x32_bf16 v[60:63], v[134:137], v[76:79], v[60:63]
	v_mfma_f32_16x16x32_bf16 v[56:59], v[154:157], v[76:79], v[56:59]
	v_mfma_f32_16x16x32_bf16 v[52:55], v[134:137], v[92:95], v[52:55]
	v_mfma_f32_16x16x32_bf16 v[48:51], v[154:157], v[92:95], v[48:51]
	v_mfma_f32_16x16x32_bf16 v[44:47], v[130:133], v[170:173], v[44:47]
	v_mfma_f32_16x16x32_bf16 v[40:43], v[150:153], v[170:173], v[40:43]
	s_waitcnt lgkmcnt(0)
	v_mfma_f32_16x16x32_bf16 v[36:39], v[134:137], v[184:187], v[36:39]
	v_mfma_f32_16x16x32_bf16 v[32:35], v[154:157], v[184:187], v[32:35]
	v_mfma_f32_16x16x32_bf16 v[188:191], v[134:137], v[176:179], v[44:47]
	v_mfma_f32_16x16x32_bf16 v[212:215], v[154:157], v[176:179], v[40:43]
	v_mfma_f32_16x16x32_bf16 v[20:23], v[104:107], v[88:91], v[20:23]
	v_mfma_f32_16x16x32_bf16 v[16:19], v[200:203], v[88:91], v[16:19]
	v_mfma_f32_16x16x32_bf16 v[4:7], v[104:107], v[180:183], v[4:7]
	v_mfma_f32_16x16x32_bf16 v[0:3], v[200:203], v[180:183], v[0:3]
	v_mfma_f32_16x16x32_bf16 v[28:31], v[104:107], v[72:75], v[28:31]
	v_mfma_f32_16x16x32_bf16 v[24:27], v[200:203], v[72:75], v[24:27]
	v_mfma_f32_16x16x32_bf16 v[20:23], v[108:111], v[92:95], v[20:23]
	v_mfma_f32_16x16x32_bf16 v[16:19], v[204:207], v[92:95], v[16:19]
	v_mfma_f32_16x16x32_bf16 v[12:15], v[104:107], v[170:173], v[12:15]
	v_mfma_f32_16x16x32_bf16 v[8:11], v[200:203], v[170:173], v[8:11]
	v_mfma_f32_16x16x32_bf16 v[4:7], v[108:111], v[184:187], v[4:7]
	v_mfma_f32_16x16x32_bf16 v[0:3], v[204:207], v[184:187], v[0:3]
	v_mfma_f32_16x16x32_bf16 v[130:133], v[108:111], v[76:79], v[28:31]
	v_mfma_f32_16x16x32_bf16 v[134:137], v[204:207], v[76:79], v[24:27]
	v_mfma_f32_16x16x32_bf16 v[150:153], v[108:111], v[176:179], v[12:15]
	v_mfma_f32_16x16x32_bf16 v[154:157], v[204:207], v[176:179], v[8:11]
	s_barrier
	s_nop 0
	ds_read_b128 v[8:11], v147
	ds_read_b128 v[12:15], v147 offset:1024
	ds_read_b128 v[170:173], v147 offset:2048
	ds_read_b128 v[176:179], v147 offset:3072
	ds_read_b128 v[24:27], v142 offset:32768
	ds_read_b128 v[28:31], v142 offset:33792
	ds_read_b128 v[40:43], v143 offset:32768
	ds_read_b128 v[44:47], v143 offset:33792
	ds_read_b128 v[180:183], v144 offset:32768
	ds_read_b128 v[184:187], v144 offset:33792
	ds_read_b128 v[200:203], v145 offset:32768
	ds_read_b128 v[204:207], v145 offset:33792
	s_waitcnt vmcnt(2)
	s_barrier
	s_waitcnt lgkmcnt(7)
	v_mfma_f32_16x16x32_bf16 v[72:75], v[8:11], v[24:27], v[124:127]
	s_waitcnt lgkmcnt(6)
	v_mfma_f32_16x16x32_bf16 v[124:127], v[12:15], v[28:31], v[72:75]
	v_mfma_f32_16x16x32_bf16 v[72:75], v[170:173], v[24:27], v[120:123]
	v_mfma_f32_16x16x32_bf16 v[120:123], v[176:179], v[28:31], v[72:75]
	s_waitcnt lgkmcnt(5)
	v_mfma_f32_16x16x32_bf16 v[72:75], v[8:11], v[40:43], v[116:119]
	s_waitcnt lgkmcnt(4)
	v_mfma_f32_16x16x32_bf16 v[108:111], v[12:15], v[44:47], v[72:75]
	v_mfma_f32_16x16x32_bf16 v[72:75], v[170:173], v[40:43], v[112:115]
	v_mfma_f32_16x16x32_bf16 v[104:107], v[176:179], v[44:47], v[72:75]
	s_waitcnt lgkmcnt(3)
	v_mfma_f32_16x16x32_bf16 v[72:75], v[8:11], v[180:183], v[192:195]
	s_waitcnt lgkmcnt(2)
	v_mfma_f32_16x16x32_bf16 v[92:95], v[12:15], v[184:187], v[72:75]
	v_mfma_f32_16x16x32_bf16 v[72:75], v[170:173], v[180:183], v[196:199]
	v_mfma_f32_16x16x32_bf16 v[88:91], v[176:179], v[184:187], v[72:75]
	s_waitcnt lgkmcnt(1)
	v_mfma_f32_16x16x32_bf16 v[72:75], v[8:11], v[200:203], v[100:103]
	s_waitcnt lgkmcnt(0)
	v_mfma_f32_16x16x32_bf16 v[76:79], v[12:15], v[204:207], v[72:75]
	v_mfma_f32_16x16x32_bf16 v[72:75], v[170:173], v[200:203], v[96:99]
	v_mfma_f32_16x16x32_bf16 v[72:75], v[176:179], v[204:207], v[72:75]
	s_barrier
; #define LDA(dst, b, h)                                                                                               \
;   _Pragma("unroll") for (int m = 0; m < 4; ++m) _Pragma("unroll") for (int k = 0; k < 2; ++k) dst[m][k] =            \
;       *reinterpret_cast<const bf16x8*>(SA(b, h) + lds_byte(wr * 64 + m * 16 + fr, k * 32 + fq * 8))
; #define LDB(dst, b, h)                                                                                               \
;   _Pragma("unroll") for (int n = 0; n < 2; ++n) _Pragma("unroll") for (int k = 0; k < 2; ++k) dst[n][k] =            \
;       *reinterpret_cast<const bf16x8*>(SB(b, h) + lds_byte(wc * 32 + n * 16 + fr, k * 32 + fq * 8))
; #define WAIT_V(n) asm volatile("s_waitcnt vmcnt(" #n ")" ::: "memory")
; #define WAIT_L(n) asm volatile("s_waitcnt lgkmcnt(" #n ")" ::: "memory")
; #define BAR __builtin_amdgcn_s_barrier()
; template <int EPI>
; __device__ __forceinline__ void gemm_phase(const u16* __restrict__ A, const u16* __restrict__ Bt, const int K,
;                                            const int nN, char* shm, const EpiArgs& ea) {
;     ...
;       LDB(B1, 1, 1); WAIT_V(0); BAR; WAIT_L(0); MMA(0, 1, At, B1); BAR;
;       LDA(At, 1, 1); BAR; WAIT_L(0); MMA(1, 0, At, B0); MMA(1, 1, At, B1); BAR;
;     }
;     if (wr == 0) BAR;
	ds_read_b128 v[192:195], v148
	ds_read_b128 v[196:199], v148 offset:1024
	ds_read_b128 v[216:219], v148 offset:2048
	ds_read_b128 v[220:223], v148 offset:3072
	s_waitcnt vmcnt(0)
	s_barrier
	s_waitcnt lgkmcnt(3)
	v_mfma_f32_16x16x32_bf16 v[96:99], v[192:195], v[24:27], v[208:211]
	s_waitcnt lgkmcnt(1)
	v_mfma_f32_16x16x32_bf16 v[24:27], v[216:219], v[24:27], v[158:161]
	s_waitcnt lgkmcnt(0)
	v_mfma_f32_16x16x32_bf16 v[112:115], v[220:223], v[28:31], v[24:27]
	v_mfma_f32_16x16x32_bf16 v[24:27], v[192:195], v[40:43], v[84:87]
	v_mfma_f32_16x16x32_bf16 v[100:103], v[196:199], v[44:47], v[24:27]
	v_mfma_f32_16x16x32_bf16 v[24:27], v[216:219], v[40:43], v[80:83]
	v_mfma_f32_16x16x32_bf16 v[116:119], v[196:199], v[28:31], v[96:99]
	v_mfma_f32_16x16x32_bf16 v[96:99], v[220:223], v[44:47], v[24:27]
	v_mfma_f32_16x16x32_bf16 v[24:27], v[192:195], v[180:183], v[162:165]
	v_mfma_f32_16x16x32_bf16 v[84:87], v[196:199], v[184:187], v[24:27]
	v_mfma_f32_16x16x32_bf16 v[24:27], v[216:219], v[180:183], v[166:169]
	v_mfma_f32_16x16x32_bf16 v[80:83], v[220:223], v[184:187], v[24:27]
	v_mfma_f32_16x16x32_bf16 v[24:27], v[192:195], v[200:203], v[68:71]
	v_mfma_f32_16x16x32_bf16 v[68:71], v[196:199], v[204:207], v[24:27]
	v_mfma_f32_16x16x32_bf16 v[24:27], v[216:219], v[200:203], v[64:67]
	v_mfma_f32_16x16x32_bf16 v[64:67], v[220:223], v[204:207], v[24:27]
	s_barrier
	ds_read_b128 v[158:161], v142 offset:49152
	ds_read_b128 v[162:165], v142 offset:50176
	ds_read_b128 v[166:169], v143 offset:49152
	ds_read_b128 v[180:183], v143 offset:50176
	ds_read_b128 v[184:187], v144 offset:49152
	ds_read_b128 v[200:203], v144 offset:50176
	ds_read_b128 v[204:207], v145 offset:49152
	ds_read_b128 v[208:211], v145 offset:50176
	s_barrier
	s_waitcnt lgkmcnt(7)
	v_mfma_f32_16x16x32_bf16 v[24:27], v[8:11], v[158:161], v[60:63]
	s_waitcnt lgkmcnt(6)
	v_mfma_f32_16x16x32_bf16 v[60:63], v[12:15], v[162:165], v[24:27]
	v_mfma_f32_16x16x32_bf16 v[24:27], v[170:173], v[158:161], v[56:59]
	v_mfma_f32_16x16x32_bf16 v[56:59], v[176:179], v[162:165], v[24:27]
	s_waitcnt lgkmcnt(5)
	v_mfma_f32_16x16x32_bf16 v[24:27], v[8:11], v[166:169], v[52:55]
	s_waitcnt lgkmcnt(4)
	v_mfma_f32_16x16x32_bf16 v[44:47], v[12:15], v[180:183], v[24:27]
	v_mfma_f32_16x16x32_bf16 v[24:27], v[170:173], v[166:169], v[48:51]
	v_mfma_f32_16x16x32_bf16 v[40:43], v[176:179], v[180:183], v[24:27]
	s_waitcnt lgkmcnt(3)
	v_mfma_f32_16x16x32_bf16 v[24:27], v[8:11], v[184:187], v[188:191]
	s_waitcnt lgkmcnt(1)
	v_mfma_f32_16x16x32_bf16 v[8:11], v[8:11], v[204:207], v[36:39]
	v_mfma_f32_16x16x32_bf16 v[28:31], v[12:15], v[200:203], v[24:27]
	v_mfma_f32_16x16x32_bf16 v[24:27], v[170:173], v[184:187], v[212:215]
	s_waitcnt lgkmcnt(0)
	v_mfma_f32_16x16x32_bf16 v[12:15], v[12:15], v[208:211], v[8:11]
	v_mfma_f32_16x16x32_bf16 v[8:11], v[170:173], v[204:207], v[32:35]
	v_mfma_f32_16x16x32_bf16 v[24:27], v[176:179], v[200:203], v[24:27]
	v_mfma_f32_16x16x32_bf16 v[8:11], v[176:179], v[208:211], v[8:11]
	v_mfma_f32_16x16x32_bf16 v[32:35], v[192:195], v[158:161], v[130:133]
	v_mfma_f32_16x16x32_bf16 v[52:55], v[196:199], v[162:165], v[32:35]
	v_mfma_f32_16x16x32_bf16 v[32:35], v[216:219], v[158:161], v[134:137]
	v_mfma_f32_16x16x32_bf16 v[16:19], v[216:219], v[166:169], v[16:19]
	v_mfma_f32_16x16x32_bf16 v[48:51], v[220:223], v[162:165], v[32:35]
	v_mfma_f32_16x16x32_bf16 v[20:23], v[192:195], v[166:169], v[20:23]
	v_mfma_f32_16x16x32_bf16 v[32:35], v[220:223], v[180:183], v[16:19]
	v_mfma_f32_16x16x32_bf16 v[16:19], v[192:195], v[184:187], v[150:153]
	v_mfma_f32_16x16x32_bf16 v[36:39], v[196:199], v[180:183], v[20:23]
	v_mfma_f32_16x16x32_bf16 v[20:23], v[196:199], v[200:203], v[16:19]
	v_mfma_f32_16x16x32_bf16 v[16:19], v[216:219], v[184:187], v[154:157]
	v_mfma_f32_16x16x32_bf16 v[4:7], v[192:195], v[204:207], v[4:7]
	v_mfma_f32_16x16x32_bf16 v[0:3], v[216:219], v[204:207], v[0:3]
	v_mfma_f32_16x16x32_bf16 v[16:19], v[220:223], v[200:203], v[16:19]
	v_mfma_f32_16x16x32_bf16 v[4:7], v[196:199], v[208:211], v[4:7]
	v_mfma_f32_16x16x32_bf16 v[0:3], v[220:223], v[208:211], v[0:3]
	s_andn2_b64 vcc, exec, s[14:15]
	s_barrier
	s_cbranch_vccnz .LBB0_634
	s_barrier
